# v28 + GEMM K-loops: removed the redundant s_setprio 0/1 toggle between the two 16-MFMA groups and the no-op lgkmcnt(0) after the segment barrier (3 fewer issue slots per MFMA segment)
# speedup vs baseline: 1.0068x; 1.0068x over previous
; #define PG8_STAGE(bufoff, gbase, voff) do { _Pragma("unroll") for (int _i = 0; _i < 2; ++_i) \
;         __builtin_amdgcn_global_load_lds((const unsigned*)((const char*)(gbase) + (voff)[_i]), (PG8_LAS unsigned*)(lds + (bufoff) + ldsw + _i * 8192), 16, 0, 0); } while (0)
; #define PG8_LDA(dst, b, h) do { _Pragma("unroll") for (int m = 0; m < 4; ++m) _Pragma("unroll") for (int k = 0; k < 2; ++k) dst[m][k] = *(const PG8_LAS bf16x8*)(lds + PG8_SA(b, h) + aoff + m * 2048 + k * 1024); } while (0)
; #define PG8_LDB(dst, b, h) do { _Pragma("unroll") for (int n = 0; n < 2; ++n) _Pragma("unroll") for (int k = 0; k < 2; ++k) dst[n][k] = *(const PG8_LAS bf16x8*)(lds + PG8_SB(b, h) + boff + n * 2048 + k * 1024); } while (0)
; #define PG8_MMA(ai, bj, At, Bt) do { __builtin_amdgcn_s_setprio(1); _Pragma("unroll") for (int m = 0; m < 4; ++m) _Pragma("unroll") for (int n = 0; n < 2; ++n) _Pragma("unroll") for (int k = 0; k < 2; ++k) \
;         acc[ai][bj][m][n] = __builtin_amdgcn_mfma_f32_16x16x32_bf16(Bt[n][k], At[m][k], acc[ai][bj][m][n], 0, 0, 0); __builtin_amdgcn_s_setprio(0); } while (0)
; #define PG8_WAIT_V(n) asm volatile("s_waitcnt vmcnt(" #n ")" ::: "memory")
; #define PG8_WAIT_L(n) asm volatile("s_waitcnt lgkmcnt(" #n ")" ::: "memory")
; #define PG8_BAR __builtin_amdgcn_s_barrier()
; #define PG8_SCHED __builtin_amdgcn_sched_barrier(0)
; template <class Epi, class Sched, bool ALIGN_EPI = false, bool SP2 = false>
; __device__ __forceinline__ void gemm_phase(PG8_LAS unsigned char* lds, const Gemm g, const Sched& S, const Epi& E) {
;     ...
;             PG8_LDB(B0, 0, 0); PG8_LDB(B1, 0, 1); PG8_SCHED; PG8_LDA(At, 0, 0); PG8_STAGE(PG8_SA(1, 1), a1 + hstep, voffA);
;             PG8_WAIT_V(8); PG8_WAIT_L(0); PG8_BAR; PG8_MMA(0, 0, At, B0); PG8_MMA(0, 1, At, B1); PG8_BAR; PG8_SCHED;
;             PG8_LDA(At, 0, 1); PG8_STAGE(PG8_SB(0, 0), b2, voffB); PG8_STAGE(PG8_SB(0, 1), b2 + hstep, voffB); PG8_STAGE(PG8_SA(0, 0), a2, voffA);
;             PG8_WAIT_V(8); PG8_WAIT_L(0); PG8_BAR; PG8_MMA(1, 0, At, B0); PG8_MMA(1, 1, At, B1); PG8_BAR; PG8_SCHED;
.LBB0_182:
	s_add_u32 s40, s38, 0xfffc0080
	s_addc_u32 s41, s39, -1
	s_add_i32 s60, 0, 0x10000
	s_cmp_eq_u32 s58, 12
	s_cselect_b32 s43, s15, s41
	s_cselect_b32 s42, s54, s40
	v_add_u32_e32 v142, s60, v159
	s_cselect_b32 s41, s13, s57
	s_cselect_b32 s40, s55, s56
	s_add_i32 s62, 0, 0x14000
	ds_read_b128 v[164:167], v142
	ds_read_b128 v[168:171], v142 offset:1024
	ds_read_b128 v[172:175], v142 offset:2048
	ds_read_b128 v[176:179], v142 offset:3072
	v_add_u32_e32 v142, s62, v159
	ds_read_b128 v[180:183], v142
	ds_read_b128 v[184:187], v142 offset:1024
	ds_read_b128 v[188:191], v142 offset:2048
	ds_read_b128 v[192:195], v142 offset:3072
	s_add_i32 m0, s47, 0xc000
	ds_read_b128 v[196:199], v163
	ds_read_b128 v[216:219], v163 offset:1024
	ds_read_b128 v[220:223], v163 offset:2048
	ds_read_b128 v[224:227], v163 offset:3072
	ds_read_b128 v[228:231], v163 offset:4096
	ds_read_b128 v[232:235], v163 offset:5120
	ds_read_b128 v[236:239], v163 offset:6144
	ds_read_b128 v[240:243], v163 offset:7168
	global_load_lds_dwordx4 v138, s[38:39]
	s_add_i32 m0, s47, 0xe000
	s_nop 0
	global_load_lds_dwordx4 v140, s[38:39]
	s_waitcnt vmcnt(8)
	s_waitcnt lgkmcnt(0)
	s_barrier
	s_setprio 1
	v_mfma_f32_16x16x32_bf16 v[116:119], v[164:167], v[196:199], v[116:119]
	v_mfma_f32_16x16x32_bf16 v[112:115], v[172:175], v[196:199], v[112:115]
	v_mfma_f32_16x16x32_bf16 v[100:103], v[164:167], v[220:223], v[100:103]
	v_mfma_f32_16x16x32_bf16 v[96:99], v[172:175], v[220:223], v[96:99]
	v_mfma_f32_16x16x32_bf16 v[84:87], v[164:167], v[228:231], v[84:87]
	v_mfma_f32_16x16x32_bf16 v[80:83], v[172:175], v[228:231], v[80:83]
	v_mfma_f32_16x16x32_bf16 v[68:71], v[164:167], v[236:239], v[68:71]
	v_mfma_f32_16x16x32_bf16 v[64:67], v[172:175], v[236:239], v[64:67]
	v_mfma_f32_16x16x32_bf16 v[116:119], v[168:171], v[216:219], v[116:119]
	v_mfma_f32_16x16x32_bf16 v[112:115], v[176:179], v[216:219], v[112:115]
	v_mfma_f32_16x16x32_bf16 v[100:103], v[168:171], v[224:227], v[100:103]
	v_mfma_f32_16x16x32_bf16 v[96:99], v[176:179], v[224:227], v[96:99]
	v_mfma_f32_16x16x32_bf16 v[84:87], v[168:171], v[232:235], v[84:87]
	v_mfma_f32_16x16x32_bf16 v[80:83], v[176:179], v[232:235], v[80:83]
	v_mfma_f32_16x16x32_bf16 v[68:71], v[168:171], v[240:243], v[68:71]
	v_mfma_f32_16x16x32_bf16 v[64:67], v[176:179], v[240:243], v[64:67]
	v_mfma_f32_16x16x32_bf16 v[124:127], v[180:183], v[196:199], v[124:127]
	v_mfma_f32_16x16x32_bf16 v[120:123], v[188:191], v[196:199], v[120:123]
	v_mfma_f32_16x16x32_bf16 v[108:111], v[180:183], v[220:223], v[108:111]
	v_mfma_f32_16x16x32_bf16 v[104:107], v[188:191], v[220:223], v[104:107]
	v_mfma_f32_16x16x32_bf16 v[92:95], v[180:183], v[228:231], v[92:95]
	v_mfma_f32_16x16x32_bf16 v[88:91], v[188:191], v[228:231], v[88:91]
	v_mfma_f32_16x16x32_bf16 v[76:79], v[180:183], v[236:239], v[76:79]
	v_mfma_f32_16x16x32_bf16 v[72:75], v[188:191], v[236:239], v[72:75]
	v_mfma_f32_16x16x32_bf16 v[124:127], v[184:187], v[216:219], v[124:127]
	v_mfma_f32_16x16x32_bf16 v[120:123], v[192:195], v[216:219], v[120:123]
	v_mfma_f32_16x16x32_bf16 v[108:111], v[184:187], v[224:227], v[108:111]
	v_mfma_f32_16x16x32_bf16 v[104:107], v[192:195], v[224:227], v[104:107]
	v_mfma_f32_16x16x32_bf16 v[92:95], v[184:187], v[232:235], v[92:95]
	v_mfma_f32_16x16x32_bf16 v[88:91], v[192:195], v[232:235], v[88:91]
	v_mfma_f32_16x16x32_bf16 v[76:79], v[184:187], v[240:243], v[76:79]
	v_mfma_f32_16x16x32_bf16 v[72:75], v[192:195], v[240:243], v[72:75]
	s_setprio 0
	s_barrier
	s_add_i32 s60, s60, s45
	s_mov_b32 m0, s60
	ds_read_b128 v[196:199], v163 offset:16384
	ds_read_b128 v[216:219], v163 offset:17408
	ds_read_b128 v[220:223], v163 offset:18432
	ds_read_b128 v[224:227], v163 offset:19456
	ds_read_b128 v[228:231], v163 offset:20480
	ds_read_b128 v[232:235], v163 offset:21504
	ds_read_b128 v[236:239], v163 offset:22528
	ds_read_b128 v[240:243], v163 offset:23552
	global_load_lds_dwordx4 v132, s[40:41]
	s_add_i32 m0, s60, 0x2000
	s_add_u32 s60, s40, 0x40000
	s_addc_u32 s61, s41, 0
	s_add_i32 s62, s62, s45
	global_load_lds_dwordx4 v128, s[40:41]
	s_mov_b32 m0, s62
	s_nop 0
	global_load_lds_dwordx4 v132, s[60:61]
	s_add_i32 m0, s62, 0x2000
	s_nop 0
	global_load_lds_dwordx4 v128, s[60:61]
	s_mov_b32 m0, s47
	s_nop 0
	global_load_lds_dwordx4 v134, s[42:43]
	s_mov_b32 m0, s48
	s_nop 0
	global_load_lds_dwordx4 v130, s[42:43]
	s_waitcnt vmcnt(8)
	s_waitcnt lgkmcnt(0)
	s_barrier
	s_setprio 1
	v_mfma_f32_16x16x32_bf16 v[52:55], v[164:167], v[196:199], v[52:55]
	v_mfma_f32_16x16x32_bf16 v[48:51], v[172:175], v[196:199], v[48:51]
	v_mfma_f32_16x16x32_bf16 v[36:39], v[164:167], v[220:223], v[36:39]
	v_mfma_f32_16x16x32_bf16 v[32:35], v[172:175], v[220:223], v[32:35]
	v_mfma_f32_16x16x32_bf16 v[20:23], v[164:167], v[228:231], v[20:23]
	v_mfma_f32_16x16x32_bf16 v[16:19], v[172:175], v[228:231], v[16:19]
	v_mfma_f32_16x16x32_bf16 v[4:7], v[164:167], v[236:239], v[4:7]
	v_mfma_f32_16x16x32_bf16 v[0:3], v[172:175], v[236:239], v[0:3]
	v_mfma_f32_16x16x32_bf16 v[52:55], v[168:171], v[216:219], v[52:55]
	v_mfma_f32_16x16x32_bf16 v[48:51], v[176:179], v[216:219], v[48:51]
	v_mfma_f32_16x16x32_bf16 v[36:39], v[168:171], v[224:227], v[36:39]
	v_mfma_f32_16x16x32_bf16 v[32:35], v[176:179], v[224:227], v[32:35]
	v_mfma_f32_16x16x32_bf16 v[20:23], v[168:171], v[232:235], v[20:23]
	v_mfma_f32_16x16x32_bf16 v[16:19], v[176:179], v[232:235], v[16:19]
	v_mfma_f32_16x16x32_bf16 v[4:7], v[168:171], v[240:243], v[4:7]
	v_mfma_f32_16x16x32_bf16 v[0:3], v[176:179], v[240:243], v[0:3]
	v_mfma_f32_16x16x32_bf16 v[60:63], v[180:183], v[196:199], v[60:63]
	v_mfma_f32_16x16x32_bf16 v[56:59], v[188:191], v[196:199], v[56:59]
	v_mfma_f32_16x16x32_bf16 v[44:47], v[180:183], v[220:223], v[44:47]
	v_mfma_f32_16x16x32_bf16 v[40:43], v[188:191], v[220:223], v[40:43]
	v_mfma_f32_16x16x32_bf16 v[28:31], v[180:183], v[228:231], v[28:31]
	v_mfma_f32_16x16x32_bf16 v[24:27], v[188:191], v[228:231], v[24:27]
	v_mfma_f32_16x16x32_bf16 v[12:15], v[180:183], v[236:239], v[12:15]
	v_mfma_f32_16x16x32_bf16 v[8:11], v[188:191], v[236:239], v[8:11]
	v_mfma_f32_16x16x32_bf16 v[60:63], v[184:187], v[216:219], v[60:63]
	v_mfma_f32_16x16x32_bf16 v[56:59], v[192:195], v[216:219], v[56:59]
	v_mfma_f32_16x16x32_bf16 v[44:47], v[184:187], v[224:227], v[44:47]
	v_mfma_f32_16x16x32_bf16 v[40:43], v[192:195], v[224:227], v[40:43]
	v_mfma_f32_16x16x32_bf16 v[28:31], v[184:187], v[232:235], v[28:31]
	v_mfma_f32_16x16x32_bf16 v[24:27], v[192:195], v[232:235], v[24:27]
	v_mfma_f32_16x16x32_bf16 v[12:15], v[184:187], v[240:243], v[12:15]
	v_mfma_f32_16x16x32_bf16 v[8:11], v[192:195], v[240:243], v[8:11]
	s_setprio 0
	s_barrier
; #define PG8_STAGE(bufoff, gbase, voff) do { _Pragma("unroll") for (int _i = 0; _i < 2; ++_i) \
;         __builtin_amdgcn_global_load_lds((const unsigned*)((const char*)(gbase) + (voff)[_i]), (PG8_LAS unsigned*)(lds + (bufoff) + ldsw + _i * 8192), 16, 0, 0); } while (0)
; #define PG8_LDA(dst, b, h) do { _Pragma("unroll") for (int m = 0; m < 4; ++m) _Pragma("unroll") for (int k = 0; k < 2; ++k) dst[m][k] = *(const PG8_LAS bf16x8*)(lds + PG8_SA(b, h) + aoff + m * 2048 + k * 1024); } while (0)
; #define PG8_LDB(dst, b, h) do { _Pragma("unroll") for (int n = 0; n < 2; ++n) _Pragma("unroll") for (int k = 0; k < 2; ++k) dst[n][k] = *(const PG8_LAS bf16x8*)(lds + PG8_SB(b, h) + boff + n * 2048 + k * 1024); } while (0)
; #define PG8_MMA(ai, bj, At, Bt) do { __builtin_amdgcn_s_setprio(1); _Pragma("unroll") for (int m = 0; m < 4; ++m) _Pragma("unroll") for (int n = 0; n < 2; ++n) _Pragma("unroll") for (int k = 0; k < 2; ++k) \
;         acc[ai][bj][m][n] = __builtin_amdgcn_mfma_f32_16x16x32_bf16(Bt[n][k], At[m][k], acc[ai][bj][m][n], 0, 0, 0); __builtin_amdgcn_s_setprio(0); } while (0)
; #define PG8_WAIT_V(n) asm volatile("s_waitcnt vmcnt(" #n ")" ::: "memory")
; #define PG8_WAIT_L(n) asm volatile("s_waitcnt lgkmcnt(" #n ")" ::: "memory")
; #define PG8_BAR __builtin_amdgcn_s_barrier()
; #define PG8_SCHED __builtin_amdgcn_sched_barrier(0)
; template <class Epi, class Sched, bool ALIGN_EPI = false, bool SP2 = false>
; __device__ __forceinline__ void gemm_phase(PG8_LAS unsigned char* lds, const Gemm g, const Sched& S, const Epi& E) {
;     ...
;             PG8_LDB(B0, 1, 0); PG8_LDB(B1, 1, 1); PG8_SCHED; PG8_LDA(At, 1, 0); PG8_STAGE(PG8_SA(0, 1), a2 + hstep, voffA);
;             PG8_WAIT_V(8); PG8_WAIT_L(0); PG8_BAR; PG8_MMA(0, 0, At, B0); PG8_MMA(0, 1, At, B1); PG8_BAR; PG8_SCHED;
;             PG8_LDA(At, 1, 1); PG8_STAGE(PG8_SB(1, 0), b3, voffB); PG8_STAGE(PG8_SB(1, 1), b3 + hstep, voffB); PG8_STAGE(PG8_SA(1, 0), a3, voffA);
;             PG8_WAIT_V(8); PG8_WAIT_L(0); PG8_BAR; PG8_MMA(1, 0, At, B0); PG8_MMA(1, 1, At, B1); PG8_BAR; PG8_SCHED;
	s_add_i32 s60, 0, 0x18000
	s_add_i32 s61, 0, 0x1c000
	v_add_u32_e32 v176, s60, v159
	v_add_u32_e32 v192, s61, v159
	ds_read_b128 v[164:167], v176
	ds_read_b128 v[168:171], v176 offset:1024
	ds_read_b128 v[172:175], v176 offset:2048
	ds_read_b128 v[176:179], v176 offset:3072
	ds_read_b128 v[180:183], v192
	ds_read_b128 v[184:187], v192 offset:1024
	ds_read_b128 v[188:191], v192 offset:2048
	ds_read_b128 v[192:195], v192 offset:3072
	s_add_u32 s42, s42, 0x40000
	s_addc_u32 s43, s43, 0
	s_mov_b32 m0, s49
	ds_read_b128 v[196:199], v163 offset:32768
	ds_read_b128 v[216:219], v163 offset:33792
	ds_read_b128 v[220:223], v163 offset:34816
	ds_read_b128 v[224:227], v163 offset:35840
	ds_read_b128 v[228:231], v163 offset:36864
	ds_read_b128 v[232:235], v163 offset:37888
	ds_read_b128 v[236:239], v163 offset:38912
	ds_read_b128 v[240:243], v163 offset:39936
	global_load_lds_dwordx4 v134, s[42:43]
	s_mov_b32 m0, s50
	s_nop 0
	global_load_lds_dwordx4 v130, s[42:43]
	s_waitcnt vmcnt(8)
	s_waitcnt lgkmcnt(0)
	s_barrier
	s_setprio 1
	v_mfma_f32_16x16x32_bf16 v[116:119], v[164:167], v[196:199], v[116:119]
	v_mfma_f32_16x16x32_bf16 v[112:115], v[172:175], v[196:199], v[112:115]
	v_mfma_f32_16x16x32_bf16 v[100:103], v[164:167], v[220:223], v[100:103]
	v_mfma_f32_16x16x32_bf16 v[96:99], v[172:175], v[220:223], v[96:99]
	v_mfma_f32_16x16x32_bf16 v[84:87], v[164:167], v[228:231], v[84:87]
	v_mfma_f32_16x16x32_bf16 v[80:83], v[172:175], v[228:231], v[80:83]
	v_mfma_f32_16x16x32_bf16 v[68:71], v[164:167], v[236:239], v[68:71]
	v_mfma_f32_16x16x32_bf16 v[64:67], v[172:175], v[236:239], v[64:67]
	v_mfma_f32_16x16x32_bf16 v[116:119], v[168:171], v[216:219], v[116:119]
	v_mfma_f32_16x16x32_bf16 v[112:115], v[176:179], v[216:219], v[112:115]
	v_mfma_f32_16x16x32_bf16 v[100:103], v[168:171], v[224:227], v[100:103]
	v_mfma_f32_16x16x32_bf16 v[96:99], v[176:179], v[224:227], v[96:99]
	v_mfma_f32_16x16x32_bf16 v[84:87], v[168:171], v[232:235], v[84:87]
	v_mfma_f32_16x16x32_bf16 v[80:83], v[176:179], v[232:235], v[80:83]
	v_mfma_f32_16x16x32_bf16 v[68:71], v[168:171], v[240:243], v[68:71]
	v_mfma_f32_16x16x32_bf16 v[64:67], v[176:179], v[240:243], v[64:67]
	v_mfma_f32_16x16x32_bf16 v[124:127], v[180:183], v[196:199], v[124:127]
	v_mfma_f32_16x16x32_bf16 v[120:123], v[188:191], v[196:199], v[120:123]
	v_mfma_f32_16x16x32_bf16 v[108:111], v[180:183], v[220:223], v[108:111]
	v_mfma_f32_16x16x32_bf16 v[104:107], v[188:191], v[220:223], v[104:107]
	v_mfma_f32_16x16x32_bf16 v[92:95], v[180:183], v[228:231], v[92:95]
	v_mfma_f32_16x16x32_bf16 v[88:91], v[188:191], v[228:231], v[88:91]
	v_mfma_f32_16x16x32_bf16 v[76:79], v[180:183], v[236:239], v[76:79]
	v_mfma_f32_16x16x32_bf16 v[72:75], v[188:191], v[236:239], v[72:75]
	v_mfma_f32_16x16x32_bf16 v[124:127], v[184:187], v[216:219], v[124:127]
	v_mfma_f32_16x16x32_bf16 v[120:123], v[192:195], v[216:219], v[120:123]
	v_mfma_f32_16x16x32_bf16 v[108:111], v[184:187], v[224:227], v[108:111]
	v_mfma_f32_16x16x32_bf16 v[104:107], v[192:195], v[224:227], v[104:107]
	v_mfma_f32_16x16x32_bf16 v[92:95], v[184:187], v[232:235], v[92:95]
	v_mfma_f32_16x16x32_bf16 v[88:91], v[192:195], v[232:235], v[88:91]
	v_mfma_f32_16x16x32_bf16 v[76:79], v[184:187], v[240:243], v[76:79]
	v_mfma_f32_16x16x32_bf16 v[72:75], v[192:195], v[240:243], v[72:75]
	s_setprio 0
	s_barrier
	s_add_i32 m0, s45, 0x18000
	s_add_u32 s40, s40, 0x80
	s_addc_u32 s41, s41, 0
	ds_read_b128 v[196:199], v163 offset:49152
	ds_read_b128 v[216:219], v163 offset:50176
	ds_read_b128 v[220:223], v163 offset:51200
	ds_read_b128 v[224:227], v163 offset:52224
	ds_read_b128 v[228:231], v163 offset:53248
	ds_read_b128 v[232:235], v163 offset:54272
	ds_read_b128 v[236:239], v163 offset:55296
	ds_read_b128 v[240:243], v163 offset:56320
	global_load_lds_dwordx4 v132, s[40:41]
	s_add_i32 m0, s45, 0x1a000
	s_add_u32 s60, s42, 0xfffc0080
	s_addc_u32 s61, s43, -1
	global_load_lds_dwordx4 v128, s[40:41]
	s_add_u32 s40, s40, 0x40000
	s_addc_u32 s41, s41, 0
	s_add_i32 m0, s45, 0x1c000
	s_nop 0
	global_load_lds_dwordx4 v132, s[40:41]
	s_add_i32 m0, s45, 0x1e000
	s_nop 0
	global_load_lds_dwordx4 v128, s[40:41]
	s_mov_b32 m0, s51
	s_nop 0
	global_load_lds_dwordx4 v134, s[60:61]
	s_mov_b32 m0, s52
	s_nop 0
	global_load_lds_dwordx4 v130, s[60:61]
	s_waitcnt vmcnt(8)
	s_waitcnt lgkmcnt(0)
	s_barrier
	s_setprio 1
	v_mfma_f32_16x16x32_bf16 v[52:55], v[164:167], v[196:199], v[52:55]
	v_mfma_f32_16x16x32_bf16 v[48:51], v[172:175], v[196:199], v[48:51]
	v_mfma_f32_16x16x32_bf16 v[36:39], v[164:167], v[220:223], v[36:39]
	v_mfma_f32_16x16x32_bf16 v[32:35], v[172:175], v[220:223], v[32:35]
	v_mfma_f32_16x16x32_bf16 v[20:23], v[164:167], v[228:231], v[20:23]
	v_mfma_f32_16x16x32_bf16 v[16:19], v[172:175], v[228:231], v[16:19]
	v_mfma_f32_16x16x32_bf16 v[4:7], v[164:167], v[236:239], v[4:7]
	v_mfma_f32_16x16x32_bf16 v[0:3], v[172:175], v[236:239], v[0:3]
	v_mfma_f32_16x16x32_bf16 v[52:55], v[168:171], v[216:219], v[52:55]
	v_mfma_f32_16x16x32_bf16 v[48:51], v[176:179], v[216:219], v[48:51]
	v_mfma_f32_16x16x32_bf16 v[36:39], v[168:171], v[224:227], v[36:39]
	v_mfma_f32_16x16x32_bf16 v[32:35], v[176:179], v[224:227], v[32:35]
	v_mfma_f32_16x16x32_bf16 v[20:23], v[168:171], v[232:235], v[20:23]
	v_mfma_f32_16x16x32_bf16 v[16:19], v[176:179], v[232:235], v[16:19]
	v_mfma_f32_16x16x32_bf16 v[4:7], v[168:171], v[240:243], v[4:7]
	v_mfma_f32_16x16x32_bf16 v[0:3], v[176:179], v[240:243], v[0:3]
	v_mfma_f32_16x16x32_bf16 v[60:63], v[180:183], v[196:199], v[60:63]
	v_mfma_f32_16x16x32_bf16 v[56:59], v[188:191], v[196:199], v[56:59]
	v_mfma_f32_16x16x32_bf16 v[44:47], v[180:183], v[220:223], v[44:47]
	v_mfma_f32_16x16x32_bf16 v[40:43], v[188:191], v[220:223], v[40:43]
	v_mfma_f32_16x16x32_bf16 v[28:31], v[180:183], v[228:231], v[28:31]
	v_mfma_f32_16x16x32_bf16 v[24:27], v[188:191], v[228:231], v[24:27]
	v_mfma_f32_16x16x32_bf16 v[12:15], v[180:183], v[236:239], v[12:15]
	v_mfma_f32_16x16x32_bf16 v[8:11], v[188:191], v[236:239], v[8:11]
	v_mfma_f32_16x16x32_bf16 v[60:63], v[184:187], v[216:219], v[60:63]
	v_mfma_f32_16x16x32_bf16 v[56:59], v[192:195], v[216:219], v[56:59]
	v_mfma_f32_16x16x32_bf16 v[44:47], v[184:187], v[224:227], v[44:47]
	v_mfma_f32_16x16x32_bf16 v[40:43], v[192:195], v[224:227], v[40:43]
	v_mfma_f32_16x16x32_bf16 v[28:31], v[184:187], v[232:235], v[28:31]
	v_mfma_f32_16x16x32_bf16 v[24:27], v[192:195], v[232:235], v[24:27]
	v_mfma_f32_16x16x32_bf16 v[12:15], v[184:187], v[240:243], v[12:15]
	v_mfma_f32_16x16x32_bf16 v[8:11], v[192:195], v[240:243], v[8:11]
	s_setprio 0
	s_barrier
	s_add_i32 s58, s58, 2
	s_add_u32 s38, s38, 0x100
	s_addc_u32 s39, s39, 0
	s_add_u32 s56, s56, 0x100
	s_addc_u32 s57, s57, 0
	s_cmp_gt_u32 s58, 13
	s_cbranch_scc0 .LBB0_182
	s_and_b64 vcc, exec, s[10:11]
	s_cbranch_vccz .LBB0_185
	s_barrier

; #define PG8_STAGE(bufoff, gbase, voff) do { _Pragma("unroll") for (int _i = 0; _i < 2; ++_i) \
;         __builtin_amdgcn_global_load_lds((const unsigned*)((const char*)(gbase) + (voff)[_i]), (PG8_LAS unsigned*)(lds + (bufoff) + ldsw + _i * 8192), 16, 0, 0); } while (0)
; #define PG8_LDA(dst, b, h) do { _Pragma("unroll") for (int m = 0; m < 4; ++m) _Pragma("unroll") for (int k = 0; k < 2; ++k) dst[m][k] = *(const PG8_LAS bf16x8*)(lds + PG8_SA(b, h) + aoff + m * 2048 + k * 1024); } while (0)
; #define PG8_LDB(dst, b, h) do { _Pragma("unroll") for (int n = 0; n < 2; ++n) _Pragma("unroll") for (int k = 0; k < 2; ++k) dst[n][k] = *(const PG8_LAS bf16x8*)(lds + PG8_SB(b, h) + boff + n * 2048 + k * 1024); } while (0)
; #define PG8_MMA(ai, bj, At, Bt) do { __builtin_amdgcn_s_setprio(1); _Pragma("unroll") for (int m = 0; m < 4; ++m) _Pragma("unroll") for (int n = 0; n < 2; ++n) _Pragma("unroll") for (int k = 0; k < 2; ++k) \
;         acc[ai][bj][m][n] = __builtin_amdgcn_mfma_f32_16x16x32_bf16(Bt[n][k], At[m][k], acc[ai][bj][m][n], 0, 0, 0); __builtin_amdgcn_s_setprio(0); } while (0)
; #define PG8_WAIT_V(n) asm volatile("s_waitcnt vmcnt(" #n ")" ::: "memory")
; #define PG8_WAIT_L(n) asm volatile("s_waitcnt lgkmcnt(" #n ")" ::: "memory")
; #define PG8_BAR __builtin_amdgcn_s_barrier()
; #define PG8_SCHED __builtin_amdgcn_sched_barrier(0)
; template <class Epi, class Sched, bool ALIGN_EPI = false, bool SP2 = false>
; __device__ __forceinline__ void gemm_phase(PG8_LAS unsigned char* lds, const Gemm g, const Sched& S, const Epi& E) {
;     ...
;             PG8_LDB(B0, 0, 0); PG8_LDB(B1, 0, 1); PG8_SCHED; PG8_LDA(At, 0, 0); PG8_STAGE(PG8_SA(1, 1), a1 + hstep, voffA);
;             PG8_WAIT_V(8); PG8_WAIT_L(0); PG8_BAR; PG8_MMA(0, 0, At, B0); PG8_MMA(0, 1, At, B1); PG8_BAR; PG8_SCHED;
;             PG8_LDA(At, 0, 1); PG8_STAGE(PG8_SB(0, 0), b2, voffB); PG8_STAGE(PG8_SB(0, 1), b2 + hstep, voffB); PG8_STAGE(PG8_SA(0, 0), a2, voffA);
.LBB0_270:
	s_add_u32 s18, s16, 0x100
	s_addc_u32 s19, s17, 0
	s_add_i32 s61, 0, 0x10000
	s_cmp_eq_u32 s60, 40
	s_cselect_b32 s41, s1, s19
	s_cselect_b32 s40, s0, s18
	v_add_u32_e32 v144, s61, v168
	s_cselect_b32 s29, s15, s58
	s_cselect_b32 s28, s14, s57
	s_add_i32 s62, 0, 0x14000
	ds_read_b128 v[128:131], v144
	ds_read_b128 v[132:135], v144 offset:1024
	ds_read_b128 v[162:165], v144 offset:2048
	ds_read_b128 v[170:173], v144 offset:3072
	v_add_u32_e32 v144, s62, v168
	ds_read_b128 v[174:177], v144
	ds_read_b128 v[178:181], v144 offset:1024
	ds_read_b128 v[182:185], v144 offset:2048
	ds_read_b128 v[186:189], v144 offset:3072
	v_lshl_add_u64 v[166:167], s[16:17], 0, v[158:159]
	s_add_i32 m0, s44, 0xc000
	ds_read_b128 v[190:193], v169
	ds_read_b128 v[194:197], v169 offset:1024
	ds_read_b128 v[216:219], v169 offset:2048
	ds_read_b128 v[220:223], v169 offset:3072
	ds_read_b128 v[224:227], v169 offset:4096
	ds_read_b128 v[228:231], v169 offset:5120
	ds_read_b128 v[232:235], v169 offset:6144
	ds_read_b128 v[236:239], v169 offset:7168
	global_load_lds_dwordx4 v[166:167], off
	v_lshl_add_u64 v[166:167], s[16:17], 0, v[160:161]
	s_add_i32 m0, s44, 0xe000
	s_nop 0
	global_load_lds_dwordx4 v[166:167], off
	s_waitcnt vmcnt(8)
	s_waitcnt lgkmcnt(0)
	s_barrier
	s_setprio 1
	v_mfma_f32_16x16x32_bf16 v[124:127], v[128:131], v[190:193], v[124:127]
	v_mfma_f32_16x16x32_bf16 v[120:123], v[162:165], v[190:193], v[120:123]
	v_mfma_f32_16x16x32_bf16 v[108:111], v[128:131], v[216:219], v[108:111]
	v_mfma_f32_16x16x32_bf16 v[104:107], v[162:165], v[216:219], v[104:107]
	v_mfma_f32_16x16x32_bf16 v[92:95], v[128:131], v[224:227], v[92:95]
	v_mfma_f32_16x16x32_bf16 v[88:91], v[162:165], v[224:227], v[88:91]
	v_mfma_f32_16x16x32_bf16 v[76:79], v[128:131], v[232:235], v[76:79]
	v_mfma_f32_16x16x32_bf16 v[72:75], v[162:165], v[232:235], v[72:75]
	v_mfma_f32_16x16x32_bf16 v[124:127], v[132:135], v[194:197], v[124:127]
	v_mfma_f32_16x16x32_bf16 v[120:123], v[170:173], v[194:197], v[120:123]
	v_mfma_f32_16x16x32_bf16 v[108:111], v[132:135], v[220:223], v[108:111]
	v_mfma_f32_16x16x32_bf16 v[104:107], v[170:173], v[220:223], v[104:107]
	v_mfma_f32_16x16x32_bf16 v[92:95], v[132:135], v[228:231], v[92:95]
	v_mfma_f32_16x16x32_bf16 v[88:91], v[170:173], v[228:231], v[88:91]
	v_mfma_f32_16x16x32_bf16 v[76:79], v[132:135], v[236:239], v[76:79]
	v_mfma_f32_16x16x32_bf16 v[72:75], v[170:173], v[236:239], v[72:75]
	v_mfma_f32_16x16x32_bf16 v[116:119], v[174:177], v[190:193], v[116:119]
	v_mfma_f32_16x16x32_bf16 v[112:115], v[182:185], v[190:193], v[112:115]
	v_mfma_f32_16x16x32_bf16 v[100:103], v[174:177], v[216:219], v[100:103]
	v_mfma_f32_16x16x32_bf16 v[96:99], v[182:185], v[216:219], v[96:99]
	v_mfma_f32_16x16x32_bf16 v[84:87], v[174:177], v[224:227], v[84:87]
	v_mfma_f32_16x16x32_bf16 v[80:83], v[182:185], v[224:227], v[80:83]
	v_mfma_f32_16x16x32_bf16 v[68:71], v[174:177], v[232:235], v[68:71]
	v_mfma_f32_16x16x32_bf16 v[64:67], v[182:185], v[232:235], v[64:67]
	v_mfma_f32_16x16x32_bf16 v[116:119], v[178:181], v[194:197], v[116:119]
	v_mfma_f32_16x16x32_bf16 v[112:115], v[186:189], v[194:197], v[112:115]
	v_mfma_f32_16x16x32_bf16 v[100:103], v[178:181], v[220:223], v[100:103]
	v_mfma_f32_16x16x32_bf16 v[96:99], v[186:189], v[220:223], v[96:99]
	v_mfma_f32_16x16x32_bf16 v[84:87], v[178:181], v[228:231], v[84:87]
	v_mfma_f32_16x16x32_bf16 v[80:83], v[186:189], v[228:231], v[80:83]
	v_mfma_f32_16x16x32_bf16 v[68:71], v[178:181], v[236:239], v[68:71]
	v_mfma_f32_16x16x32_bf16 v[64:67], v[186:189], v[236:239], v[64:67]
	s_setprio 0
	s_barrier
	s_add_i32 s16, s61, s43
	v_lshl_add_u64 v[166:167], s[28:29], 0, v[138:139]
	s_mov_b32 m0, s16
	ds_read_b128 v[190:193], v169 offset:16384
	ds_read_b128 v[194:197], v169 offset:17408
	ds_read_b128 v[216:219], v169 offset:18432
	ds_read_b128 v[220:223], v169 offset:19456
	ds_read_b128 v[224:227], v169 offset:20480
	ds_read_b128 v[228:231], v169 offset:21504
	ds_read_b128 v[232:235], v169 offset:22528
	ds_read_b128 v[236:239], v169 offset:23552
	global_load_lds_dwordx4 v[166:167], off
	s_add_i32 m0, s16, 0x2000
	s_add_u32 s16, s28, 0xb0000
	v_lshl_add_u64 v[198:199], s[28:29], 0, v[142:143]
	s_addc_u32 s17, s29, 0
	s_add_i32 s61, s62, s43
	global_load_lds_dwordx4 v[198:199], off
	v_lshl_add_u64 v[240:241], s[16:17], 0, v[138:139]
	s_mov_b32 m0, s61
	v_lshl_add_u64 v[242:243], s[40:41], 0, v[140:141]
	global_load_lds_dwordx4 v[240:241], off
	v_lshl_add_u64 v[240:241], s[16:17], 0, v[142:143]
	s_add_i32 m0, s61, 0x2000
	s_nop 0
	global_load_lds_dwordx4 v[240:241], off
	v_lshl_add_u64 v[240:241], s[40:41], 0, v[136:137]
	s_mov_b32 m0, s44
	s_nop 0
	global_load_lds_dwordx4 v[240:241], off
	s_mov_b32 m0, s45
	s_nop 0
	global_load_lds_dwordx4 v[242:243], off
	s_waitcnt vmcnt(8)
	s_waitcnt lgkmcnt(0)
	s_barrier
; #define PG8_STAGE(bufoff, gbase, voff) do { _Pragma("unroll") for (int _i = 0; _i < 2; ++_i) \
;         __builtin_amdgcn_global_load_lds((const unsigned*)((const char*)(gbase) + (voff)[_i]), (PG8_LAS unsigned*)(lds + (bufoff) + ldsw + _i * 8192), 16, 0, 0); } while (0)
; #define PG8_LDA(dst, b, h) do { _Pragma("unroll") for (int m = 0; m < 4; ++m) _Pragma("unroll") for (int k = 0; k < 2; ++k) dst[m][k] = *(const PG8_LAS bf16x8*)(lds + PG8_SA(b, h) + aoff + m * 2048 + k * 1024); } while (0)
; #define PG8_LDB(dst, b, h) do { _Pragma("unroll") for (int n = 0; n < 2; ++n) _Pragma("unroll") for (int k = 0; k < 2; ++k) dst[n][k] = *(const PG8_LAS bf16x8*)(lds + PG8_SB(b, h) + boff + n * 2048 + k * 1024); } while (0)
; #define PG8_MMA(ai, bj, At, Bt) do { __builtin_amdgcn_s_setprio(1); _Pragma("unroll") for (int m = 0; m < 4; ++m) _Pragma("unroll") for (int n = 0; n < 2; ++n) _Pragma("unroll") for (int k = 0; k < 2; ++k) \
;         acc[ai][bj][m][n] = __builtin_amdgcn_mfma_f32_16x16x32_bf16(Bt[n][k], At[m][k], acc[ai][bj][m][n], 0, 0, 0); __builtin_amdgcn_s_setprio(0); } while (0)
; #define PG8_WAIT_V(n) asm volatile("s_waitcnt vmcnt(" #n ")" ::: "memory")
; #define PG8_WAIT_L(n) asm volatile("s_waitcnt lgkmcnt(" #n ")" ::: "memory")
; #define PG8_BAR __builtin_amdgcn_s_barrier()
; #define PG8_SCHED __builtin_amdgcn_sched_barrier(0)
; template <class Epi, class Sched, bool ALIGN_EPI = false, bool SP2 = false>
; __device__ __forceinline__ void gemm_phase(PG8_LAS unsigned char* lds, const Gemm g, const Sched& S, const Epi& E) {
;     ...
;             PG8_WAIT_V(8); PG8_WAIT_L(0); PG8_BAR; PG8_MMA(1, 0, At, B0); PG8_MMA(1, 1, At, B1); PG8_BAR; PG8_SCHED;
;             PG8_LDB(B0, 1, 0); PG8_LDB(B1, 1, 1); PG8_SCHED; PG8_LDA(At, 1, 0); PG8_STAGE(PG8_SA(0, 1), a2 + hstep, voffA);
;             PG8_WAIT_V(8); PG8_WAIT_L(0); PG8_BAR; PG8_MMA(0, 0, At, B0); PG8_MMA(0, 1, At, B1); PG8_BAR; PG8_SCHED;
	s_setprio 1
	v_mfma_f32_16x16x32_bf16 v[60:63], v[128:131], v[190:193], v[60:63]
	v_mfma_f32_16x16x32_bf16 v[56:59], v[162:165], v[190:193], v[56:59]
	v_mfma_f32_16x16x32_bf16 v[44:47], v[128:131], v[216:219], v[44:47]
	v_mfma_f32_16x16x32_bf16 v[40:43], v[162:165], v[216:219], v[40:43]
	v_mfma_f32_16x16x32_bf16 v[28:31], v[128:131], v[224:227], v[28:31]
	v_mfma_f32_16x16x32_bf16 v[24:27], v[162:165], v[224:227], v[24:27]
	v_mfma_f32_16x16x32_bf16 v[12:15], v[128:131], v[232:235], v[12:15]
	v_mfma_f32_16x16x32_bf16 v[8:11], v[162:165], v[232:235], v[8:11]
	v_mfma_f32_16x16x32_bf16 v[60:63], v[132:135], v[194:197], v[60:63]
	v_mfma_f32_16x16x32_bf16 v[56:59], v[170:173], v[194:197], v[56:59]
	v_mfma_f32_16x16x32_bf16 v[44:47], v[132:135], v[220:223], v[44:47]
	v_mfma_f32_16x16x32_bf16 v[40:43], v[170:173], v[220:223], v[40:43]
	v_mfma_f32_16x16x32_bf16 v[28:31], v[132:135], v[228:231], v[28:31]
	v_mfma_f32_16x16x32_bf16 v[24:27], v[170:173], v[228:231], v[24:27]
	v_mfma_f32_16x16x32_bf16 v[12:15], v[132:135], v[236:239], v[12:15]
	v_mfma_f32_16x16x32_bf16 v[8:11], v[170:173], v[236:239], v[8:11]
	v_mfma_f32_16x16x32_bf16 v[52:55], v[174:177], v[190:193], v[52:55]
	v_mfma_f32_16x16x32_bf16 v[48:51], v[182:185], v[190:193], v[48:51]
	v_mfma_f32_16x16x32_bf16 v[36:39], v[174:177], v[216:219], v[36:39]
	v_mfma_f32_16x16x32_bf16 v[32:35], v[182:185], v[216:219], v[32:35]
	v_mfma_f32_16x16x32_bf16 v[20:23], v[174:177], v[224:227], v[20:23]
	v_mfma_f32_16x16x32_bf16 v[16:19], v[182:185], v[224:227], v[16:19]
	v_mfma_f32_16x16x32_bf16 v[4:7], v[174:177], v[232:235], v[4:7]
	v_mfma_f32_16x16x32_bf16 v[0:3], v[182:185], v[232:235], v[0:3]
	v_mfma_f32_16x16x32_bf16 v[52:55], v[178:181], v[194:197], v[52:55]
	v_mfma_f32_16x16x32_bf16 v[48:51], v[186:189], v[194:197], v[48:51]
	v_mfma_f32_16x16x32_bf16 v[36:39], v[178:181], v[220:223], v[36:39]
	v_mfma_f32_16x16x32_bf16 v[32:35], v[186:189], v[220:223], v[32:35]
	v_mfma_f32_16x16x32_bf16 v[20:23], v[178:181], v[228:231], v[20:23]
	v_mfma_f32_16x16x32_bf16 v[16:19], v[186:189], v[228:231], v[16:19]
	v_mfma_f32_16x16x32_bf16 v[4:7], v[178:181], v[236:239], v[4:7]
	v_mfma_f32_16x16x32_bf16 v[0:3], v[186:189], v[236:239], v[0:3]
	s_setprio 0
	s_barrier
	s_add_i32 s61, 0, 0x18000
	v_add_u32_e32 v144, s61, v168
	s_add_i32 s62, 0, 0x1c000
	ds_read_b128 v[128:131], v144
	ds_read_b128 v[132:135], v144 offset:1024
	ds_read_b128 v[162:165], v144 offset:2048
	ds_read_b128 v[170:173], v144 offset:3072
	v_add_u32_e32 v144, s62, v168
	ds_read_b128 v[174:177], v144
	ds_read_b128 v[178:181], v144 offset:1024
	ds_read_b128 v[182:185], v144 offset:2048
	ds_read_b128 v[186:189], v144 offset:3072
	s_add_u32 s16, s40, 0xb0000
	s_addc_u32 s17, s41, 0
	s_mov_b32 m0, s46
	v_lshl_add_u64 v[244:245], s[16:17], 0, v[136:137]
	ds_read_b128 v[190:193], v169 offset:32768
	ds_read_b128 v[194:197], v169 offset:33792
	ds_read_b128 v[216:219], v169 offset:34816
	ds_read_b128 v[220:223], v169 offset:35840
	ds_read_b128 v[224:227], v169 offset:36864
	ds_read_b128 v[228:231], v169 offset:37888
	ds_read_b128 v[232:235], v169 offset:38912
	ds_read_b128 v[236:239], v169 offset:39936
	global_load_lds_dwordx4 v[244:245], off
	v_lshl_add_u64 v[244:245], s[16:17], 0, v[140:141]
	s_mov_b32 m0, s47
	s_nop 0
	global_load_lds_dwordx4 v[244:245], off
	s_waitcnt vmcnt(8)
	s_waitcnt lgkmcnt(0)
	s_barrier
	s_setprio 1
	v_mfma_f32_16x16x32_bf16 v[124:127], v[128:131], v[190:193], v[124:127]
	v_mfma_f32_16x16x32_bf16 v[120:123], v[162:165], v[190:193], v[120:123]
	v_mfma_f32_16x16x32_bf16 v[108:111], v[128:131], v[216:219], v[108:111]
	v_mfma_f32_16x16x32_bf16 v[104:107], v[162:165], v[216:219], v[104:107]
	v_mfma_f32_16x16x32_bf16 v[92:95], v[128:131], v[224:227], v[92:95]
	v_mfma_f32_16x16x32_bf16 v[88:91], v[162:165], v[224:227], v[88:91]
	v_mfma_f32_16x16x32_bf16 v[76:79], v[128:131], v[232:235], v[76:79]
	v_mfma_f32_16x16x32_bf16 v[72:75], v[162:165], v[232:235], v[72:75]
	v_mfma_f32_16x16x32_bf16 v[124:127], v[132:135], v[194:197], v[124:127]
	v_mfma_f32_16x16x32_bf16 v[120:123], v[170:173], v[194:197], v[120:123]
	v_mfma_f32_16x16x32_bf16 v[108:111], v[132:135], v[220:223], v[108:111]
	v_mfma_f32_16x16x32_bf16 v[104:107], v[170:173], v[220:223], v[104:107]
	v_mfma_f32_16x16x32_bf16 v[92:95], v[132:135], v[228:231], v[92:95]
	v_mfma_f32_16x16x32_bf16 v[88:91], v[170:173], v[228:231], v[88:91]
	v_mfma_f32_16x16x32_bf16 v[76:79], v[132:135], v[236:239], v[76:79]
	v_mfma_f32_16x16x32_bf16 v[72:75], v[170:173], v[236:239], v[72:75]
	v_mfma_f32_16x16x32_bf16 v[116:119], v[174:177], v[190:193], v[116:119]
	v_mfma_f32_16x16x32_bf16 v[112:115], v[182:185], v[190:193], v[112:115]
	v_mfma_f32_16x16x32_bf16 v[100:103], v[174:177], v[216:219], v[100:103]
	v_mfma_f32_16x16x32_bf16 v[96:99], v[182:185], v[216:219], v[96:99]
	v_mfma_f32_16x16x32_bf16 v[84:87], v[174:177], v[224:227], v[84:87]
	v_mfma_f32_16x16x32_bf16 v[80:83], v[182:185], v[224:227], v[80:83]
	v_mfma_f32_16x16x32_bf16 v[68:71], v[174:177], v[232:235], v[68:71]
	v_mfma_f32_16x16x32_bf16 v[64:67], v[182:185], v[232:235], v[64:67]
	v_mfma_f32_16x16x32_bf16 v[116:119], v[178:181], v[194:197], v[116:119]
	v_mfma_f32_16x16x32_bf16 v[112:115], v[186:189], v[194:197], v[112:115]
	v_mfma_f32_16x16x32_bf16 v[100:103], v[178:181], v[220:223], v[100:103]
	v_mfma_f32_16x16x32_bf16 v[96:99], v[186:189], v[220:223], v[96:99]
	v_mfma_f32_16x16x32_bf16 v[84:87], v[178:181], v[228:231], v[84:87]
	v_mfma_f32_16x16x32_bf16 v[80:83], v[186:189], v[228:231], v[80:83]
	v_mfma_f32_16x16x32_bf16 v[68:71], v[178:181], v[236:239], v[68:71]
	v_mfma_f32_16x16x32_bf16 v[64:67], v[186:189], v[236:239], v[64:67]
	s_setprio 0
	s_barrier
; #define PG8_STAGE(bufoff, gbase, voff) do { _Pragma("unroll") for (int _i = 0; _i < 2; ++_i) \
;         __builtin_amdgcn_global_load_lds((const unsigned*)((const char*)(gbase) + (voff)[_i]), (PG8_LAS unsigned*)(lds + (bufoff) + ldsw + _i * 8192), 16, 0, 0); } while (0)
; #define PG8_LDA(dst, b, h) do { _Pragma("unroll") for (int m = 0; m < 4; ++m) _Pragma("unroll") for (int k = 0; k < 2; ++k) dst[m][k] = *(const PG8_LAS bf16x8*)(lds + PG8_SA(b, h) + aoff + m * 2048 + k * 1024); } while (0)
; #define PG8_MMA(ai, bj, At, Bt) do { __builtin_amdgcn_s_setprio(1); _Pragma("unroll") for (int m = 0; m < 4; ++m) _Pragma("unroll") for (int n = 0; n < 2; ++n) _Pragma("unroll") for (int k = 0; k < 2; ++k) \
;         acc[ai][bj][m][n] = __builtin_amdgcn_mfma_f32_16x16x32_bf16(Bt[n][k], At[m][k], acc[ai][bj][m][n], 0, 0, 0); __builtin_amdgcn_s_setprio(0); } while (0)
; #define PG8_WAIT_V(n) asm volatile("s_waitcnt vmcnt(" #n ")" ::: "memory")
; #define PG8_WAIT_L(n) asm volatile("s_waitcnt lgkmcnt(" #n ")" ::: "memory")
; #define PG8_BAR __builtin_amdgcn_s_barrier()
; #define PG8_SCHED __builtin_amdgcn_sched_barrier(0)
; template <class Epi, class Sched, bool ALIGN_EPI = false, bool SP2 = false>
; __device__ __forceinline__ void gemm_phase(PG8_LAS unsigned char* lds, const Gemm g, const Sched& S, const Epi& E) {
;     ...
;             PG8_LDA(At, 1, 1); PG8_STAGE(PG8_SB(1, 0), b3, voffB); PG8_STAGE(PG8_SB(1, 1), b3 + hstep, voffB); PG8_STAGE(PG8_SA(1, 0), a3, voffA);
;             PG8_WAIT_V(8); PG8_WAIT_L(0); PG8_BAR; PG8_MMA(1, 0, At, B0); PG8_MMA(1, 1, At, B1); PG8_BAR; PG8_SCHED;
;     ...
;         }
;         if constexpr (ALIGN_EPI) { if (wr == 0) PG8_BAR; }
	s_add_i32 s16, s61, s43
	v_lshl_add_u64 v[166:167], v[166:167], 0, s[2:3]
	s_mov_b32 m0, s16
	ds_read_b128 v[190:193], v169 offset:49152
	ds_read_b128 v[194:197], v169 offset:50176
	ds_read_b128 v[216:219], v169 offset:51200
	ds_read_b128 v[220:223], v169 offset:52224
	ds_read_b128 v[224:227], v169 offset:53248
	ds_read_b128 v[228:231], v169 offset:54272
	ds_read_b128 v[232:235], v169 offset:55296
	ds_read_b128 v[236:239], v169 offset:56320
	global_load_lds_dwordx4 v[166:167], off
	s_add_i32 m0, s16, 0x2000
	s_add_u32 s16, s28, 0xb0080
	v_lshl_add_u64 v[166:167], v[198:199], 0, s[2:3]
	s_addc_u32 s17, s29, 0
	s_add_i32 s28, s62, s43
	global_load_lds_dwordx4 v[166:167], off
	v_lshl_add_u64 v[166:167], s[16:17], 0, v[138:139]
	s_mov_b32 m0, s28
	s_nop 0
	global_load_lds_dwordx4 v[166:167], off
	v_lshl_add_u64 v[166:167], s[16:17], 0, v[142:143]
	s_add_i32 m0, s28, 0x2000
	s_nop 0
	global_load_lds_dwordx4 v[166:167], off
	v_lshl_add_u64 v[166:167], v[240:241], 0, s[2:3]
	s_mov_b32 m0, s50
	s_nop 0
	global_load_lds_dwordx4 v[166:167], off
	v_lshl_add_u64 v[166:167], v[242:243], 0, s[2:3]
	s_mov_b32 m0, s51
	s_nop 0
	global_load_lds_dwordx4 v[166:167], off
	s_waitcnt vmcnt(8)
	s_waitcnt lgkmcnt(0)
	s_barrier
	s_setprio 1
	v_mfma_f32_16x16x32_bf16 v[60:63], v[128:131], v[190:193], v[60:63]
	v_mfma_f32_16x16x32_bf16 v[56:59], v[162:165], v[190:193], v[56:59]
	v_mfma_f32_16x16x32_bf16 v[44:47], v[128:131], v[216:219], v[44:47]
	v_mfma_f32_16x16x32_bf16 v[40:43], v[162:165], v[216:219], v[40:43]
	v_mfma_f32_16x16x32_bf16 v[28:31], v[128:131], v[224:227], v[28:31]
	v_mfma_f32_16x16x32_bf16 v[24:27], v[162:165], v[224:227], v[24:27]
	v_mfma_f32_16x16x32_bf16 v[12:15], v[128:131], v[232:235], v[12:15]
	v_mfma_f32_16x16x32_bf16 v[8:11], v[162:165], v[232:235], v[8:11]
	v_mfma_f32_16x16x32_bf16 v[60:63], v[132:135], v[194:197], v[60:63]
	v_mfma_f32_16x16x32_bf16 v[56:59], v[170:173], v[194:197], v[56:59]
	v_mfma_f32_16x16x32_bf16 v[44:47], v[132:135], v[220:223], v[44:47]
	v_mfma_f32_16x16x32_bf16 v[40:43], v[170:173], v[220:223], v[40:43]
	v_mfma_f32_16x16x32_bf16 v[28:31], v[132:135], v[228:231], v[28:31]
	v_mfma_f32_16x16x32_bf16 v[24:27], v[170:173], v[228:231], v[24:27]
	v_mfma_f32_16x16x32_bf16 v[12:15], v[132:135], v[236:239], v[12:15]
	v_mfma_f32_16x16x32_bf16 v[8:11], v[170:173], v[236:239], v[8:11]
	v_mfma_f32_16x16x32_bf16 v[52:55], v[174:177], v[190:193], v[52:55]
	v_mfma_f32_16x16x32_bf16 v[48:51], v[182:185], v[190:193], v[48:51]
	v_mfma_f32_16x16x32_bf16 v[36:39], v[174:177], v[216:219], v[36:39]
	v_mfma_f32_16x16x32_bf16 v[32:35], v[182:185], v[216:219], v[32:35]
	v_mfma_f32_16x16x32_bf16 v[20:23], v[174:177], v[224:227], v[20:23]
	v_mfma_f32_16x16x32_bf16 v[16:19], v[182:185], v[224:227], v[16:19]
	v_mfma_f32_16x16x32_bf16 v[4:7], v[174:177], v[232:235], v[4:7]
	v_mfma_f32_16x16x32_bf16 v[0:3], v[182:185], v[232:235], v[0:3]
	v_mfma_f32_16x16x32_bf16 v[52:55], v[178:181], v[194:197], v[52:55]
	v_mfma_f32_16x16x32_bf16 v[48:51], v[186:189], v[194:197], v[48:51]
	v_mfma_f32_16x16x32_bf16 v[36:39], v[178:181], v[220:223], v[36:39]
	v_mfma_f32_16x16x32_bf16 v[32:35], v[186:189], v[220:223], v[32:35]
	v_mfma_f32_16x16x32_bf16 v[20:23], v[178:181], v[228:231], v[20:23]
	v_mfma_f32_16x16x32_bf16 v[16:19], v[186:189], v[228:231], v[16:19]
	v_mfma_f32_16x16x32_bf16 v[4:7], v[178:181], v[236:239], v[4:7]
	v_mfma_f32_16x16x32_bf16 v[0:3], v[186:189], v[236:239], v[0:3]
	s_setprio 0
	s_barrier
	s_add_i32 s60, s60, 2
	s_add_u32 s57, s57, 0x100
	s_addc_u32 s58, s58, 0
	s_cmp_gt_u32 s60, 41
	s_mov_b64 s[16:17], s[18:19]
	s_cbranch_scc0 .LBB0_270
	s_and_b64 vcc, exec, s[12:13]
	s_cbranch_vccz .LBB0_273
	s_barrier

; #define PG8_STAGE(bufoff, gbase, voff) do { _Pragma("unroll") for (int _i = 0; _i < 2; ++_i) \
;         __builtin_amdgcn_global_load_lds((const unsigned*)((const char*)(gbase) + (voff)[_i]), (PG8_LAS unsigned*)(lds + (bufoff) + ldsw + _i * 8192), 16, 0, 0); } while (0)
; #define PG8_LDA(dst, b, h) do { _Pragma("unroll") for (int m = 0; m < 4; ++m) _Pragma("unroll") for (int k = 0; k < 2; ++k) dst[m][k] = *(const PG8_LAS bf16x8*)(lds + PG8_SA(b, h) + aoff + m * 2048 + k * 1024); } while (0)
; #define PG8_LDB(dst, b, h) do { _Pragma("unroll") for (int n = 0; n < 2; ++n) _Pragma("unroll") for (int k = 0; k < 2; ++k) dst[n][k] = *(const PG8_LAS bf16x8*)(lds + PG8_SB(b, h) + boff + n * 2048 + k * 1024); } while (0)
; #define PG8_MMA(ai, bj, At, Bt) do { __builtin_amdgcn_s_setprio(1); _Pragma("unroll") for (int m = 0; m < 4; ++m) _Pragma("unroll") for (int n = 0; n < 2; ++n) _Pragma("unroll") for (int k = 0; k < 2; ++k) \
;         acc[ai][bj][m][n] = __builtin_amdgcn_mfma_f32_16x16x32_bf16(Bt[n][k], At[m][k], acc[ai][bj][m][n], 0, 0, 0); __builtin_amdgcn_s_setprio(0); } while (0)
; #define PG8_WAIT_V(n) asm volatile("s_waitcnt vmcnt(" #n ")" ::: "memory")
; #define PG8_WAIT_L(n) asm volatile("s_waitcnt lgkmcnt(" #n ")" ::: "memory")
; #define PG8_BAR __builtin_amdgcn_s_barrier()
; #define PG8_SCHED __builtin_amdgcn_sched_barrier(0)
; template <class Epi, class Sched, bool ALIGN_EPI = false, bool SP2 = false>
; __device__ __forceinline__ void gemm_phase(PG8_LAS unsigned char* lds, const Gemm g, const Sched& S, const Epi& E) {
;     ...
;             PG8_LDB(B0, 0, 0); PG8_LDB(B1, 0, 1); PG8_SCHED; PG8_LDA(At, 0, 0); PG8_STAGE(PG8_SA(1, 1), a1 + hstep, voffA);
;             PG8_WAIT_V(8); PG8_WAIT_L(0); PG8_BAR; PG8_MMA(0, 0, At, B0); PG8_MMA(0, 1, At, B1); PG8_BAR; PG8_SCHED;
;             PG8_LDA(At, 0, 1); PG8_STAGE(PG8_SB(0, 0), b2, voffB); PG8_STAGE(PG8_SB(0, 1), b2 + hstep, voffB); PG8_STAGE(PG8_SA(0, 0), a2, voffA);
.LBB0_368:
	s_add_u32 s44, s40, 0xfffc0080
	s_addc_u32 s45, s41, -1
	s_add_i32 s66, 0, 0x10000
	s_cmp_eq_u32 s63, 12
	s_cselect_b32 s47, s15, s45
	s_cselect_b32 s46, s29, s44
	v_add_u32_e32 v142, s66, v159
	s_cselect_b32 s45, s13, s62
	s_cselect_b32 s44, s58, s61
	s_add_i32 s68, 0, 0x14000
	ds_read_b128 v[162:165], v142
	ds_read_b128 v[166:169], v142 offset:1024
	ds_read_b128 v[170:173], v142 offset:2048
	ds_read_b128 v[174:177], v142 offset:3072
	v_add_u32_e32 v142, s68, v159
	ds_read_b128 v[178:181], v142
	ds_read_b128 v[182:185], v142 offset:1024
	ds_read_b128 v[186:189], v142 offset:2048
	ds_read_b128 v[190:193], v142 offset:3072
	v_lshl_add_u64 v[142:143], s[40:41], 0, v[138:139]
	s_add_i32 m0, s43, 0xc000
	ds_read_b128 v[194:197], v161
	ds_read_b128 v[216:219], v161 offset:1024
	ds_read_b128 v[220:223], v161 offset:2048
	ds_read_b128 v[224:227], v161 offset:3072
	ds_read_b128 v[228:231], v161 offset:4096
	ds_read_b128 v[232:235], v161 offset:5120
	ds_read_b128 v[236:239], v161 offset:6144
	ds_read_b128 v[240:243], v161 offset:7168
	global_load_lds_dwordx4 v[142:143], off
	v_lshl_add_u64 v[142:143], s[40:41], 0, v[140:141]
	s_add_i32 m0, s43, 0xe000
	s_nop 0
	global_load_lds_dwordx4 v[142:143], off
	s_waitcnt vmcnt(8)
	s_waitcnt lgkmcnt(0)
	s_barrier
	s_setprio 1
	v_mfma_f32_16x16x32_bf16 v[124:127], v[162:165], v[194:197], v[124:127]
	v_mfma_f32_16x16x32_bf16 v[120:123], v[170:173], v[194:197], v[120:123]
	v_mfma_f32_16x16x32_bf16 v[108:111], v[162:165], v[220:223], v[108:111]
	v_mfma_f32_16x16x32_bf16 v[104:107], v[170:173], v[220:223], v[104:107]
	v_mfma_f32_16x16x32_bf16 v[92:95], v[162:165], v[228:231], v[92:95]
	v_mfma_f32_16x16x32_bf16 v[88:91], v[170:173], v[228:231], v[88:91]
	v_mfma_f32_16x16x32_bf16 v[76:79], v[162:165], v[236:239], v[76:79]
	v_mfma_f32_16x16x32_bf16 v[72:75], v[170:173], v[236:239], v[72:75]
	v_mfma_f32_16x16x32_bf16 v[124:127], v[166:169], v[216:219], v[124:127]
	v_mfma_f32_16x16x32_bf16 v[120:123], v[174:177], v[216:219], v[120:123]
	v_mfma_f32_16x16x32_bf16 v[108:111], v[166:169], v[224:227], v[108:111]
	v_mfma_f32_16x16x32_bf16 v[104:107], v[174:177], v[224:227], v[104:107]
	v_mfma_f32_16x16x32_bf16 v[92:95], v[166:169], v[232:235], v[92:95]
	v_mfma_f32_16x16x32_bf16 v[88:91], v[174:177], v[232:235], v[88:91]
	v_mfma_f32_16x16x32_bf16 v[76:79], v[166:169], v[240:243], v[76:79]
	v_mfma_f32_16x16x32_bf16 v[72:75], v[174:177], v[240:243], v[72:75]
	v_mfma_f32_16x16x32_bf16 v[116:119], v[178:181], v[194:197], v[116:119]
	v_mfma_f32_16x16x32_bf16 v[112:115], v[186:189], v[194:197], v[112:115]
	v_mfma_f32_16x16x32_bf16 v[100:103], v[178:181], v[220:223], v[100:103]
	v_mfma_f32_16x16x32_bf16 v[96:99], v[186:189], v[220:223], v[96:99]
	v_mfma_f32_16x16x32_bf16 v[84:87], v[178:181], v[228:231], v[84:87]
	v_mfma_f32_16x16x32_bf16 v[80:83], v[186:189], v[228:231], v[80:83]
	v_mfma_f32_16x16x32_bf16 v[68:71], v[178:181], v[236:239], v[68:71]
	v_mfma_f32_16x16x32_bf16 v[64:67], v[186:189], v[236:239], v[64:67]
	v_mfma_f32_16x16x32_bf16 v[116:119], v[182:185], v[216:219], v[116:119]
	v_mfma_f32_16x16x32_bf16 v[112:115], v[190:193], v[216:219], v[112:115]
	v_mfma_f32_16x16x32_bf16 v[100:103], v[182:185], v[224:227], v[100:103]
	v_mfma_f32_16x16x32_bf16 v[96:99], v[190:193], v[224:227], v[96:99]
	v_mfma_f32_16x16x32_bf16 v[84:87], v[182:185], v[232:235], v[84:87]
	v_mfma_f32_16x16x32_bf16 v[80:83], v[190:193], v[232:235], v[80:83]
	v_mfma_f32_16x16x32_bf16 v[68:71], v[182:185], v[240:243], v[68:71]
	v_mfma_f32_16x16x32_bf16 v[64:67], v[190:193], v[240:243], v[64:67]
	s_setprio 0
	s_barrier
	s_add_i32 s66, s66, s51
	v_lshl_add_u64 v[142:143], s[44:45], 0, v[130:131]
	s_mov_b32 m0, s66
	ds_read_b128 v[194:197], v161 offset:16384
	ds_read_b128 v[216:219], v161 offset:17408
	ds_read_b128 v[220:223], v161 offset:18432
	ds_read_b128 v[224:227], v161 offset:19456
	ds_read_b128 v[228:231], v161 offset:20480
	ds_read_b128 v[232:235], v161 offset:21504
	ds_read_b128 v[236:239], v161 offset:22528
	ds_read_b128 v[240:243], v161 offset:23552
	global_load_lds_dwordx4 v[142:143], off
	s_add_i32 m0, s66, 0x2000
	s_add_u32 s66, s44, 0x40000
	v_lshl_add_u64 v[156:157], s[44:45], 0, v[134:135]
	s_addc_u32 s67, s45, 0
	s_add_i32 s68, s68, s51
	global_load_lds_dwordx4 v[156:157], off
	v_lshl_add_u64 v[198:199], s[66:67], 0, v[130:131]
	s_mov_b32 m0, s68
	v_lshl_add_u64 v[244:245], s[46:47], 0, v[132:133]
	global_load_lds_dwordx4 v[198:199], off
	v_lshl_add_u64 v[198:199], s[66:67], 0, v[134:135]
	s_add_i32 m0, s68, 0x2000
	s_nop 0
	global_load_lds_dwordx4 v[198:199], off
	v_lshl_add_u64 v[198:199], s[46:47], 0, v[128:129]
	s_mov_b32 m0, s43
	s_nop 0
	global_load_lds_dwordx4 v[198:199], off
	s_mov_b32 m0, s52
	s_nop 0
	global_load_lds_dwordx4 v[244:245], off
	s_waitcnt vmcnt(8)
	s_waitcnt lgkmcnt(0)
	s_barrier
; #define PG8_STAGE(bufoff, gbase, voff) do { _Pragma("unroll") for (int _i = 0; _i < 2; ++_i) \
;         __builtin_amdgcn_global_load_lds((const unsigned*)((const char*)(gbase) + (voff)[_i]), (PG8_LAS unsigned*)(lds + (bufoff) + ldsw + _i * 8192), 16, 0, 0); } while (0)
; #define PG8_LDA(dst, b, h) do { _Pragma("unroll") for (int m = 0; m < 4; ++m) _Pragma("unroll") for (int k = 0; k < 2; ++k) dst[m][k] = *(const PG8_LAS bf16x8*)(lds + PG8_SA(b, h) + aoff + m * 2048 + k * 1024); } while (0)
; #define PG8_LDB(dst, b, h) do { _Pragma("unroll") for (int n = 0; n < 2; ++n) _Pragma("unroll") for (int k = 0; k < 2; ++k) dst[n][k] = *(const PG8_LAS bf16x8*)(lds + PG8_SB(b, h) + boff + n * 2048 + k * 1024); } while (0)
; #define PG8_MMA(ai, bj, At, Bt) do { __builtin_amdgcn_s_setprio(1); _Pragma("unroll") for (int m = 0; m < 4; ++m) _Pragma("unroll") for (int n = 0; n < 2; ++n) _Pragma("unroll") for (int k = 0; k < 2; ++k) \
;         acc[ai][bj][m][n] = __builtin_amdgcn_mfma_f32_16x16x32_bf16(Bt[n][k], At[m][k], acc[ai][bj][m][n], 0, 0, 0); __builtin_amdgcn_s_setprio(0); } while (0)
; #define PG8_WAIT_V(n) asm volatile("s_waitcnt vmcnt(" #n ")" ::: "memory")
; #define PG8_WAIT_L(n) asm volatile("s_waitcnt lgkmcnt(" #n ")" ::: "memory")
; #define PG8_BAR __builtin_amdgcn_s_barrier()
; #define PG8_SCHED __builtin_amdgcn_sched_barrier(0)
; template <class Epi, class Sched, bool ALIGN_EPI = false, bool SP2 = false>
; __device__ __forceinline__ void gemm_phase(PG8_LAS unsigned char* lds, const Gemm g, const Sched& S, const Epi& E) {
;     ...
;             PG8_WAIT_V(8); PG8_WAIT_L(0); PG8_BAR; PG8_MMA(1, 0, At, B0); PG8_MMA(1, 1, At, B1); PG8_BAR; PG8_SCHED;
;             PG8_LDB(B0, 1, 0); PG8_LDB(B1, 1, 1); PG8_SCHED; PG8_LDA(At, 1, 0); PG8_STAGE(PG8_SA(0, 1), a2 + hstep, voffA);
;             PG8_WAIT_V(8); PG8_WAIT_L(0); PG8_BAR; PG8_MMA(0, 0, At, B0); PG8_MMA(0, 1, At, B1); PG8_BAR; PG8_SCHED;
	s_setprio 1
	v_mfma_f32_16x16x32_bf16 v[60:63], v[162:165], v[194:197], v[60:63]
	v_mfma_f32_16x16x32_bf16 v[56:59], v[170:173], v[194:197], v[56:59]
	v_mfma_f32_16x16x32_bf16 v[44:47], v[162:165], v[220:223], v[44:47]
	v_mfma_f32_16x16x32_bf16 v[40:43], v[170:173], v[220:223], v[40:43]
	v_mfma_f32_16x16x32_bf16 v[28:31], v[162:165], v[228:231], v[28:31]
	v_mfma_f32_16x16x32_bf16 v[24:27], v[170:173], v[228:231], v[24:27]
	v_mfma_f32_16x16x32_bf16 v[12:15], v[162:165], v[236:239], v[12:15]
	v_mfma_f32_16x16x32_bf16 v[8:11], v[170:173], v[236:239], v[8:11]
	v_mfma_f32_16x16x32_bf16 v[60:63], v[166:169], v[216:219], v[60:63]
	v_mfma_f32_16x16x32_bf16 v[56:59], v[174:177], v[216:219], v[56:59]
	v_mfma_f32_16x16x32_bf16 v[44:47], v[166:169], v[224:227], v[44:47]
	v_mfma_f32_16x16x32_bf16 v[40:43], v[174:177], v[224:227], v[40:43]
	v_mfma_f32_16x16x32_bf16 v[28:31], v[166:169], v[232:235], v[28:31]
	v_mfma_f32_16x16x32_bf16 v[24:27], v[174:177], v[232:235], v[24:27]
	v_mfma_f32_16x16x32_bf16 v[12:15], v[166:169], v[240:243], v[12:15]
	v_mfma_f32_16x16x32_bf16 v[8:11], v[174:177], v[240:243], v[8:11]
	v_mfma_f32_16x16x32_bf16 v[52:55], v[178:181], v[194:197], v[52:55]
	v_mfma_f32_16x16x32_bf16 v[48:51], v[186:189], v[194:197], v[48:51]
	v_mfma_f32_16x16x32_bf16 v[36:39], v[178:181], v[220:223], v[36:39]
	v_mfma_f32_16x16x32_bf16 v[32:35], v[186:189], v[220:223], v[32:35]
	v_mfma_f32_16x16x32_bf16 v[20:23], v[178:181], v[228:231], v[20:23]
	v_mfma_f32_16x16x32_bf16 v[16:19], v[186:189], v[228:231], v[16:19]
	v_mfma_f32_16x16x32_bf16 v[4:7], v[178:181], v[236:239], v[4:7]
	v_mfma_f32_16x16x32_bf16 v[0:3], v[186:189], v[236:239], v[0:3]
	v_mfma_f32_16x16x32_bf16 v[52:55], v[182:185], v[216:219], v[52:55]
	v_mfma_f32_16x16x32_bf16 v[48:51], v[190:193], v[216:219], v[48:51]
	v_mfma_f32_16x16x32_bf16 v[36:39], v[182:185], v[224:227], v[36:39]
	v_mfma_f32_16x16x32_bf16 v[32:35], v[190:193], v[224:227], v[32:35]
	v_mfma_f32_16x16x32_bf16 v[20:23], v[182:185], v[232:235], v[20:23]
	v_mfma_f32_16x16x32_bf16 v[16:19], v[190:193], v[232:235], v[16:19]
	v_mfma_f32_16x16x32_bf16 v[4:7], v[182:185], v[240:243], v[4:7]
	v_mfma_f32_16x16x32_bf16 v[0:3], v[190:193], v[240:243], v[0:3]
	s_setprio 0
	s_barrier
	s_add_i32 s66, 0, 0x18000
	v_add_u32_e32 v144, s66, v159
	s_add_i32 s67, 0, 0x1c000
	ds_read_b128 v[162:165], v144
	ds_read_b128 v[166:169], v144 offset:1024
	ds_read_b128 v[170:173], v144 offset:2048
	ds_read_b128 v[174:177], v144 offset:3072
	v_add_u32_e32 v144, s67, v159
	ds_read_b128 v[178:181], v144
	ds_read_b128 v[182:185], v144 offset:1024
	ds_read_b128 v[186:189], v144 offset:2048
	ds_read_b128 v[190:193], v144 offset:3072
	s_add_u32 s46, s46, 0x40000
	s_addc_u32 s47, s47, 0
	s_mov_b32 m0, s53
	v_lshl_add_u64 v[246:247], s[46:47], 0, v[128:129]
	ds_read_b128 v[194:197], v161 offset:32768
	ds_read_b128 v[216:219], v161 offset:33792
	ds_read_b128 v[220:223], v161 offset:34816
	ds_read_b128 v[224:227], v161 offset:35840
	ds_read_b128 v[228:231], v161 offset:36864
	ds_read_b128 v[232:235], v161 offset:37888
	ds_read_b128 v[236:239], v161 offset:38912
	ds_read_b128 v[240:243], v161 offset:39936
	global_load_lds_dwordx4 v[246:247], off
	v_lshl_add_u64 v[246:247], s[46:47], 0, v[132:133]
	s_mov_b32 m0, s54
	s_nop 0
	global_load_lds_dwordx4 v[246:247], off
	s_waitcnt vmcnt(8)
	s_waitcnt lgkmcnt(0)
	s_barrier
	s_setprio 1
	v_mfma_f32_16x16x32_bf16 v[124:127], v[162:165], v[194:197], v[124:127]
	v_mfma_f32_16x16x32_bf16 v[120:123], v[170:173], v[194:197], v[120:123]
	v_mfma_f32_16x16x32_bf16 v[108:111], v[162:165], v[220:223], v[108:111]
	v_mfma_f32_16x16x32_bf16 v[104:107], v[170:173], v[220:223], v[104:107]
	v_mfma_f32_16x16x32_bf16 v[92:95], v[162:165], v[228:231], v[92:95]
	v_mfma_f32_16x16x32_bf16 v[88:91], v[170:173], v[228:231], v[88:91]
	v_mfma_f32_16x16x32_bf16 v[76:79], v[162:165], v[236:239], v[76:79]
	v_mfma_f32_16x16x32_bf16 v[72:75], v[170:173], v[236:239], v[72:75]
	v_mfma_f32_16x16x32_bf16 v[124:127], v[166:169], v[216:219], v[124:127]
	v_mfma_f32_16x16x32_bf16 v[120:123], v[174:177], v[216:219], v[120:123]
	v_mfma_f32_16x16x32_bf16 v[108:111], v[166:169], v[224:227], v[108:111]
	v_mfma_f32_16x16x32_bf16 v[104:107], v[174:177], v[224:227], v[104:107]
	v_mfma_f32_16x16x32_bf16 v[92:95], v[166:169], v[232:235], v[92:95]
	v_mfma_f32_16x16x32_bf16 v[88:91], v[174:177], v[232:235], v[88:91]
	v_mfma_f32_16x16x32_bf16 v[76:79], v[166:169], v[240:243], v[76:79]
	v_mfma_f32_16x16x32_bf16 v[72:75], v[174:177], v[240:243], v[72:75]
	v_mfma_f32_16x16x32_bf16 v[116:119], v[178:181], v[194:197], v[116:119]
	v_mfma_f32_16x16x32_bf16 v[112:115], v[186:189], v[194:197], v[112:115]
	v_mfma_f32_16x16x32_bf16 v[100:103], v[178:181], v[220:223], v[100:103]
	v_mfma_f32_16x16x32_bf16 v[96:99], v[186:189], v[220:223], v[96:99]
	v_mfma_f32_16x16x32_bf16 v[84:87], v[178:181], v[228:231], v[84:87]
	v_mfma_f32_16x16x32_bf16 v[80:83], v[186:189], v[228:231], v[80:83]
	v_mfma_f32_16x16x32_bf16 v[68:71], v[178:181], v[236:239], v[68:71]
	v_mfma_f32_16x16x32_bf16 v[64:67], v[186:189], v[236:239], v[64:67]
	v_mfma_f32_16x16x32_bf16 v[116:119], v[182:185], v[216:219], v[116:119]
	v_mfma_f32_16x16x32_bf16 v[112:115], v[190:193], v[216:219], v[112:115]
	v_mfma_f32_16x16x32_bf16 v[100:103], v[182:185], v[224:227], v[100:103]
	v_mfma_f32_16x16x32_bf16 v[96:99], v[190:193], v[224:227], v[96:99]
	v_mfma_f32_16x16x32_bf16 v[84:87], v[182:185], v[232:235], v[84:87]
	v_mfma_f32_16x16x32_bf16 v[80:83], v[190:193], v[232:235], v[80:83]
	v_mfma_f32_16x16x32_bf16 v[68:71], v[182:185], v[240:243], v[68:71]
	v_mfma_f32_16x16x32_bf16 v[64:67], v[190:193], v[240:243], v[64:67]
	s_setprio 0
	s_barrier
; #define PG8_STAGE(bufoff, gbase, voff) do { _Pragma("unroll") for (int _i = 0; _i < 2; ++_i) \
;         __builtin_amdgcn_global_load_lds((const unsigned*)((const char*)(gbase) + (voff)[_i]), (PG8_LAS unsigned*)(lds + (bufoff) + ldsw + _i * 8192), 16, 0, 0); } while (0)
; #define PG8_LDA(dst, b, h) do { _Pragma("unroll") for (int m = 0; m < 4; ++m) _Pragma("unroll") for (int k = 0; k < 2; ++k) dst[m][k] = *(const PG8_LAS bf16x8*)(lds + PG8_SA(b, h) + aoff + m * 2048 + k * 1024); } while (0)
; #define PG8_MMA(ai, bj, At, Bt) do { __builtin_amdgcn_s_setprio(1); _Pragma("unroll") for (int m = 0; m < 4; ++m) _Pragma("unroll") for (int n = 0; n < 2; ++n) _Pragma("unroll") for (int k = 0; k < 2; ++k) \
;         acc[ai][bj][m][n] = __builtin_amdgcn_mfma_f32_16x16x32_bf16(Bt[n][k], At[m][k], acc[ai][bj][m][n], 0, 0, 0); __builtin_amdgcn_s_setprio(0); } while (0)
; #define PG8_WAIT_V(n) asm volatile("s_waitcnt vmcnt(" #n ")" ::: "memory")
; #define PG8_WAIT_L(n) asm volatile("s_waitcnt lgkmcnt(" #n ")" ::: "memory")
; #define PG8_BAR __builtin_amdgcn_s_barrier()
; #define PG8_SCHED __builtin_amdgcn_sched_barrier(0)
; template <class Epi, class Sched, bool ALIGN_EPI = false, bool SP2 = false>
; __device__ __forceinline__ void gemm_phase(PG8_LAS unsigned char* lds, const Gemm g, const Sched& S, const Epi& E) {
;     ...
;             PG8_LDA(At, 1, 1); PG8_STAGE(PG8_SB(1, 0), b3, voffB); PG8_STAGE(PG8_SB(1, 1), b3 + hstep, voffB); PG8_STAGE(PG8_SA(1, 0), a3, voffA);
;             PG8_WAIT_V(8); PG8_WAIT_L(0); PG8_BAR; PG8_MMA(1, 0, At, B0); PG8_MMA(1, 1, At, B1); PG8_BAR; PG8_SCHED;
;     ...
;         }
;         if constexpr (ALIGN_EPI) { if (wr == 0) PG8_BAR; }
	s_add_i32 s46, s66, s51
	v_lshl_add_u64 v[142:143], v[142:143], 0, s[2:3]
	s_mov_b32 m0, s46
	ds_read_b128 v[194:197], v161 offset:49152
	ds_read_b128 v[216:219], v161 offset:50176
	ds_read_b128 v[220:223], v161 offset:51200
	ds_read_b128 v[224:227], v161 offset:52224
	ds_read_b128 v[228:231], v161 offset:53248
	ds_read_b128 v[232:235], v161 offset:54272
	ds_read_b128 v[236:239], v161 offset:55296
	ds_read_b128 v[240:243], v161 offset:56320
	global_load_lds_dwordx4 v[142:143], off
	s_add_i32 m0, s46, 0x2000
	s_add_u32 s44, s44, 0x40080
	v_lshl_add_u64 v[142:143], v[156:157], 0, s[2:3]
	s_addc_u32 s45, s45, 0
	s_add_i32 s46, s67, s51
	global_load_lds_dwordx4 v[142:143], off
	v_lshl_add_u64 v[142:143], s[44:45], 0, v[130:131]
	s_mov_b32 m0, s46
	s_nop 0
	global_load_lds_dwordx4 v[142:143], off
	v_lshl_add_u64 v[142:143], s[44:45], 0, v[134:135]
	s_add_i32 m0, s46, 0x2000
	s_nop 0
	global_load_lds_dwordx4 v[142:143], off
	v_lshl_add_u64 v[142:143], v[198:199], 0, s[2:3]
	s_mov_b32 m0, s55
	s_nop 0
	global_load_lds_dwordx4 v[142:143], off
	v_lshl_add_u64 v[142:143], v[244:245], 0, s[2:3]
	s_mov_b32 m0, s56
	s_nop 0
	global_load_lds_dwordx4 v[142:143], off
	s_waitcnt vmcnt(8)
	s_waitcnt lgkmcnt(0)
	s_barrier
	s_setprio 1
	v_mfma_f32_16x16x32_bf16 v[60:63], v[162:165], v[194:197], v[60:63]
	v_mfma_f32_16x16x32_bf16 v[56:59], v[170:173], v[194:197], v[56:59]
	v_mfma_f32_16x16x32_bf16 v[44:47], v[162:165], v[220:223], v[44:47]
	v_mfma_f32_16x16x32_bf16 v[40:43], v[170:173], v[220:223], v[40:43]
	v_mfma_f32_16x16x32_bf16 v[28:31], v[162:165], v[228:231], v[28:31]
	v_mfma_f32_16x16x32_bf16 v[24:27], v[170:173], v[228:231], v[24:27]
	v_mfma_f32_16x16x32_bf16 v[12:15], v[162:165], v[236:239], v[12:15]
	v_mfma_f32_16x16x32_bf16 v[8:11], v[170:173], v[236:239], v[8:11]
	v_mfma_f32_16x16x32_bf16 v[60:63], v[166:169], v[216:219], v[60:63]
	v_mfma_f32_16x16x32_bf16 v[56:59], v[174:177], v[216:219], v[56:59]
	v_mfma_f32_16x16x32_bf16 v[44:47], v[166:169], v[224:227], v[44:47]
	v_mfma_f32_16x16x32_bf16 v[40:43], v[174:177], v[224:227], v[40:43]
	v_mfma_f32_16x16x32_bf16 v[28:31], v[166:169], v[232:235], v[28:31]
	v_mfma_f32_16x16x32_bf16 v[24:27], v[174:177], v[232:235], v[24:27]
	v_mfma_f32_16x16x32_bf16 v[12:15], v[166:169], v[240:243], v[12:15]
	v_mfma_f32_16x16x32_bf16 v[8:11], v[174:177], v[240:243], v[8:11]
	v_mfma_f32_16x16x32_bf16 v[52:55], v[178:181], v[194:197], v[52:55]
	v_mfma_f32_16x16x32_bf16 v[48:51], v[186:189], v[194:197], v[48:51]
	v_mfma_f32_16x16x32_bf16 v[36:39], v[178:181], v[220:223], v[36:39]
	v_mfma_f32_16x16x32_bf16 v[32:35], v[186:189], v[220:223], v[32:35]
	v_mfma_f32_16x16x32_bf16 v[20:23], v[178:181], v[228:231], v[20:23]
	v_mfma_f32_16x16x32_bf16 v[16:19], v[186:189], v[228:231], v[16:19]
	v_mfma_f32_16x16x32_bf16 v[4:7], v[178:181], v[236:239], v[4:7]
	v_mfma_f32_16x16x32_bf16 v[0:3], v[186:189], v[236:239], v[0:3]
	v_mfma_f32_16x16x32_bf16 v[52:55], v[182:185], v[216:219], v[52:55]
	v_mfma_f32_16x16x32_bf16 v[48:51], v[190:193], v[216:219], v[48:51]
	v_mfma_f32_16x16x32_bf16 v[36:39], v[182:185], v[224:227], v[36:39]
	v_mfma_f32_16x16x32_bf16 v[32:35], v[190:193], v[224:227], v[32:35]
	v_mfma_f32_16x16x32_bf16 v[20:23], v[182:185], v[232:235], v[20:23]
	v_mfma_f32_16x16x32_bf16 v[16:19], v[190:193], v[232:235], v[16:19]
	v_mfma_f32_16x16x32_bf16 v[4:7], v[182:185], v[240:243], v[4:7]
	v_mfma_f32_16x16x32_bf16 v[0:3], v[190:193], v[240:243], v[0:3]
	s_setprio 0
	s_barrier
	s_add_i32 s63, s63, 2
	s_add_u32 s40, s40, 0x100
	s_addc_u32 s41, s41, 0
	s_add_u32 s61, s61, 0x100
	s_addc_u32 s62, s62, 0
	s_cmp_gt_u32 s63, 13
	s_cbranch_scc0 .LBB0_368
	s_and_b64 vcc, exec, s[10:11]
	s_cbranch_vccz .LBB0_371
	s_barrier

; #define PG8_STAGE(bufoff, gbase, voff) do { _Pragma("unroll") for (int _i = 0; _i < 2; ++_i) \
;         __builtin_amdgcn_global_load_lds((const unsigned*)((const char*)(gbase) + (voff)[_i]), (PG8_LAS unsigned*)(lds + (bufoff) + ldsw + _i * 8192), 16, 0, 0); } while (0)
; #define PG8_LDA(dst, b, h) do { _Pragma("unroll") for (int m = 0; m < 4; ++m) _Pragma("unroll") for (int k = 0; k < 2; ++k) dst[m][k] = *(const PG8_LAS bf16x8*)(lds + PG8_SA(b, h) + aoff + m * 2048 + k * 1024); } while (0)
; #define PG8_LDB(dst, b, h) do { _Pragma("unroll") for (int n = 0; n < 2; ++n) _Pragma("unroll") for (int k = 0; k < 2; ++k) dst[n][k] = *(const PG8_LAS bf16x8*)(lds + PG8_SB(b, h) + boff + n * 2048 + k * 1024); } while (0)
; #define PG8_MMA(ai, bj, At, Bt) do { __builtin_amdgcn_s_setprio(1); _Pragma("unroll") for (int m = 0; m < 4; ++m) _Pragma("unroll") for (int n = 0; n < 2; ++n) _Pragma("unroll") for (int k = 0; k < 2; ++k) \
;         acc[ai][bj][m][n] = __builtin_amdgcn_mfma_f32_16x16x32_bf16(Bt[n][k], At[m][k], acc[ai][bj][m][n], 0, 0, 0); __builtin_amdgcn_s_setprio(0); } while (0)
; #define PG8_WAIT_V(n) asm volatile("s_waitcnt vmcnt(" #n ")" ::: "memory")
; #define PG8_WAIT_L(n) asm volatile("s_waitcnt lgkmcnt(" #n ")" ::: "memory")
; #define PG8_BAR __builtin_amdgcn_s_barrier()
; #define PG8_SCHED __builtin_amdgcn_sched_barrier(0)
; template <class Epi, class Sched, bool ALIGN_EPI = false, bool SP2 = false>
; __device__ __forceinline__ void gemm_phase(PG8_LAS unsigned char* lds, const Gemm g, const Sched& S, const Epi& E) {
;     ...
;             PG8_LDB(B0, 0, 0); PG8_LDB(B1, 0, 1); PG8_SCHED; PG8_LDA(At, 0, 0); PG8_STAGE(PG8_SA(1, 1), a1 + hstep, voffA);
;             PG8_WAIT_V(8); PG8_WAIT_L(0); PG8_BAR; PG8_MMA(0, 0, At, B0); PG8_MMA(0, 1, At, B1); PG8_BAR; PG8_SCHED;
;             PG8_LDA(At, 0, 1); PG8_STAGE(PG8_SB(0, 0), b2, voffB); PG8_STAGE(PG8_SB(0, 1), b2 + hstep, voffB); PG8_STAGE(PG8_SA(0, 0), a2, voffA);
.LBB0_426:
	s_add_u32 s38, s28, 0xfffc0080
	s_addc_u32 s39, s29, -1
	s_add_i32 s58, 0, 0x10000
	s_cmp_eq_u32 s57, 12
	s_cselect_b32 s41, s13, s39
	s_cselect_b32 s40, s53, s38
	s_cselect_b32 s39, s11, s56
	s_cselect_b32 s38, s54, s55
	s_add_i32 s62, 0, 0x14000
	v_add_u32_e32 v140, s58, v171
	v_add_u32_e32 v178, s62, v171
	ds_read_b128 v[128:131], v140
	ds_read_b128 v[132:135], v140 offset:1024
	ds_read_b128 v[136:139], v140 offset:2048
	ds_read_b128 v[140:143], v140 offset:3072
	ds_read_b128 v[162:165], v178
	ds_read_b128 v[166:169], v178 offset:1024
	ds_read_b128 v[174:177], v178 offset:2048
	ds_read_b128 v[178:181], v178 offset:3072
	v_lshl_add_u64 v[198:199], s[28:29], 0, v[158:159]
	s_add_i32 m0, s47, 0xc000
	ds_read_b128 v[182:185], v173
	ds_read_b128 v[186:189], v173 offset:1024
	ds_read_b128 v[190:193], v173 offset:2048
	ds_read_b128 v[194:197], v173 offset:3072
	ds_read_b128 v[216:219], v173 offset:4096
	ds_read_b128 v[220:223], v173 offset:5120
	ds_read_b128 v[224:227], v173 offset:6144
	ds_read_b128 v[228:231], v173 offset:7168
	global_load_lds_dwordx4 v[198:199], off
	v_lshl_add_u64 v[198:199], s[28:29], 0, v[160:161]
	s_add_i32 m0, s47, 0xe000
	s_nop 0
	global_load_lds_dwordx4 v[198:199], off
	s_waitcnt vmcnt(8)
	s_waitcnt lgkmcnt(0)
	s_barrier
	s_setprio 1
	v_mfma_f32_16x16x32_bf16 v[124:127], v[128:131], v[182:185], v[124:127]
	v_mfma_f32_16x16x32_bf16 v[92:95], v[136:139], v[182:185], v[92:95]
	v_mfma_f32_16x16x32_bf16 v[120:123], v[128:131], v[190:193], v[120:123]
	v_mfma_f32_16x16x32_bf16 v[88:91], v[136:139], v[190:193], v[88:91]
	v_mfma_f32_16x16x32_bf16 v[116:119], v[128:131], v[216:219], v[116:119]
	v_mfma_f32_16x16x32_bf16 v[84:87], v[136:139], v[216:219], v[84:87]
	v_mfma_f32_16x16x32_bf16 v[112:115], v[128:131], v[224:227], v[112:115]
	v_mfma_f32_16x16x32_bf16 v[80:83], v[136:139], v[224:227], v[80:83]
	v_mfma_f32_16x16x32_bf16 v[124:127], v[132:135], v[186:189], v[124:127]
	v_mfma_f32_16x16x32_bf16 v[92:95], v[140:143], v[186:189], v[92:95]
	v_mfma_f32_16x16x32_bf16 v[120:123], v[132:135], v[194:197], v[120:123]
	v_mfma_f32_16x16x32_bf16 v[88:91], v[140:143], v[194:197], v[88:91]
	v_mfma_f32_16x16x32_bf16 v[116:119], v[132:135], v[220:223], v[116:119]
	v_mfma_f32_16x16x32_bf16 v[84:87], v[140:143], v[220:223], v[84:87]
	v_mfma_f32_16x16x32_bf16 v[112:115], v[132:135], v[228:231], v[112:115]
	v_mfma_f32_16x16x32_bf16 v[80:83], v[140:143], v[228:231], v[80:83]
	v_mfma_f32_16x16x32_bf16 v[60:63], v[162:165], v[182:185], v[60:63]
	v_mfma_f32_16x16x32_bf16 v[28:31], v[174:177], v[182:185], v[28:31]
	v_mfma_f32_16x16x32_bf16 v[56:59], v[162:165], v[190:193], v[56:59]
	v_mfma_f32_16x16x32_bf16 v[24:27], v[174:177], v[190:193], v[24:27]
	v_mfma_f32_16x16x32_bf16 v[52:55], v[162:165], v[216:219], v[52:55]
	v_mfma_f32_16x16x32_bf16 v[20:23], v[174:177], v[216:219], v[20:23]
	v_mfma_f32_16x16x32_bf16 v[48:51], v[162:165], v[224:227], v[48:51]
	v_mfma_f32_16x16x32_bf16 v[16:19], v[174:177], v[224:227], v[16:19]
	v_mfma_f32_16x16x32_bf16 v[60:63], v[166:169], v[186:189], v[60:63]
	v_mfma_f32_16x16x32_bf16 v[28:31], v[178:181], v[186:189], v[28:31]
	v_mfma_f32_16x16x32_bf16 v[56:59], v[166:169], v[194:197], v[56:59]
	v_mfma_f32_16x16x32_bf16 v[24:27], v[178:181], v[194:197], v[24:27]
	v_mfma_f32_16x16x32_bf16 v[52:55], v[166:169], v[220:223], v[52:55]
	v_mfma_f32_16x16x32_bf16 v[20:23], v[178:181], v[220:223], v[20:23]
	v_mfma_f32_16x16x32_bf16 v[48:51], v[166:169], v[228:231], v[48:51]
	v_mfma_f32_16x16x32_bf16 v[16:19], v[178:181], v[228:231], v[16:19]
	s_setprio 0
	s_barrier
	s_add_i32 s58, s58, s46
	v_lshl_add_u64 v[198:199], s[38:39], 0, v[144:145]
	s_mov_b32 m0, s58
	ds_read_b128 v[182:185], v173 offset:16384
	ds_read_b128 v[186:189], v173 offset:17408
	ds_read_b128 v[190:193], v173 offset:18432
	ds_read_b128 v[194:197], v173 offset:19456
	ds_read_b128 v[216:219], v173 offset:20480
	ds_read_b128 v[220:223], v173 offset:21504
	ds_read_b128 v[224:227], v173 offset:22528
	ds_read_b128 v[228:231], v173 offset:23552
	global_load_lds_dwordx4 v[198:199], off
	s_add_i32 m0, s58, 0x2000
	s_add_u32 s60, s38, 0x40000
	v_lshl_add_u64 v[232:233], s[38:39], 0, v[156:157]
	s_addc_u32 s61, s39, 0
	s_add_i32 s58, s62, s46
	global_load_lds_dwordx4 v[232:233], off
	v_lshl_add_u64 v[234:235], s[60:61], 0, v[144:145]
	s_mov_b32 m0, s58
	v_lshl_add_u64 v[236:237], s[40:41], 0, v[156:157]
	global_load_lds_dwordx4 v[234:235], off
	v_lshl_add_u64 v[234:235], s[60:61], 0, v[156:157]
	s_add_i32 m0, s58, 0x2000
	s_nop 0
	global_load_lds_dwordx4 v[234:235], off
	v_lshl_add_u64 v[234:235], s[40:41], 0, v[144:145]
	s_mov_b32 m0, s47
	s_nop 0
	global_load_lds_dwordx4 v[234:235], off
	s_mov_b32 m0, s48
	s_nop 0
	global_load_lds_dwordx4 v[236:237], off
	s_waitcnt vmcnt(8)
	s_waitcnt lgkmcnt(0)
	s_barrier
; #define PG8_STAGE(bufoff, gbase, voff) do { _Pragma("unroll") for (int _i = 0; _i < 2; ++_i) \
;         __builtin_amdgcn_global_load_lds((const unsigned*)((const char*)(gbase) + (voff)[_i]), (PG8_LAS unsigned*)(lds + (bufoff) + ldsw + _i * 8192), 16, 0, 0); } while (0)
; #define PG8_LDA(dst, b, h) do { _Pragma("unroll") for (int m = 0; m < 4; ++m) _Pragma("unroll") for (int k = 0; k < 2; ++k) dst[m][k] = *(const PG8_LAS bf16x8*)(lds + PG8_SA(b, h) + aoff + m * 2048 + k * 1024); } while (0)
; #define PG8_LDB(dst, b, h) do { _Pragma("unroll") for (int n = 0; n < 2; ++n) _Pragma("unroll") for (int k = 0; k < 2; ++k) dst[n][k] = *(const PG8_LAS bf16x8*)(lds + PG8_SB(b, h) + boff + n * 2048 + k * 1024); } while (0)
; #define PG8_MMA(ai, bj, At, Bt) do { __builtin_amdgcn_s_setprio(1); _Pragma("unroll") for (int m = 0; m < 4; ++m) _Pragma("unroll") for (int n = 0; n < 2; ++n) _Pragma("unroll") for (int k = 0; k < 2; ++k) \
;         acc[ai][bj][m][n] = __builtin_amdgcn_mfma_f32_16x16x32_bf16(Bt[n][k], At[m][k], acc[ai][bj][m][n], 0, 0, 0); __builtin_amdgcn_s_setprio(0); } while (0)
; #define PG8_WAIT_V(n) asm volatile("s_waitcnt vmcnt(" #n ")" ::: "memory")
; #define PG8_WAIT_L(n) asm volatile("s_waitcnt lgkmcnt(" #n ")" ::: "memory")
; #define PG8_BAR __builtin_amdgcn_s_barrier()
; #define PG8_SCHED __builtin_amdgcn_sched_barrier(0)
; template <class Epi, class Sched, bool ALIGN_EPI = false, bool SP2 = false>
; __device__ __forceinline__ void gemm_phase(PG8_LAS unsigned char* lds, const Gemm g, const Sched& S, const Epi& E) {
;     ...
;             PG8_WAIT_V(8); PG8_WAIT_L(0); PG8_BAR; PG8_MMA(1, 0, At, B0); PG8_MMA(1, 1, At, B1); PG8_BAR; PG8_SCHED;
;             PG8_LDB(B0, 1, 0); PG8_LDB(B1, 1, 1); PG8_SCHED; PG8_LDA(At, 1, 0); PG8_STAGE(PG8_SA(0, 1), a2 + hstep, voffA);
;             PG8_WAIT_V(8); PG8_WAIT_L(0); PG8_BAR; PG8_MMA(0, 0, At, B0); PG8_MMA(0, 1, At, B1); PG8_BAR; PG8_SCHED;
	s_setprio 1
	v_mfma_f32_16x16x32_bf16 v[108:111], v[128:131], v[182:185], v[108:111]
	v_mfma_f32_16x16x32_bf16 v[76:79], v[136:139], v[182:185], v[76:79]
	v_mfma_f32_16x16x32_bf16 v[104:107], v[128:131], v[190:193], v[104:107]
	v_mfma_f32_16x16x32_bf16 v[72:75], v[136:139], v[190:193], v[72:75]
	v_mfma_f32_16x16x32_bf16 v[100:103], v[128:131], v[216:219], v[100:103]
	v_mfma_f32_16x16x32_bf16 v[68:71], v[136:139], v[216:219], v[68:71]
	v_mfma_f32_16x16x32_bf16 v[96:99], v[128:131], v[224:227], v[96:99]
	v_mfma_f32_16x16x32_bf16 v[64:67], v[136:139], v[224:227], v[64:67]
	v_mfma_f32_16x16x32_bf16 v[108:111], v[132:135], v[186:189], v[108:111]
	v_mfma_f32_16x16x32_bf16 v[76:79], v[140:143], v[186:189], v[76:79]
	v_mfma_f32_16x16x32_bf16 v[104:107], v[132:135], v[194:197], v[104:107]
	v_mfma_f32_16x16x32_bf16 v[72:75], v[140:143], v[194:197], v[72:75]
	v_mfma_f32_16x16x32_bf16 v[100:103], v[132:135], v[220:223], v[100:103]
	v_mfma_f32_16x16x32_bf16 v[68:71], v[140:143], v[220:223], v[68:71]
	v_mfma_f32_16x16x32_bf16 v[96:99], v[132:135], v[228:231], v[96:99]
	v_mfma_f32_16x16x32_bf16 v[64:67], v[140:143], v[228:231], v[64:67]
	v_mfma_f32_16x16x32_bf16 v[44:47], v[162:165], v[182:185], v[44:47]
	v_mfma_f32_16x16x32_bf16 v[12:15], v[174:177], v[182:185], v[12:15]
	v_mfma_f32_16x16x32_bf16 v[40:43], v[162:165], v[190:193], v[40:43]
	v_mfma_f32_16x16x32_bf16 v[8:11], v[174:177], v[190:193], v[8:11]
	v_mfma_f32_16x16x32_bf16 v[36:39], v[162:165], v[216:219], v[36:39]
	v_mfma_f32_16x16x32_bf16 v[4:7], v[174:177], v[216:219], v[4:7]
	v_mfma_f32_16x16x32_bf16 v[32:35], v[162:165], v[224:227], v[32:35]
	v_mfma_f32_16x16x32_bf16 v[0:3], v[174:177], v[224:227], v[0:3]
	v_mfma_f32_16x16x32_bf16 v[44:47], v[166:169], v[186:189], v[44:47]
	v_mfma_f32_16x16x32_bf16 v[12:15], v[178:181], v[186:189], v[12:15]
	v_mfma_f32_16x16x32_bf16 v[40:43], v[166:169], v[194:197], v[40:43]
	v_mfma_f32_16x16x32_bf16 v[8:11], v[178:181], v[194:197], v[8:11]
	v_mfma_f32_16x16x32_bf16 v[36:39], v[166:169], v[220:223], v[36:39]
	v_mfma_f32_16x16x32_bf16 v[4:7], v[178:181], v[220:223], v[4:7]
	v_mfma_f32_16x16x32_bf16 v[32:35], v[166:169], v[228:231], v[32:35]
	v_mfma_f32_16x16x32_bf16 v[0:3], v[178:181], v[228:231], v[0:3]
	s_setprio 0
	s_barrier
	s_add_i32 s58, 0, 0x18000
	s_add_i32 s60, 0, 0x1c000
	v_add_u32_e32 v140, s58, v171
	v_add_u32_e32 v178, s60, v171
	ds_read_b128 v[128:131], v140
	ds_read_b128 v[132:135], v140 offset:1024
	ds_read_b128 v[136:139], v140 offset:2048
	ds_read_b128 v[140:143], v140 offset:3072
	ds_read_b128 v[162:165], v178
	ds_read_b128 v[166:169], v178 offset:1024
	ds_read_b128 v[174:177], v178 offset:2048
	ds_read_b128 v[178:181], v178 offset:3072
	s_add_u32 s40, s40, 0x40000
	s_addc_u32 s41, s41, 0
	s_mov_b32 m0, s49
	v_lshl_add_u64 v[238:239], s[40:41], 0, v[144:145]
	ds_read_b128 v[182:185], v173 offset:32768
	ds_read_b128 v[186:189], v173 offset:33792
	ds_read_b128 v[190:193], v173 offset:34816
	ds_read_b128 v[194:197], v173 offset:35840
	ds_read_b128 v[216:219], v173 offset:36864
	ds_read_b128 v[220:223], v173 offset:37888
	ds_read_b128 v[224:227], v173 offset:38912
	ds_read_b128 v[228:231], v173 offset:39936
	global_load_lds_dwordx4 v[238:239], off
	v_lshl_add_u64 v[238:239], s[40:41], 0, v[156:157]
	s_mov_b32 m0, s50
	s_nop 0
	global_load_lds_dwordx4 v[238:239], off
	s_waitcnt vmcnt(8)
	s_waitcnt lgkmcnt(0)
	s_barrier
	s_setprio 1
	v_mfma_f32_16x16x32_bf16 v[124:127], v[128:131], v[182:185], v[124:127]
	v_mfma_f32_16x16x32_bf16 v[92:95], v[136:139], v[182:185], v[92:95]
	v_mfma_f32_16x16x32_bf16 v[120:123], v[128:131], v[190:193], v[120:123]
	v_mfma_f32_16x16x32_bf16 v[88:91], v[136:139], v[190:193], v[88:91]
	v_mfma_f32_16x16x32_bf16 v[116:119], v[128:131], v[216:219], v[116:119]
	v_mfma_f32_16x16x32_bf16 v[84:87], v[136:139], v[216:219], v[84:87]
	v_mfma_f32_16x16x32_bf16 v[112:115], v[128:131], v[224:227], v[112:115]
	v_mfma_f32_16x16x32_bf16 v[80:83], v[136:139], v[224:227], v[80:83]
	v_mfma_f32_16x16x32_bf16 v[124:127], v[132:135], v[186:189], v[124:127]
	v_mfma_f32_16x16x32_bf16 v[92:95], v[140:143], v[186:189], v[92:95]
	v_mfma_f32_16x16x32_bf16 v[120:123], v[132:135], v[194:197], v[120:123]
	v_mfma_f32_16x16x32_bf16 v[88:91], v[140:143], v[194:197], v[88:91]
	v_mfma_f32_16x16x32_bf16 v[116:119], v[132:135], v[220:223], v[116:119]
	v_mfma_f32_16x16x32_bf16 v[84:87], v[140:143], v[220:223], v[84:87]
	v_mfma_f32_16x16x32_bf16 v[112:115], v[132:135], v[228:231], v[112:115]
	v_mfma_f32_16x16x32_bf16 v[80:83], v[140:143], v[228:231], v[80:83]
	v_mfma_f32_16x16x32_bf16 v[60:63], v[162:165], v[182:185], v[60:63]
	v_mfma_f32_16x16x32_bf16 v[28:31], v[174:177], v[182:185], v[28:31]
	v_mfma_f32_16x16x32_bf16 v[56:59], v[162:165], v[190:193], v[56:59]
	v_mfma_f32_16x16x32_bf16 v[24:27], v[174:177], v[190:193], v[24:27]
	v_mfma_f32_16x16x32_bf16 v[52:55], v[162:165], v[216:219], v[52:55]
	v_mfma_f32_16x16x32_bf16 v[20:23], v[174:177], v[216:219], v[20:23]
	v_mfma_f32_16x16x32_bf16 v[48:51], v[162:165], v[224:227], v[48:51]
	v_mfma_f32_16x16x32_bf16 v[16:19], v[174:177], v[224:227], v[16:19]
	v_mfma_f32_16x16x32_bf16 v[60:63], v[166:169], v[186:189], v[60:63]
	v_mfma_f32_16x16x32_bf16 v[28:31], v[178:181], v[186:189], v[28:31]
	v_mfma_f32_16x16x32_bf16 v[56:59], v[166:169], v[194:197], v[56:59]
	v_mfma_f32_16x16x32_bf16 v[24:27], v[178:181], v[194:197], v[24:27]
	v_mfma_f32_16x16x32_bf16 v[52:55], v[166:169], v[220:223], v[52:55]
	v_mfma_f32_16x16x32_bf16 v[20:23], v[178:181], v[220:223], v[20:23]
	v_mfma_f32_16x16x32_bf16 v[48:51], v[166:169], v[228:231], v[48:51]
	v_mfma_f32_16x16x32_bf16 v[16:19], v[178:181], v[228:231], v[16:19]
	s_setprio 0
	s_barrier
; #define PG8_STAGE(bufoff, gbase, voff) do { _Pragma("unroll") for (int _i = 0; _i < 2; ++_i) \
;         __builtin_amdgcn_global_load_lds((const unsigned*)((const char*)(gbase) + (voff)[_i]), (PG8_LAS unsigned*)(lds + (bufoff) + ldsw + _i * 8192), 16, 0, 0); } while (0)
; #define PG8_LDA(dst, b, h) do { _Pragma("unroll") for (int m = 0; m < 4; ++m) _Pragma("unroll") for (int k = 0; k < 2; ++k) dst[m][k] = *(const PG8_LAS bf16x8*)(lds + PG8_SA(b, h) + aoff + m * 2048 + k * 1024); } while (0)
; #define PG8_MMA(ai, bj, At, Bt) do { __builtin_amdgcn_s_setprio(1); _Pragma("unroll") for (int m = 0; m < 4; ++m) _Pragma("unroll") for (int n = 0; n < 2; ++n) _Pragma("unroll") for (int k = 0; k < 2; ++k) \
;         acc[ai][bj][m][n] = __builtin_amdgcn_mfma_f32_16x16x32_bf16(Bt[n][k], At[m][k], acc[ai][bj][m][n], 0, 0, 0); __builtin_amdgcn_s_setprio(0); } while (0)
; #define PG8_WAIT_V(n) asm volatile("s_waitcnt vmcnt(" #n ")" ::: "memory")
; #define PG8_WAIT_L(n) asm volatile("s_waitcnt lgkmcnt(" #n ")" ::: "memory")
; #define PG8_BAR __builtin_amdgcn_s_barrier()
; #define PG8_SCHED __builtin_amdgcn_sched_barrier(0)
; template <class Epi, class Sched, bool ALIGN_EPI = false, bool SP2 = false>
; __device__ __forceinline__ void gemm_phase(PG8_LAS unsigned char* lds, const Gemm g, const Sched& S, const Epi& E) {
;     ...
;             PG8_LDA(At, 1, 1); PG8_STAGE(PG8_SB(1, 0), b3, voffB); PG8_STAGE(PG8_SB(1, 1), b3 + hstep, voffB); PG8_STAGE(PG8_SA(1, 0), a3, voffA);
;             PG8_WAIT_V(8); PG8_WAIT_L(0); PG8_BAR; PG8_MMA(1, 0, At, B0); PG8_MMA(1, 1, At, B1); PG8_BAR; PG8_SCHED;
;     ...
;         }
;         if constexpr (ALIGN_EPI) { if (wr == 0) PG8_BAR; }
	s_add_i32 s40, s58, s46
	v_lshl_add_u64 v[198:199], v[198:199], 0, s[2:3]
	s_mov_b32 m0, s40
	ds_read_b128 v[182:185], v173 offset:49152
	ds_read_b128 v[186:189], v173 offset:50176
	ds_read_b128 v[190:193], v173 offset:51200
	ds_read_b128 v[194:197], v173 offset:52224
	ds_read_b128 v[216:219], v173 offset:53248
	ds_read_b128 v[220:223], v173 offset:54272
	ds_read_b128 v[224:227], v173 offset:55296
	ds_read_b128 v[228:231], v173 offset:56320
	global_load_lds_dwordx4 v[198:199], off
	s_add_i32 m0, s40, 0x2000
	s_add_u32 s38, s38, 0x40080
	v_lshl_add_u64 v[198:199], v[232:233], 0, s[2:3]
	s_addc_u32 s39, s39, 0
	s_add_i32 s40, s60, s46
	global_load_lds_dwordx4 v[198:199], off
	v_lshl_add_u64 v[198:199], s[38:39], 0, v[144:145]
	s_mov_b32 m0, s40
	s_nop 0
	global_load_lds_dwordx4 v[198:199], off
	v_lshl_add_u64 v[198:199], s[38:39], 0, v[156:157]
	s_add_i32 m0, s40, 0x2000
	s_nop 0
	global_load_lds_dwordx4 v[198:199], off
	v_lshl_add_u64 v[198:199], v[234:235], 0, s[2:3]
	s_mov_b32 m0, s4
	s_nop 0
	global_load_lds_dwordx4 v[198:199], off
	v_lshl_add_u64 v[198:199], v[236:237], 0, s[2:3]
	s_mov_b32 m0, s51
	s_nop 0
	global_load_lds_dwordx4 v[198:199], off
	s_waitcnt vmcnt(8)
	s_waitcnt lgkmcnt(0)
	s_barrier
	s_setprio 1
	v_mfma_f32_16x16x32_bf16 v[108:111], v[128:131], v[182:185], v[108:111]
	v_mfma_f32_16x16x32_bf16 v[76:79], v[136:139], v[182:185], v[76:79]
	v_mfma_f32_16x16x32_bf16 v[104:107], v[128:131], v[190:193], v[104:107]
	v_mfma_f32_16x16x32_bf16 v[72:75], v[136:139], v[190:193], v[72:75]
	v_mfma_f32_16x16x32_bf16 v[100:103], v[128:131], v[216:219], v[100:103]
	v_mfma_f32_16x16x32_bf16 v[68:71], v[136:139], v[216:219], v[68:71]
	v_mfma_f32_16x16x32_bf16 v[96:99], v[128:131], v[224:227], v[96:99]
	v_mfma_f32_16x16x32_bf16 v[64:67], v[136:139], v[224:227], v[64:67]
	v_mfma_f32_16x16x32_bf16 v[108:111], v[132:135], v[186:189], v[108:111]
	v_mfma_f32_16x16x32_bf16 v[76:79], v[140:143], v[186:189], v[76:79]
	v_mfma_f32_16x16x32_bf16 v[104:107], v[132:135], v[194:197], v[104:107]
	v_mfma_f32_16x16x32_bf16 v[72:75], v[140:143], v[194:197], v[72:75]
	v_mfma_f32_16x16x32_bf16 v[100:103], v[132:135], v[220:223], v[100:103]
	v_mfma_f32_16x16x32_bf16 v[68:71], v[140:143], v[220:223], v[68:71]
	v_mfma_f32_16x16x32_bf16 v[96:99], v[132:135], v[228:231], v[96:99]
	v_mfma_f32_16x16x32_bf16 v[64:67], v[140:143], v[228:231], v[64:67]
	v_mfma_f32_16x16x32_bf16 v[44:47], v[162:165], v[182:185], v[44:47]
	v_mfma_f32_16x16x32_bf16 v[12:15], v[174:177], v[182:185], v[12:15]
	v_mfma_f32_16x16x32_bf16 v[40:43], v[162:165], v[190:193], v[40:43]
	v_mfma_f32_16x16x32_bf16 v[8:11], v[174:177], v[190:193], v[8:11]
	v_mfma_f32_16x16x32_bf16 v[36:39], v[162:165], v[216:219], v[36:39]
	v_mfma_f32_16x16x32_bf16 v[4:7], v[174:177], v[216:219], v[4:7]
	v_mfma_f32_16x16x32_bf16 v[32:35], v[162:165], v[224:227], v[32:35]
	v_mfma_f32_16x16x32_bf16 v[0:3], v[174:177], v[224:227], v[0:3]
	v_mfma_f32_16x16x32_bf16 v[44:47], v[166:169], v[186:189], v[44:47]
	v_mfma_f32_16x16x32_bf16 v[12:15], v[178:181], v[186:189], v[12:15]
	v_mfma_f32_16x16x32_bf16 v[40:43], v[166:169], v[194:197], v[40:43]
	v_mfma_f32_16x16x32_bf16 v[8:11], v[178:181], v[194:197], v[8:11]
	v_mfma_f32_16x16x32_bf16 v[36:39], v[166:169], v[220:223], v[36:39]
	v_mfma_f32_16x16x32_bf16 v[4:7], v[178:181], v[220:223], v[4:7]
	v_mfma_f32_16x16x32_bf16 v[32:35], v[166:169], v[228:231], v[32:35]
	v_mfma_f32_16x16x32_bf16 v[0:3], v[178:181], v[228:231], v[0:3]
	s_setprio 0
	s_barrier
	s_add_i32 s57, s57, 2
	s_add_u32 s28, s28, 0x100
	s_addc_u32 s29, s29, 0
	s_add_u32 s55, s55, 0x100
	s_addc_u32 s56, s56, 0
	s_cmp_gt_u32 s57, 13
	s_cbranch_scc0 .LBB0_426
	s_and_b64 vcc, exec, s[8:9]
	s_cbranch_vccz .LBB0_429
	s_barrier

; #define PG8_STAGE(bufoff, gbase, voff) do { _Pragma("unroll") for (int _i = 0; _i < 2; ++_i) \
;         __builtin_amdgcn_global_load_lds((const unsigned*)((const char*)(gbase) + (voff)[_i]), (PG8_LAS unsigned*)(lds + (bufoff) + ldsw + _i * 8192), 16, 0, 0); } while (0)
; #define PG8_LDA(dst, b, h) do { _Pragma("unroll") for (int m = 0; m < 4; ++m) _Pragma("unroll") for (int k = 0; k < 2; ++k) dst[m][k] = *(const PG8_LAS bf16x8*)(lds + PG8_SA(b, h) + aoff + m * 2048 + k * 1024); } while (0)
; #define PG8_LDB(dst, b, h) do { _Pragma("unroll") for (int n = 0; n < 2; ++n) _Pragma("unroll") for (int k = 0; k < 2; ++k) dst[n][k] = *(const PG8_LAS bf16x8*)(lds + PG8_SB(b, h) + boff + n * 2048 + k * 1024); } while (0)
; #define PG8_MMA(ai, bj, At, Bt) do { __builtin_amdgcn_s_setprio(1); _Pragma("unroll") for (int m = 0; m < 4; ++m) _Pragma("unroll") for (int n = 0; n < 2; ++n) _Pragma("unroll") for (int k = 0; k < 2; ++k) \
;         acc[ai][bj][m][n] = __builtin_amdgcn_mfma_f32_16x16x32_bf16(Bt[n][k], At[m][k], acc[ai][bj][m][n], 0, 0, 0); __builtin_amdgcn_s_setprio(0); } while (0)
; #define PG8_WAIT_V(n) asm volatile("s_waitcnt vmcnt(" #n ")" ::: "memory")
; #define PG8_WAIT_L(n) asm volatile("s_waitcnt lgkmcnt(" #n ")" ::: "memory")
; #define PG8_BAR __builtin_amdgcn_s_barrier()
; #define PG8_SCHED __builtin_amdgcn_sched_barrier(0)
; template <class Epi, class Sched, bool ALIGN_EPI = false, bool SP2 = false>
; __device__ __forceinline__ void gemm_phase(PG8_LAS unsigned char* lds, const Gemm g, const Sched& S, const Epi& E) {
;     ...
;             PG8_LDB(B0, 0, 0); PG8_LDB(B1, 0, 1); PG8_SCHED; PG8_LDA(At, 0, 0); PG8_STAGE(PG8_SA(1, 1), a1 + hstep, voffA);
;             PG8_WAIT_V(8); PG8_WAIT_L(0); PG8_BAR; PG8_MMA(0, 0, At, B0); PG8_MMA(0, 1, At, B1); PG8_BAR; PG8_SCHED;
;             PG8_LDA(At, 0, 1); PG8_STAGE(PG8_SB(0, 0), b2, voffB); PG8_STAGE(PG8_SB(0, 1), b2 + hstep, voffB); PG8_STAGE(PG8_SA(0, 0), a2, voffA);
.LBB0_622:
	s_add_u32 s42, s40, 0xfffc0080
	s_addc_u32 s43, s41, -1
	s_add_i32 s63, 0, 0x10000
	s_cmp_eq_u32 s62, 12
	s_cselect_b32 s45, s4, s43
	s_cselect_b32 s44, s13, s42
	v_add_u32_e32 v144, s63, v168
	s_cselect_b32 s43, s11, s61
	s_cselect_b32 s42, s19, s29
	s_add_i32 s68, 0, 0x14000
	ds_read_b128 v[128:131], v144
	ds_read_b128 v[132:135], v144 offset:1024
	ds_read_b128 v[162:165], v144 offset:2048
	ds_read_b128 v[170:173], v144 offset:3072
	v_add_u32_e32 v144, s68, v168
	ds_read_b128 v[174:177], v144
	ds_read_b128 v[178:181], v144 offset:1024
	ds_read_b128 v[182:185], v144 offset:2048
	ds_read_b128 v[186:189], v144 offset:3072
	v_lshl_add_u64 v[166:167], s[40:41], 0, v[158:159]
	s_add_i32 m0, s50, 0xc000
	ds_read_b128 v[190:193], v169
	ds_read_b128 v[194:197], v169 offset:1024
	ds_read_b128 v[216:219], v169 offset:2048
	ds_read_b128 v[220:223], v169 offset:3072
	ds_read_b128 v[224:227], v169 offset:4096
	ds_read_b128 v[228:231], v169 offset:5120
	ds_read_b128 v[232:235], v169 offset:6144
	ds_read_b128 v[236:239], v169 offset:7168
	global_load_lds_dwordx4 v[166:167], off
	v_lshl_add_u64 v[166:167], s[40:41], 0, v[160:161]
	s_add_i32 m0, s50, 0xe000
	s_nop 0
	global_load_lds_dwordx4 v[166:167], off
	s_waitcnt vmcnt(8)
	s_waitcnt lgkmcnt(0)
	s_barrier
	s_setprio 1
	v_mfma_f32_16x16x32_bf16 v[124:127], v[128:131], v[190:193], v[124:127]
	v_mfma_f32_16x16x32_bf16 v[120:123], v[162:165], v[190:193], v[120:123]
	v_mfma_f32_16x16x32_bf16 v[108:111], v[128:131], v[216:219], v[108:111]
	v_mfma_f32_16x16x32_bf16 v[104:107], v[162:165], v[216:219], v[104:107]
	v_mfma_f32_16x16x32_bf16 v[92:95], v[128:131], v[224:227], v[92:95]
	v_mfma_f32_16x16x32_bf16 v[88:91], v[162:165], v[224:227], v[88:91]
	v_mfma_f32_16x16x32_bf16 v[76:79], v[128:131], v[232:235], v[76:79]
	v_mfma_f32_16x16x32_bf16 v[72:75], v[162:165], v[232:235], v[72:75]
	v_mfma_f32_16x16x32_bf16 v[124:127], v[132:135], v[194:197], v[124:127]
	v_mfma_f32_16x16x32_bf16 v[120:123], v[170:173], v[194:197], v[120:123]
	v_mfma_f32_16x16x32_bf16 v[108:111], v[132:135], v[220:223], v[108:111]
	v_mfma_f32_16x16x32_bf16 v[104:107], v[170:173], v[220:223], v[104:107]
	v_mfma_f32_16x16x32_bf16 v[92:95], v[132:135], v[228:231], v[92:95]
	v_mfma_f32_16x16x32_bf16 v[88:91], v[170:173], v[228:231], v[88:91]
	v_mfma_f32_16x16x32_bf16 v[76:79], v[132:135], v[236:239], v[76:79]
	v_mfma_f32_16x16x32_bf16 v[72:75], v[170:173], v[236:239], v[72:75]
	v_mfma_f32_16x16x32_bf16 v[116:119], v[174:177], v[190:193], v[116:119]
	v_mfma_f32_16x16x32_bf16 v[112:115], v[182:185], v[190:193], v[112:115]
	v_mfma_f32_16x16x32_bf16 v[100:103], v[174:177], v[216:219], v[100:103]
	v_mfma_f32_16x16x32_bf16 v[96:99], v[182:185], v[216:219], v[96:99]
	v_mfma_f32_16x16x32_bf16 v[84:87], v[174:177], v[224:227], v[84:87]
	v_mfma_f32_16x16x32_bf16 v[80:83], v[182:185], v[224:227], v[80:83]
	v_mfma_f32_16x16x32_bf16 v[68:71], v[174:177], v[232:235], v[68:71]
	v_mfma_f32_16x16x32_bf16 v[64:67], v[182:185], v[232:235], v[64:67]
	v_mfma_f32_16x16x32_bf16 v[116:119], v[178:181], v[194:197], v[116:119]
	v_mfma_f32_16x16x32_bf16 v[112:115], v[186:189], v[194:197], v[112:115]
	v_mfma_f32_16x16x32_bf16 v[100:103], v[178:181], v[220:223], v[100:103]
	v_mfma_f32_16x16x32_bf16 v[96:99], v[186:189], v[220:223], v[96:99]
	v_mfma_f32_16x16x32_bf16 v[84:87], v[178:181], v[228:231], v[84:87]
	v_mfma_f32_16x16x32_bf16 v[80:83], v[186:189], v[228:231], v[80:83]
	v_mfma_f32_16x16x32_bf16 v[68:71], v[178:181], v[236:239], v[68:71]
	v_mfma_f32_16x16x32_bf16 v[64:67], v[186:189], v[236:239], v[64:67]
	s_setprio 0
	s_barrier
	s_add_i32 s63, s63, s47
	v_lshl_add_u64 v[166:167], s[42:43], 0, v[138:139]
	s_mov_b32 m0, s63
	ds_read_b128 v[190:193], v169 offset:16384
	ds_read_b128 v[194:197], v169 offset:17408
	ds_read_b128 v[216:219], v169 offset:18432
	ds_read_b128 v[220:223], v169 offset:19456
	ds_read_b128 v[224:227], v169 offset:20480
	ds_read_b128 v[228:231], v169 offset:21504
	ds_read_b128 v[232:235], v169 offset:22528
	ds_read_b128 v[236:239], v169 offset:23552
	global_load_lds_dwordx4 v[166:167], off
	s_add_i32 m0, s63, 0x2000
	s_add_u32 s66, s42, 0x40000
	v_lshl_add_u64 v[198:199], s[42:43], 0, v[142:143]
	s_addc_u32 s67, s43, 0
	s_add_i32 s63, s68, s47
	global_load_lds_dwordx4 v[198:199], off
	v_lshl_add_u64 v[240:241], s[66:67], 0, v[138:139]
	s_mov_b32 m0, s63
	v_lshl_add_u64 v[242:243], s[44:45], 0, v[140:141]
	global_load_lds_dwordx4 v[240:241], off
	v_lshl_add_u64 v[240:241], s[66:67], 0, v[142:143]
	s_add_i32 m0, s63, 0x2000
	s_nop 0
	global_load_lds_dwordx4 v[240:241], off
	v_lshl_add_u64 v[240:241], s[44:45], 0, v[136:137]
	s_mov_b32 m0, s50
	s_nop 0
	global_load_lds_dwordx4 v[240:241], off
	s_mov_b32 m0, s51
	s_nop 0
	global_load_lds_dwordx4 v[242:243], off
	s_waitcnt vmcnt(8)
	s_waitcnt lgkmcnt(0)
	s_barrier
; #define PG8_STAGE(bufoff, gbase, voff) do { _Pragma("unroll") for (int _i = 0; _i < 2; ++_i) \
;         __builtin_amdgcn_global_load_lds((const unsigned*)((const char*)(gbase) + (voff)[_i]), (PG8_LAS unsigned*)(lds + (bufoff) + ldsw + _i * 8192), 16, 0, 0); } while (0)
; #define PG8_LDA(dst, b, h) do { _Pragma("unroll") for (int m = 0; m < 4; ++m) _Pragma("unroll") for (int k = 0; k < 2; ++k) dst[m][k] = *(const PG8_LAS bf16x8*)(lds + PG8_SA(b, h) + aoff + m * 2048 + k * 1024); } while (0)
; #define PG8_LDB(dst, b, h) do { _Pragma("unroll") for (int n = 0; n < 2; ++n) _Pragma("unroll") for (int k = 0; k < 2; ++k) dst[n][k] = *(const PG8_LAS bf16x8*)(lds + PG8_SB(b, h) + boff + n * 2048 + k * 1024); } while (0)
; #define PG8_MMA(ai, bj, At, Bt) do { __builtin_amdgcn_s_setprio(1); _Pragma("unroll") for (int m = 0; m < 4; ++m) _Pragma("unroll") for (int n = 0; n < 2; ++n) _Pragma("unroll") for (int k = 0; k < 2; ++k) \
;         acc[ai][bj][m][n] = __builtin_amdgcn_mfma_f32_16x16x32_bf16(Bt[n][k], At[m][k], acc[ai][bj][m][n], 0, 0, 0); __builtin_amdgcn_s_setprio(0); } while (0)
; #define PG8_WAIT_V(n) asm volatile("s_waitcnt vmcnt(" #n ")" ::: "memory")
; #define PG8_WAIT_L(n) asm volatile("s_waitcnt lgkmcnt(" #n ")" ::: "memory")
; #define PG8_BAR __builtin_amdgcn_s_barrier()
; #define PG8_SCHED __builtin_amdgcn_sched_barrier(0)
; template <class Epi, class Sched, bool ALIGN_EPI = false, bool SP2 = false>
; __device__ __forceinline__ void gemm_phase(PG8_LAS unsigned char* lds, const Gemm g, const Sched& S, const Epi& E) {
;     ...
;             PG8_WAIT_V(8); PG8_WAIT_L(0); PG8_BAR; PG8_MMA(1, 0, At, B0); PG8_MMA(1, 1, At, B1); PG8_BAR; PG8_SCHED;
;             PG8_LDB(B0, 1, 0); PG8_LDB(B1, 1, 1); PG8_SCHED; PG8_LDA(At, 1, 0); PG8_STAGE(PG8_SA(0, 1), a2 + hstep, voffA);
;             PG8_WAIT_V(8); PG8_WAIT_L(0); PG8_BAR; PG8_MMA(0, 0, At, B0); PG8_MMA(0, 1, At, B1); PG8_BAR; PG8_SCHED;
	s_setprio 1
	v_mfma_f32_16x16x32_bf16 v[60:63], v[128:131], v[190:193], v[60:63]
	v_mfma_f32_16x16x32_bf16 v[56:59], v[162:165], v[190:193], v[56:59]
	v_mfma_f32_16x16x32_bf16 v[44:47], v[128:131], v[216:219], v[44:47]
	v_mfma_f32_16x16x32_bf16 v[40:43], v[162:165], v[216:219], v[40:43]
	v_mfma_f32_16x16x32_bf16 v[28:31], v[128:131], v[224:227], v[28:31]
	v_mfma_f32_16x16x32_bf16 v[24:27], v[162:165], v[224:227], v[24:27]
	v_mfma_f32_16x16x32_bf16 v[12:15], v[128:131], v[232:235], v[12:15]
	v_mfma_f32_16x16x32_bf16 v[8:11], v[162:165], v[232:235], v[8:11]
	v_mfma_f32_16x16x32_bf16 v[60:63], v[132:135], v[194:197], v[60:63]
	v_mfma_f32_16x16x32_bf16 v[56:59], v[170:173], v[194:197], v[56:59]
	v_mfma_f32_16x16x32_bf16 v[44:47], v[132:135], v[220:223], v[44:47]
	v_mfma_f32_16x16x32_bf16 v[40:43], v[170:173], v[220:223], v[40:43]
	v_mfma_f32_16x16x32_bf16 v[28:31], v[132:135], v[228:231], v[28:31]
	v_mfma_f32_16x16x32_bf16 v[24:27], v[170:173], v[228:231], v[24:27]
	v_mfma_f32_16x16x32_bf16 v[12:15], v[132:135], v[236:239], v[12:15]
	v_mfma_f32_16x16x32_bf16 v[8:11], v[170:173], v[236:239], v[8:11]
	v_mfma_f32_16x16x32_bf16 v[52:55], v[174:177], v[190:193], v[52:55]
	v_mfma_f32_16x16x32_bf16 v[48:51], v[182:185], v[190:193], v[48:51]
	v_mfma_f32_16x16x32_bf16 v[36:39], v[174:177], v[216:219], v[36:39]
	v_mfma_f32_16x16x32_bf16 v[32:35], v[182:185], v[216:219], v[32:35]
	v_mfma_f32_16x16x32_bf16 v[20:23], v[174:177], v[224:227], v[20:23]
	v_mfma_f32_16x16x32_bf16 v[16:19], v[182:185], v[224:227], v[16:19]
	v_mfma_f32_16x16x32_bf16 v[4:7], v[174:177], v[232:235], v[4:7]
	v_mfma_f32_16x16x32_bf16 v[0:3], v[182:185], v[232:235], v[0:3]
	v_mfma_f32_16x16x32_bf16 v[52:55], v[178:181], v[194:197], v[52:55]
	v_mfma_f32_16x16x32_bf16 v[48:51], v[186:189], v[194:197], v[48:51]
	v_mfma_f32_16x16x32_bf16 v[36:39], v[178:181], v[220:223], v[36:39]
	v_mfma_f32_16x16x32_bf16 v[32:35], v[186:189], v[220:223], v[32:35]
	v_mfma_f32_16x16x32_bf16 v[20:23], v[178:181], v[228:231], v[20:23]
	v_mfma_f32_16x16x32_bf16 v[16:19], v[186:189], v[228:231], v[16:19]
	v_mfma_f32_16x16x32_bf16 v[4:7], v[178:181], v[236:239], v[4:7]
	v_mfma_f32_16x16x32_bf16 v[0:3], v[186:189], v[236:239], v[0:3]
	s_setprio 0
	s_barrier
	s_add_i32 s63, 0, 0x18000
	v_add_u32_e32 v144, s63, v168
	s_add_i32 s66, 0, 0x1c000
	ds_read_b128 v[128:131], v144
	ds_read_b128 v[132:135], v144 offset:1024
	ds_read_b128 v[162:165], v144 offset:2048
	ds_read_b128 v[170:173], v144 offset:3072
	v_add_u32_e32 v144, s66, v168
	ds_read_b128 v[174:177], v144
	ds_read_b128 v[178:181], v144 offset:1024
	ds_read_b128 v[182:185], v144 offset:2048
	ds_read_b128 v[186:189], v144 offset:3072
	s_add_u32 s44, s44, 0x40000
	s_addc_u32 s45, s45, 0
	s_mov_b32 m0, s52
	v_lshl_add_u64 v[244:245], s[44:45], 0, v[136:137]
	ds_read_b128 v[190:193], v169 offset:32768
	ds_read_b128 v[194:197], v169 offset:33792
	ds_read_b128 v[216:219], v169 offset:34816
	ds_read_b128 v[220:223], v169 offset:35840
	ds_read_b128 v[224:227], v169 offset:36864
	ds_read_b128 v[228:231], v169 offset:37888
	ds_read_b128 v[232:235], v169 offset:38912
	ds_read_b128 v[236:239], v169 offset:39936
	global_load_lds_dwordx4 v[244:245], off
	v_lshl_add_u64 v[244:245], s[44:45], 0, v[140:141]
	s_mov_b32 m0, s53
	s_nop 0
	global_load_lds_dwordx4 v[244:245], off
	s_waitcnt vmcnt(8)
	s_waitcnt lgkmcnt(0)
	s_barrier
	s_setprio 1
	v_mfma_f32_16x16x32_bf16 v[124:127], v[128:131], v[190:193], v[124:127]
	v_mfma_f32_16x16x32_bf16 v[120:123], v[162:165], v[190:193], v[120:123]
	v_mfma_f32_16x16x32_bf16 v[108:111], v[128:131], v[216:219], v[108:111]
	v_mfma_f32_16x16x32_bf16 v[104:107], v[162:165], v[216:219], v[104:107]
	v_mfma_f32_16x16x32_bf16 v[92:95], v[128:131], v[224:227], v[92:95]
	v_mfma_f32_16x16x32_bf16 v[88:91], v[162:165], v[224:227], v[88:91]
	v_mfma_f32_16x16x32_bf16 v[76:79], v[128:131], v[232:235], v[76:79]
	v_mfma_f32_16x16x32_bf16 v[72:75], v[162:165], v[232:235], v[72:75]
	v_mfma_f32_16x16x32_bf16 v[124:127], v[132:135], v[194:197], v[124:127]
	v_mfma_f32_16x16x32_bf16 v[120:123], v[170:173], v[194:197], v[120:123]
	v_mfma_f32_16x16x32_bf16 v[108:111], v[132:135], v[220:223], v[108:111]
	v_mfma_f32_16x16x32_bf16 v[104:107], v[170:173], v[220:223], v[104:107]
	v_mfma_f32_16x16x32_bf16 v[92:95], v[132:135], v[228:231], v[92:95]
	v_mfma_f32_16x16x32_bf16 v[88:91], v[170:173], v[228:231], v[88:91]
	v_mfma_f32_16x16x32_bf16 v[76:79], v[132:135], v[236:239], v[76:79]
	v_mfma_f32_16x16x32_bf16 v[72:75], v[170:173], v[236:239], v[72:75]
	v_mfma_f32_16x16x32_bf16 v[116:119], v[174:177], v[190:193], v[116:119]
	v_mfma_f32_16x16x32_bf16 v[112:115], v[182:185], v[190:193], v[112:115]
	v_mfma_f32_16x16x32_bf16 v[100:103], v[174:177], v[216:219], v[100:103]
	v_mfma_f32_16x16x32_bf16 v[96:99], v[182:185], v[216:219], v[96:99]
	v_mfma_f32_16x16x32_bf16 v[84:87], v[174:177], v[224:227], v[84:87]
	v_mfma_f32_16x16x32_bf16 v[80:83], v[182:185], v[224:227], v[80:83]
	v_mfma_f32_16x16x32_bf16 v[68:71], v[174:177], v[232:235], v[68:71]
	v_mfma_f32_16x16x32_bf16 v[64:67], v[182:185], v[232:235], v[64:67]
	v_mfma_f32_16x16x32_bf16 v[116:119], v[178:181], v[194:197], v[116:119]
	v_mfma_f32_16x16x32_bf16 v[112:115], v[186:189], v[194:197], v[112:115]
	v_mfma_f32_16x16x32_bf16 v[100:103], v[178:181], v[220:223], v[100:103]
	v_mfma_f32_16x16x32_bf16 v[96:99], v[186:189], v[220:223], v[96:99]
	v_mfma_f32_16x16x32_bf16 v[84:87], v[178:181], v[228:231], v[84:87]
	v_mfma_f32_16x16x32_bf16 v[80:83], v[186:189], v[228:231], v[80:83]
	v_mfma_f32_16x16x32_bf16 v[68:71], v[178:181], v[236:239], v[68:71]
	v_mfma_f32_16x16x32_bf16 v[64:67], v[186:189], v[236:239], v[64:67]
	s_setprio 0
	s_barrier
; #define PG8_STAGE(bufoff, gbase, voff) do { _Pragma("unroll") for (int _i = 0; _i < 2; ++_i) \
;         __builtin_amdgcn_global_load_lds((const unsigned*)((const char*)(gbase) + (voff)[_i]), (PG8_LAS unsigned*)(lds + (bufoff) + ldsw + _i * 8192), 16, 0, 0); } while (0)
; #define PG8_LDA(dst, b, h) do { _Pragma("unroll") for (int m = 0; m < 4; ++m) _Pragma("unroll") for (int k = 0; k < 2; ++k) dst[m][k] = *(const PG8_LAS bf16x8*)(lds + PG8_SA(b, h) + aoff + m * 2048 + k * 1024); } while (0)
; #define PG8_MMA(ai, bj, At, Bt) do { __builtin_amdgcn_s_setprio(1); _Pragma("unroll") for (int m = 0; m < 4; ++m) _Pragma("unroll") for (int n = 0; n < 2; ++n) _Pragma("unroll") for (int k = 0; k < 2; ++k) \
;         acc[ai][bj][m][n] = __builtin_amdgcn_mfma_f32_16x16x32_bf16(Bt[n][k], At[m][k], acc[ai][bj][m][n], 0, 0, 0); __builtin_amdgcn_s_setprio(0); } while (0)
; #define PG8_WAIT_V(n) asm volatile("s_waitcnt vmcnt(" #n ")" ::: "memory")
; #define PG8_WAIT_L(n) asm volatile("s_waitcnt lgkmcnt(" #n ")" ::: "memory")
; #define PG8_BAR __builtin_amdgcn_s_barrier()
; #define PG8_SCHED __builtin_amdgcn_sched_barrier(0)
; template <class Epi, class Sched, bool ALIGN_EPI = false, bool SP2 = false>
; __device__ __forceinline__ void gemm_phase(PG8_LAS unsigned char* lds, const Gemm g, const Sched& S, const Epi& E) {
;     ...
;             PG8_LDA(At, 1, 1); PG8_STAGE(PG8_SB(1, 0), b3, voffB); PG8_STAGE(PG8_SB(1, 1), b3 + hstep, voffB); PG8_STAGE(PG8_SA(1, 0), a3, voffA);
;             PG8_WAIT_V(8); PG8_WAIT_L(0); PG8_BAR; PG8_MMA(1, 0, At, B0); PG8_MMA(1, 1, At, B1); PG8_BAR; PG8_SCHED;
;     ...
;         }
;         if constexpr (ALIGN_EPI) { if (wr == 0) PG8_BAR; }
	s_add_i32 s44, s63, s47
	v_lshl_add_u64 v[166:167], v[166:167], 0, s[2:3]
	s_mov_b32 m0, s44
	ds_read_b128 v[190:193], v169 offset:49152
	ds_read_b128 v[194:197], v169 offset:50176
	ds_read_b128 v[216:219], v169 offset:51200
	ds_read_b128 v[220:223], v169 offset:52224
	ds_read_b128 v[224:227], v169 offset:53248
	ds_read_b128 v[228:231], v169 offset:54272
	ds_read_b128 v[232:235], v169 offset:55296
	ds_read_b128 v[236:239], v169 offset:56320
	global_load_lds_dwordx4 v[166:167], off
	s_add_i32 m0, s44, 0x2000
	s_add_u32 s42, s42, 0x40080
	v_lshl_add_u64 v[166:167], v[198:199], 0, s[2:3]
	s_addc_u32 s43, s43, 0
	s_add_i32 s44, s66, s47
	global_load_lds_dwordx4 v[166:167], off
	v_lshl_add_u64 v[166:167], s[42:43], 0, v[138:139]
	s_mov_b32 m0, s44
	s_nop 0
	global_load_lds_dwordx4 v[166:167], off
	v_lshl_add_u64 v[166:167], s[42:43], 0, v[142:143]
	s_add_i32 m0, s44, 0x2000
	s_nop 0
	global_load_lds_dwordx4 v[166:167], off
	v_lshl_add_u64 v[166:167], v[240:241], 0, s[2:3]
	s_mov_b32 m0, s56
	s_nop 0
	global_load_lds_dwordx4 v[166:167], off
	v_lshl_add_u64 v[166:167], v[242:243], 0, s[2:3]
	s_mov_b32 m0, s57
	s_nop 0
	global_load_lds_dwordx4 v[166:167], off
	s_waitcnt vmcnt(8)
	s_waitcnt lgkmcnt(0)
	s_barrier
	s_setprio 1
	v_mfma_f32_16x16x32_bf16 v[60:63], v[128:131], v[190:193], v[60:63]
	v_mfma_f32_16x16x32_bf16 v[56:59], v[162:165], v[190:193], v[56:59]
	v_mfma_f32_16x16x32_bf16 v[44:47], v[128:131], v[216:219], v[44:47]
	v_mfma_f32_16x16x32_bf16 v[40:43], v[162:165], v[216:219], v[40:43]
	v_mfma_f32_16x16x32_bf16 v[28:31], v[128:131], v[224:227], v[28:31]
	v_mfma_f32_16x16x32_bf16 v[24:27], v[162:165], v[224:227], v[24:27]
	v_mfma_f32_16x16x32_bf16 v[12:15], v[128:131], v[232:235], v[12:15]
	v_mfma_f32_16x16x32_bf16 v[8:11], v[162:165], v[232:235], v[8:11]
	v_mfma_f32_16x16x32_bf16 v[60:63], v[132:135], v[194:197], v[60:63]
	v_mfma_f32_16x16x32_bf16 v[56:59], v[170:173], v[194:197], v[56:59]
	v_mfma_f32_16x16x32_bf16 v[44:47], v[132:135], v[220:223], v[44:47]
	v_mfma_f32_16x16x32_bf16 v[40:43], v[170:173], v[220:223], v[40:43]
	v_mfma_f32_16x16x32_bf16 v[28:31], v[132:135], v[228:231], v[28:31]
	v_mfma_f32_16x16x32_bf16 v[24:27], v[170:173], v[228:231], v[24:27]
	v_mfma_f32_16x16x32_bf16 v[12:15], v[132:135], v[236:239], v[12:15]
	v_mfma_f32_16x16x32_bf16 v[8:11], v[170:173], v[236:239], v[8:11]
	v_mfma_f32_16x16x32_bf16 v[52:55], v[174:177], v[190:193], v[52:55]
	v_mfma_f32_16x16x32_bf16 v[48:51], v[182:185], v[190:193], v[48:51]
	v_mfma_f32_16x16x32_bf16 v[36:39], v[174:177], v[216:219], v[36:39]
	v_mfma_f32_16x16x32_bf16 v[32:35], v[182:185], v[216:219], v[32:35]
	v_mfma_f32_16x16x32_bf16 v[20:23], v[174:177], v[224:227], v[20:23]
	v_mfma_f32_16x16x32_bf16 v[16:19], v[182:185], v[224:227], v[16:19]
	v_mfma_f32_16x16x32_bf16 v[4:7], v[174:177], v[232:235], v[4:7]
	v_mfma_f32_16x16x32_bf16 v[0:3], v[182:185], v[232:235], v[0:3]
	v_mfma_f32_16x16x32_bf16 v[52:55], v[178:181], v[194:197], v[52:55]
	v_mfma_f32_16x16x32_bf16 v[48:51], v[186:189], v[194:197], v[48:51]
	v_mfma_f32_16x16x32_bf16 v[36:39], v[178:181], v[220:223], v[36:39]
	v_mfma_f32_16x16x32_bf16 v[32:35], v[186:189], v[220:223], v[32:35]
	v_mfma_f32_16x16x32_bf16 v[20:23], v[178:181], v[228:231], v[20:23]
	v_mfma_f32_16x16x32_bf16 v[16:19], v[186:189], v[228:231], v[16:19]
	v_mfma_f32_16x16x32_bf16 v[4:7], v[178:181], v[236:239], v[4:7]
	v_mfma_f32_16x16x32_bf16 v[0:3], v[186:189], v[236:239], v[0:3]
	s_setprio 0
	s_barrier
	s_add_i32 s62, s62, 2
	s_add_u32 s40, s40, 0x100
	s_addc_u32 s41, s41, 0
	s_add_u32 s29, s29, 0x100
	s_addc_u32 s61, s61, 0
	s_cmp_gt_u32 s62, 13
	s_cbranch_scc0 .LBB0_622
	s_and_b64 vcc, exec, s[8:9]
	s_cbranch_vccz .LBB0_625
	s_barrier

; #define PG8_STAGE(bufoff, gbase, voff) do { _Pragma("unroll") for (int _i = 0; _i < 2; ++_i) \
;         __builtin_amdgcn_global_load_lds((const unsigned*)((const char*)(gbase) + (voff)[_i]), (PG8_LAS unsigned*)(lds + (bufoff) + ldsw + _i * 8192), 16, 0, 0); } while (0)
; #define PG8_LDA(dst, b, h) do { _Pragma("unroll") for (int m = 0; m < 4; ++m) _Pragma("unroll") for (int k = 0; k < 2; ++k) dst[m][k] = *(const PG8_LAS bf16x8*)(lds + PG8_SA(b, h) + aoff + m * 2048 + k * 1024); } while (0)
; #define PG8_LDB(dst, b, h) do { _Pragma("unroll") for (int n = 0; n < 2; ++n) _Pragma("unroll") for (int k = 0; k < 2; ++k) dst[n][k] = *(const PG8_LAS bf16x8*)(lds + PG8_SB(b, h) + boff + n * 2048 + k * 1024); } while (0)
; #define PG8_MMA(ai, bj, At, Bt) do { __builtin_amdgcn_s_setprio(1); _Pragma("unroll") for (int m = 0; m < 4; ++m) _Pragma("unroll") for (int n = 0; n < 2; ++n) _Pragma("unroll") for (int k = 0; k < 2; ++k) \
;         acc[ai][bj][m][n] = __builtin_amdgcn_mfma_f32_16x16x32_bf16(Bt[n][k], At[m][k], acc[ai][bj][m][n], 0, 0, 0); __builtin_amdgcn_s_setprio(0); } while (0)
; #define PG8_WAIT_V(n) asm volatile("s_waitcnt vmcnt(" #n ")" ::: "memory")
; #define PG8_WAIT_L(n) asm volatile("s_waitcnt lgkmcnt(" #n ")" ::: "memory")
; #define PG8_BAR __builtin_amdgcn_s_barrier()
; #define PG8_SCHED __builtin_amdgcn_sched_barrier(0)
; template <class Epi, class Sched, bool ALIGN_EPI = false, bool SP2 = false>
; __device__ __forceinline__ void gemm_phase(PG8_LAS unsigned char* lds, const Gemm g, const Sched& S, const Epi& E) {
;     ...
;             PG8_LDB(B0, 0, 0); PG8_LDB(B1, 0, 1); PG8_SCHED; PG8_LDA(At, 0, 0); PG8_STAGE(PG8_SA(1, 1), a1 + hstep, voffA);
;             PG8_WAIT_V(8); PG8_WAIT_L(0); PG8_BAR; PG8_MMA(0, 0, At, B0); PG8_MMA(0, 1, At, B1); PG8_BAR; PG8_SCHED;
;             PG8_LDA(At, 0, 1); PG8_STAGE(PG8_SB(0, 0), b2, voffB); PG8_STAGE(PG8_SB(0, 1), b2 + hstep, voffB); PG8_STAGE(PG8_SA(0, 0), a2, voffA);
;             PG8_WAIT_V(8); PG8_WAIT_L(0); PG8_BAR; PG8_MMA(1, 0, At, B0); PG8_MMA(1, 1, At, B1); PG8_BAR; PG8_SCHED;
.LBB0_711:
	s_add_u32 s28, s18, 0xfffc0080
	s_addc_u32 s29, s19, -1
	s_add_i32 s57, 0, 0x10000
	s_cmp_eq_u32 s56, 12
	s_cselect_b32 s39, s11, s29
	s_cselect_b32 s38, s52, s28
	v_add_u32_e32 v142, s57, v159
	s_cselect_b32 s29, s9, s55
	s_cselect_b32 s28, s53, s54
	s_add_i32 s60, 0, 0x14000
	ds_read_b128 v[164:167], v142
	ds_read_b128 v[168:171], v142 offset:1024
	ds_read_b128 v[172:175], v142 offset:2048
	ds_read_b128 v[176:179], v142 offset:3072
	v_add_u32_e32 v142, s60, v159
	ds_read_b128 v[180:183], v142
	ds_read_b128 v[184:187], v142 offset:1024
	ds_read_b128 v[188:191], v142 offset:2048
	ds_read_b128 v[192:195], v142 offset:3072
	s_add_i32 m0, s45, 0xc000
	ds_read_b128 v[196:199], v163
	ds_read_b128 v[216:219], v163 offset:1024
	ds_read_b128 v[220:223], v163 offset:2048
	ds_read_b128 v[224:227], v163 offset:3072
	ds_read_b128 v[228:231], v163 offset:4096
	ds_read_b128 v[232:235], v163 offset:5120
	ds_read_b128 v[236:239], v163 offset:6144
	ds_read_b128 v[240:243], v163 offset:7168
	global_load_lds_dwordx4 v138, s[18:19]
	s_add_i32 m0, s45, 0xe000
	s_nop 0
	global_load_lds_dwordx4 v140, s[18:19]
	s_waitcnt vmcnt(8)
	s_waitcnt lgkmcnt(0)
	s_barrier
	s_setprio 1
	v_mfma_f32_16x16x32_bf16 v[116:119], v[164:167], v[196:199], v[116:119]
	v_mfma_f32_16x16x32_bf16 v[112:115], v[172:175], v[196:199], v[112:115]
	v_mfma_f32_16x16x32_bf16 v[100:103], v[164:167], v[220:223], v[100:103]
	v_mfma_f32_16x16x32_bf16 v[96:99], v[172:175], v[220:223], v[96:99]
	v_mfma_f32_16x16x32_bf16 v[84:87], v[164:167], v[228:231], v[84:87]
	v_mfma_f32_16x16x32_bf16 v[80:83], v[172:175], v[228:231], v[80:83]
	v_mfma_f32_16x16x32_bf16 v[68:71], v[164:167], v[236:239], v[68:71]
	v_mfma_f32_16x16x32_bf16 v[64:67], v[172:175], v[236:239], v[64:67]
	v_mfma_f32_16x16x32_bf16 v[116:119], v[168:171], v[216:219], v[116:119]
	v_mfma_f32_16x16x32_bf16 v[112:115], v[176:179], v[216:219], v[112:115]
	v_mfma_f32_16x16x32_bf16 v[100:103], v[168:171], v[224:227], v[100:103]
	v_mfma_f32_16x16x32_bf16 v[96:99], v[176:179], v[224:227], v[96:99]
	v_mfma_f32_16x16x32_bf16 v[84:87], v[168:171], v[232:235], v[84:87]
	v_mfma_f32_16x16x32_bf16 v[80:83], v[176:179], v[232:235], v[80:83]
	v_mfma_f32_16x16x32_bf16 v[68:71], v[168:171], v[240:243], v[68:71]
	v_mfma_f32_16x16x32_bf16 v[64:67], v[176:179], v[240:243], v[64:67]
	v_mfma_f32_16x16x32_bf16 v[124:127], v[180:183], v[196:199], v[124:127]
	v_mfma_f32_16x16x32_bf16 v[120:123], v[188:191], v[196:199], v[120:123]
	v_mfma_f32_16x16x32_bf16 v[108:111], v[180:183], v[220:223], v[108:111]
	v_mfma_f32_16x16x32_bf16 v[104:107], v[188:191], v[220:223], v[104:107]
	v_mfma_f32_16x16x32_bf16 v[92:95], v[180:183], v[228:231], v[92:95]
	v_mfma_f32_16x16x32_bf16 v[88:91], v[188:191], v[228:231], v[88:91]
	v_mfma_f32_16x16x32_bf16 v[76:79], v[180:183], v[236:239], v[76:79]
	v_mfma_f32_16x16x32_bf16 v[72:75], v[188:191], v[236:239], v[72:75]
	v_mfma_f32_16x16x32_bf16 v[124:127], v[184:187], v[216:219], v[124:127]
	v_mfma_f32_16x16x32_bf16 v[120:123], v[192:195], v[216:219], v[120:123]
	v_mfma_f32_16x16x32_bf16 v[108:111], v[184:187], v[224:227], v[108:111]
	v_mfma_f32_16x16x32_bf16 v[104:107], v[192:195], v[224:227], v[104:107]
	v_mfma_f32_16x16x32_bf16 v[92:95], v[184:187], v[232:235], v[92:95]
	v_mfma_f32_16x16x32_bf16 v[88:91], v[192:195], v[232:235], v[88:91]
	v_mfma_f32_16x16x32_bf16 v[76:79], v[184:187], v[240:243], v[76:79]
	v_mfma_f32_16x16x32_bf16 v[72:75], v[192:195], v[240:243], v[72:75]
	s_setprio 0
	s_barrier
	s_add_i32 s57, s57, s41
	s_mov_b32 m0, s57
	ds_read_b128 v[196:199], v163 offset:16384
	ds_read_b128 v[216:219], v163 offset:17408
	ds_read_b128 v[220:223], v163 offset:18432
	ds_read_b128 v[224:227], v163 offset:19456
	ds_read_b128 v[228:231], v163 offset:20480
	ds_read_b128 v[232:235], v163 offset:21504
	ds_read_b128 v[236:239], v163 offset:22528
	ds_read_b128 v[240:243], v163 offset:23552
	global_load_lds_dwordx4 v132, s[28:29]
	s_add_i32 m0, s57, 0x2000
	s_add_u32 s58, s28, 0x40000
	s_addc_u32 s59, s29, 0
	s_add_i32 s57, s60, s41
	global_load_lds_dwordx4 v128, s[28:29]
	s_mov_b32 m0, s57
	s_nop 0
	global_load_lds_dwordx4 v132, s[58:59]
	s_add_i32 m0, s57, 0x2000
	s_nop 0
	global_load_lds_dwordx4 v128, s[58:59]
	s_mov_b32 m0, s45
	s_nop 0
	global_load_lds_dwordx4 v134, s[38:39]
	s_mov_b32 m0, s46
	s_nop 0
	global_load_lds_dwordx4 v130, s[38:39]
	s_waitcnt vmcnt(8)
	s_waitcnt lgkmcnt(0)
	s_barrier
	s_setprio 1
	v_mfma_f32_16x16x32_bf16 v[52:55], v[164:167], v[196:199], v[52:55]
	v_mfma_f32_16x16x32_bf16 v[48:51], v[172:175], v[196:199], v[48:51]
	v_mfma_f32_16x16x32_bf16 v[36:39], v[164:167], v[220:223], v[36:39]
	v_mfma_f32_16x16x32_bf16 v[32:35], v[172:175], v[220:223], v[32:35]
	v_mfma_f32_16x16x32_bf16 v[20:23], v[164:167], v[228:231], v[20:23]
	v_mfma_f32_16x16x32_bf16 v[16:19], v[172:175], v[228:231], v[16:19]
	v_mfma_f32_16x16x32_bf16 v[4:7], v[164:167], v[236:239], v[4:7]
	v_mfma_f32_16x16x32_bf16 v[0:3], v[172:175], v[236:239], v[0:3]
	v_mfma_f32_16x16x32_bf16 v[52:55], v[168:171], v[216:219], v[52:55]
	v_mfma_f32_16x16x32_bf16 v[48:51], v[176:179], v[216:219], v[48:51]
	v_mfma_f32_16x16x32_bf16 v[36:39], v[168:171], v[224:227], v[36:39]
	v_mfma_f32_16x16x32_bf16 v[32:35], v[176:179], v[224:227], v[32:35]
	v_mfma_f32_16x16x32_bf16 v[20:23], v[168:171], v[232:235], v[20:23]
	v_mfma_f32_16x16x32_bf16 v[16:19], v[176:179], v[232:235], v[16:19]
	v_mfma_f32_16x16x32_bf16 v[4:7], v[168:171], v[240:243], v[4:7]
	v_mfma_f32_16x16x32_bf16 v[0:3], v[176:179], v[240:243], v[0:3]
	v_mfma_f32_16x16x32_bf16 v[60:63], v[180:183], v[196:199], v[60:63]
	v_mfma_f32_16x16x32_bf16 v[56:59], v[188:191], v[196:199], v[56:59]
	v_mfma_f32_16x16x32_bf16 v[44:47], v[180:183], v[220:223], v[44:47]
	v_mfma_f32_16x16x32_bf16 v[40:43], v[188:191], v[220:223], v[40:43]
	v_mfma_f32_16x16x32_bf16 v[28:31], v[180:183], v[228:231], v[28:31]
	v_mfma_f32_16x16x32_bf16 v[24:27], v[188:191], v[228:231], v[24:27]
	v_mfma_f32_16x16x32_bf16 v[12:15], v[180:183], v[236:239], v[12:15]
	v_mfma_f32_16x16x32_bf16 v[8:11], v[188:191], v[236:239], v[8:11]
	v_mfma_f32_16x16x32_bf16 v[60:63], v[184:187], v[216:219], v[60:63]
	v_mfma_f32_16x16x32_bf16 v[56:59], v[192:195], v[216:219], v[56:59]
	v_mfma_f32_16x16x32_bf16 v[44:47], v[184:187], v[224:227], v[44:47]
	v_mfma_f32_16x16x32_bf16 v[40:43], v[192:195], v[224:227], v[40:43]
	v_mfma_f32_16x16x32_bf16 v[28:31], v[184:187], v[232:235], v[28:31]
	v_mfma_f32_16x16x32_bf16 v[24:27], v[192:195], v[232:235], v[24:27]
	v_mfma_f32_16x16x32_bf16 v[12:15], v[184:187], v[240:243], v[12:15]
	v_mfma_f32_16x16x32_bf16 v[8:11], v[192:195], v[240:243], v[8:11]
	s_setprio 0
	s_barrier
; #define PG8_STAGE(bufoff, gbase, voff) do { _Pragma("unroll") for (int _i = 0; _i < 2; ++_i) \
;         __builtin_amdgcn_global_load_lds((const unsigned*)((const char*)(gbase) + (voff)[_i]), (PG8_LAS unsigned*)(lds + (bufoff) + ldsw + _i * 8192), 16, 0, 0); } while (0)
; #define PG8_LDA(dst, b, h) do { _Pragma("unroll") for (int m = 0; m < 4; ++m) _Pragma("unroll") for (int k = 0; k < 2; ++k) dst[m][k] = *(const PG8_LAS bf16x8*)(lds + PG8_SA(b, h) + aoff + m * 2048 + k * 1024); } while (0)
; #define PG8_LDB(dst, b, h) do { _Pragma("unroll") for (int n = 0; n < 2; ++n) _Pragma("unroll") for (int k = 0; k < 2; ++k) dst[n][k] = *(const PG8_LAS bf16x8*)(lds + PG8_SB(b, h) + boff + n * 2048 + k * 1024); } while (0)
; #define PG8_MMA(ai, bj, At, Bt) do { __builtin_amdgcn_s_setprio(1); _Pragma("unroll") for (int m = 0; m < 4; ++m) _Pragma("unroll") for (int n = 0; n < 2; ++n) _Pragma("unroll") for (int k = 0; k < 2; ++k) \
;         acc[ai][bj][m][n] = __builtin_amdgcn_mfma_f32_16x16x32_bf16(Bt[n][k], At[m][k], acc[ai][bj][m][n], 0, 0, 0); __builtin_amdgcn_s_setprio(0); } while (0)
; #define PG8_WAIT_V(n) asm volatile("s_waitcnt vmcnt(" #n ")" ::: "memory")
; #define PG8_WAIT_L(n) asm volatile("s_waitcnt lgkmcnt(" #n ")" ::: "memory")
; #define PG8_BAR __builtin_amdgcn_s_barrier()
; #define PG8_SCHED __builtin_amdgcn_sched_barrier(0)
; template <class Epi, class Sched, bool ALIGN_EPI = false, bool SP2 = false>
; __device__ __forceinline__ void gemm_phase(PG8_LAS unsigned char* lds, const Gemm g, const Sched& S, const Epi& E) {
;     ...
;             PG8_LDB(B0, 1, 0); PG8_LDB(B1, 1, 1); PG8_SCHED; PG8_LDA(At, 1, 0); PG8_STAGE(PG8_SA(0, 1), a2 + hstep, voffA);
;             PG8_WAIT_V(8); PG8_WAIT_L(0); PG8_BAR; PG8_MMA(0, 0, At, B0); PG8_MMA(0, 1, At, B1); PG8_BAR; PG8_SCHED;
;             PG8_LDA(At, 1, 1); PG8_STAGE(PG8_SB(1, 0), b3, voffB); PG8_STAGE(PG8_SB(1, 1), b3 + hstep, voffB); PG8_STAGE(PG8_SA(1, 0), a3, voffA);
;             PG8_WAIT_V(8); PG8_WAIT_L(0); PG8_BAR; PG8_MMA(1, 0, At, B0); PG8_MMA(1, 1, At, B1); PG8_BAR; PG8_SCHED;
	s_add_i32 s57, 0, 0x18000
	s_add_i32 s58, 0, 0x1c000
	v_add_u32_e32 v176, s57, v159
	v_add_u32_e32 v192, s58, v159
	ds_read_b128 v[164:167], v176
	ds_read_b128 v[168:171], v176 offset:1024
	ds_read_b128 v[172:175], v176 offset:2048
	ds_read_b128 v[176:179], v176 offset:3072
	ds_read_b128 v[180:183], v192
	ds_read_b128 v[184:187], v192 offset:1024
	ds_read_b128 v[188:191], v192 offset:2048
	ds_read_b128 v[192:195], v192 offset:3072
	s_add_u32 s38, s38, 0x40000
	s_addc_u32 s39, s39, 0
	s_mov_b32 m0, s47
	ds_read_b128 v[196:199], v163 offset:32768
	ds_read_b128 v[216:219], v163 offset:33792
	ds_read_b128 v[220:223], v163 offset:34816
	ds_read_b128 v[224:227], v163 offset:35840
	ds_read_b128 v[228:231], v163 offset:36864
	ds_read_b128 v[232:235], v163 offset:37888
	ds_read_b128 v[236:239], v163 offset:38912
	ds_read_b128 v[240:243], v163 offset:39936
	global_load_lds_dwordx4 v134, s[38:39]
	s_mov_b32 m0, s48
	s_nop 0
	global_load_lds_dwordx4 v130, s[38:39]
	s_waitcnt vmcnt(8)
	s_waitcnt lgkmcnt(0)
	s_barrier
	s_setprio 1
	v_mfma_f32_16x16x32_bf16 v[116:119], v[164:167], v[196:199], v[116:119]
	v_mfma_f32_16x16x32_bf16 v[112:115], v[172:175], v[196:199], v[112:115]
	v_mfma_f32_16x16x32_bf16 v[100:103], v[164:167], v[220:223], v[100:103]
	v_mfma_f32_16x16x32_bf16 v[96:99], v[172:175], v[220:223], v[96:99]
	v_mfma_f32_16x16x32_bf16 v[84:87], v[164:167], v[228:231], v[84:87]
	v_mfma_f32_16x16x32_bf16 v[80:83], v[172:175], v[228:231], v[80:83]
	v_mfma_f32_16x16x32_bf16 v[68:71], v[164:167], v[236:239], v[68:71]
	v_mfma_f32_16x16x32_bf16 v[64:67], v[172:175], v[236:239], v[64:67]
	v_mfma_f32_16x16x32_bf16 v[116:119], v[168:171], v[216:219], v[116:119]
	v_mfma_f32_16x16x32_bf16 v[112:115], v[176:179], v[216:219], v[112:115]
	v_mfma_f32_16x16x32_bf16 v[100:103], v[168:171], v[224:227], v[100:103]
	v_mfma_f32_16x16x32_bf16 v[96:99], v[176:179], v[224:227], v[96:99]
	v_mfma_f32_16x16x32_bf16 v[84:87], v[168:171], v[232:235], v[84:87]
	v_mfma_f32_16x16x32_bf16 v[80:83], v[176:179], v[232:235], v[80:83]
	v_mfma_f32_16x16x32_bf16 v[68:71], v[168:171], v[240:243], v[68:71]
	v_mfma_f32_16x16x32_bf16 v[64:67], v[176:179], v[240:243], v[64:67]
	v_mfma_f32_16x16x32_bf16 v[124:127], v[180:183], v[196:199], v[124:127]
	v_mfma_f32_16x16x32_bf16 v[120:123], v[188:191], v[196:199], v[120:123]
	v_mfma_f32_16x16x32_bf16 v[108:111], v[180:183], v[220:223], v[108:111]
	v_mfma_f32_16x16x32_bf16 v[104:107], v[188:191], v[220:223], v[104:107]
	v_mfma_f32_16x16x32_bf16 v[92:95], v[180:183], v[228:231], v[92:95]
	v_mfma_f32_16x16x32_bf16 v[88:91], v[188:191], v[228:231], v[88:91]
	v_mfma_f32_16x16x32_bf16 v[76:79], v[180:183], v[236:239], v[76:79]
	v_mfma_f32_16x16x32_bf16 v[72:75], v[188:191], v[236:239], v[72:75]
	v_mfma_f32_16x16x32_bf16 v[124:127], v[184:187], v[216:219], v[124:127]
	v_mfma_f32_16x16x32_bf16 v[120:123], v[192:195], v[216:219], v[120:123]
	v_mfma_f32_16x16x32_bf16 v[108:111], v[184:187], v[224:227], v[108:111]
	v_mfma_f32_16x16x32_bf16 v[104:107], v[192:195], v[224:227], v[104:107]
	v_mfma_f32_16x16x32_bf16 v[92:95], v[184:187], v[232:235], v[92:95]
	v_mfma_f32_16x16x32_bf16 v[88:91], v[192:195], v[232:235], v[88:91]
	v_mfma_f32_16x16x32_bf16 v[76:79], v[184:187], v[240:243], v[76:79]
	v_mfma_f32_16x16x32_bf16 v[72:75], v[192:195], v[240:243], v[72:75]
	s_setprio 0
	s_barrier
	s_add_i32 m0, s41, 0x18000
	s_add_u32 s28, s28, 0x80
	s_addc_u32 s29, s29, 0
	ds_read_b128 v[196:199], v163 offset:49152
	ds_read_b128 v[216:219], v163 offset:50176
	ds_read_b128 v[220:223], v163 offset:51200
	ds_read_b128 v[224:227], v163 offset:52224
	ds_read_b128 v[228:231], v163 offset:53248
	ds_read_b128 v[232:235], v163 offset:54272
	ds_read_b128 v[236:239], v163 offset:55296
	ds_read_b128 v[240:243], v163 offset:56320
	global_load_lds_dwordx4 v132, s[28:29]
	s_add_i32 m0, s41, 0x1a000
	s_add_u32 s58, s38, 0xfffc0080
	s_addc_u32 s59, s39, -1
	global_load_lds_dwordx4 v128, s[28:29]
	s_add_u32 s28, s28, 0x40000
	s_addc_u32 s29, s29, 0
	s_add_i32 m0, s41, 0x1c000
	s_nop 0
	global_load_lds_dwordx4 v132, s[28:29]
	s_add_i32 m0, s41, 0x1e000
	s_nop 0
	global_load_lds_dwordx4 v128, s[28:29]
	s_mov_b32 m0, s49
	s_nop 0
	global_load_lds_dwordx4 v134, s[58:59]
	s_mov_b32 m0, s50
	s_nop 0
	global_load_lds_dwordx4 v130, s[58:59]
	s_waitcnt vmcnt(8)
	s_waitcnt lgkmcnt(0)
	s_barrier
	s_setprio 1
	v_mfma_f32_16x16x32_bf16 v[52:55], v[164:167], v[196:199], v[52:55]
	v_mfma_f32_16x16x32_bf16 v[48:51], v[172:175], v[196:199], v[48:51]
	v_mfma_f32_16x16x32_bf16 v[36:39], v[164:167], v[220:223], v[36:39]
	v_mfma_f32_16x16x32_bf16 v[32:35], v[172:175], v[220:223], v[32:35]
	v_mfma_f32_16x16x32_bf16 v[20:23], v[164:167], v[228:231], v[20:23]
	v_mfma_f32_16x16x32_bf16 v[16:19], v[172:175], v[228:231], v[16:19]
	v_mfma_f32_16x16x32_bf16 v[4:7], v[164:167], v[236:239], v[4:7]
	v_mfma_f32_16x16x32_bf16 v[0:3], v[172:175], v[236:239], v[0:3]
	v_mfma_f32_16x16x32_bf16 v[52:55], v[168:171], v[216:219], v[52:55]
	v_mfma_f32_16x16x32_bf16 v[48:51], v[176:179], v[216:219], v[48:51]
	v_mfma_f32_16x16x32_bf16 v[36:39], v[168:171], v[224:227], v[36:39]
	v_mfma_f32_16x16x32_bf16 v[32:35], v[176:179], v[224:227], v[32:35]
	v_mfma_f32_16x16x32_bf16 v[20:23], v[168:171], v[232:235], v[20:23]
	v_mfma_f32_16x16x32_bf16 v[16:19], v[176:179], v[232:235], v[16:19]
	v_mfma_f32_16x16x32_bf16 v[4:7], v[168:171], v[240:243], v[4:7]
	v_mfma_f32_16x16x32_bf16 v[0:3], v[176:179], v[240:243], v[0:3]
	v_mfma_f32_16x16x32_bf16 v[60:63], v[180:183], v[196:199], v[60:63]
	v_mfma_f32_16x16x32_bf16 v[56:59], v[188:191], v[196:199], v[56:59]
	v_mfma_f32_16x16x32_bf16 v[44:47], v[180:183], v[220:223], v[44:47]
	v_mfma_f32_16x16x32_bf16 v[40:43], v[188:191], v[220:223], v[40:43]
	v_mfma_f32_16x16x32_bf16 v[28:31], v[180:183], v[228:231], v[28:31]
	v_mfma_f32_16x16x32_bf16 v[24:27], v[188:191], v[228:231], v[24:27]
	v_mfma_f32_16x16x32_bf16 v[12:15], v[180:183], v[236:239], v[12:15]
	v_mfma_f32_16x16x32_bf16 v[8:11], v[188:191], v[236:239], v[8:11]
	v_mfma_f32_16x16x32_bf16 v[60:63], v[184:187], v[216:219], v[60:63]
	v_mfma_f32_16x16x32_bf16 v[56:59], v[192:195], v[216:219], v[56:59]
	v_mfma_f32_16x16x32_bf16 v[44:47], v[184:187], v[224:227], v[44:47]
	v_mfma_f32_16x16x32_bf16 v[40:43], v[192:195], v[224:227], v[40:43]
	v_mfma_f32_16x16x32_bf16 v[28:31], v[184:187], v[232:235], v[28:31]
	v_mfma_f32_16x16x32_bf16 v[24:27], v[192:195], v[232:235], v[24:27]
	v_mfma_f32_16x16x32_bf16 v[12:15], v[184:187], v[240:243], v[12:15]
	v_mfma_f32_16x16x32_bf16 v[8:11], v[192:195], v[240:243], v[8:11]
	s_setprio 0
	s_barrier
	s_add_i32 s56, s56, 2
	s_add_u32 s18, s18, 0x100
	s_addc_u32 s19, s19, 0
	s_add_u32 s54, s54, 0x100
	s_addc_u32 s55, s55, 0
	s_cmp_gt_u32 s56, 13
	s_cbranch_scc0 .LBB0_711
	s_and_b64 vcc, exec, s[6:7]
	s_cbranch_vccz .LBB0_714
	s_barrier

; #define PG8_STAGE(bufoff, gbase, voff) do { _Pragma("unroll") for (int _i = 0; _i < 2; ++_i) \
;         __builtin_amdgcn_global_load_lds((const unsigned*)((const char*)(gbase) + (voff)[_i]), (PG8_LAS unsigned*)(lds + (bufoff) + ldsw + _i * 8192), 16, 0, 0); } while (0)
; #define PG8_LDA(dst, b, h) do { _Pragma("unroll") for (int m = 0; m < 4; ++m) _Pragma("unroll") for (int k = 0; k < 2; ++k) dst[m][k] = *(const PG8_LAS bf16x8*)(lds + PG8_SA(b, h) + aoff + m * 2048 + k * 1024); } while (0)
; #define PG8_LDB(dst, b, h) do { _Pragma("unroll") for (int n = 0; n < 2; ++n) _Pragma("unroll") for (int k = 0; k < 2; ++k) dst[n][k] = *(const PG8_LAS bf16x8*)(lds + PG8_SB(b, h) + boff + n * 2048 + k * 1024); } while (0)
; #define PG8_WAIT_V(n) asm volatile("s_waitcnt vmcnt(" #n ")" ::: "memory")
; #define PG8_WAIT_L(n) asm volatile("s_waitcnt lgkmcnt(" #n ")" ::: "memory")
; #define PG8_BAR __builtin_amdgcn_s_barrier()
; #define PG8_SCHED __builtin_amdgcn_sched_barrier(0)
; template <class Epi, class Sched, bool ALIGN_EPI = false, bool SP2 = false>
; __device__ __forceinline__ void gemm_phase(PG8_LAS unsigned char* lds, const Gemm g, const Sched& S, const Epi& E) {
;     ...
;         const bool has_next = S.next(ui + 1, nxt);
;         const char* nA = has_next ? (const char*)g.A + (size_t)nxt.pm * tstep : cA; const char* nB = has_next ? (const char*)g.Bt + (size_t)nxt.pn * tstep : cB;
;         for (int t = 0; t < nt; t += 2) {
;             const bool last = (t == nt - 2);
;             const char* a1 = cA + (size_t)(t + 1) * kstep;
;             const char* a2 = last ? nA : cA + (size_t)(t + 2) * kstep; const char* b2 = last ? nB : cB + (size_t)(t + 2) * kstep;
;             const char* a3 = a2 + kstep; const char* b3 = b2 + kstep;
;             if (last && has_next) S.a_ready(nxt);
;             if constexpr (SP2) {
;             PG8_LDB(B0, 0, 0); PG8_LDB(B1, 0, 1); PG8_SCHED; PG8_LDA(At, 0, 0); PG8_STAGE(PG8_SA(1, 1), a1 + hstep, voffA);
;             PG8_WAIT_V(8); PG8_WAIT_L(0); PG8_BAR; PG8_MMA(0, 0, At, B0); PG8_MMA(0, 1, At, B1); PG8_BAR; PG8_SCHED;
;             PG8_LDA(At, 0, 1); PG8_STAGE(PG8_SB(0, 0), b2, voffB); PG8_STAGE(PG8_SB(0, 1), b2 + hstep, voffB); PG8_STAGE(PG8_SA(0, 0), a2, voffA);
;             PG8_WAIT_V(8); PG8_WAIT_L(0); PG8_BAR; PG8_MMA(1, 0, At, B0); PG8_MMA(1, 1, At, B1); PG8_BAR; PG8_SCHED;
.LBB0_797:
	s_add_u32 s28, s18, 0x100
	s_addc_u32 s29, s19, 0
	s_add_i32 s63, 0, 0x10000
	s_cmp_eq_u32 s62, 40
	s_cselect_b32 s43, s1, s29
	s_cselect_b32 s42, s0, s28
	v_add_u32_e32 v144, s63, v216
	s_cselect_b32 s41, s17, s45
	s_cselect_b32 s40, s16, s4
	s_add_i32 s66, 0, 0x14000
	ds_read_b128 v[128:131], v144
	ds_read_b128 v[132:135], v144 offset:1024
	ds_read_b128 v[168:171], v144 offset:2048
	ds_read_b128 v[172:175], v144 offset:3072
	v_add_u32_e32 v144, s66, v216
	ds_read_b128 v[176:179], v144
	ds_read_b128 v[180:183], v144 offset:1024
	ds_read_b128 v[184:187], v144 offset:2048
	ds_read_b128 v[188:191], v144 offset:3072
	v_lshl_add_u64 v[242:243], s[18:19], 0, v[162:163]
	s_add_i32 m0, s50, 0xc000
	ds_read_b128 v[192:195], v217
	ds_read_b128 v[196:199], v217 offset:1024
	ds_read_b128 v[218:221], v217 offset:2048
	ds_read_b128 v[222:225], v217 offset:3072
	ds_read_b128 v[226:229], v217 offset:4096
	ds_read_b128 v[230:233], v217 offset:5120
	ds_read_b128 v[234:237], v217 offset:6144
	ds_read_b128 v[238:241], v217 offset:7168
	global_load_lds_dwordx4 v[242:243], off
	v_lshl_add_u64 v[242:243], s[18:19], 0, v[164:165]
	s_add_i32 m0, s50, 0xe000
	s_nop 0
	global_load_lds_dwordx4 v[242:243], off
	s_waitcnt vmcnt(8)
	s_waitcnt lgkmcnt(0)
	s_barrier
	s_setprio 1
	v_mfma_f32_16x16x32_bf16 v[124:127], v[128:131], v[192:195], v[124:127]
	v_mfma_f32_16x16x32_bf16 v[120:123], v[168:171], v[192:195], v[120:123]
	v_mfma_f32_16x16x32_bf16 v[108:111], v[128:131], v[218:221], v[108:111]
	v_mfma_f32_16x16x32_bf16 v[104:107], v[168:171], v[218:221], v[104:107]
	v_mfma_f32_16x16x32_bf16 v[92:95], v[128:131], v[226:229], v[92:95]
	v_mfma_f32_16x16x32_bf16 v[88:91], v[168:171], v[226:229], v[88:91]
	v_mfma_f32_16x16x32_bf16 v[76:79], v[128:131], v[234:237], v[76:79]
	v_mfma_f32_16x16x32_bf16 v[72:75], v[168:171], v[234:237], v[72:75]
	v_mfma_f32_16x16x32_bf16 v[124:127], v[132:135], v[196:199], v[124:127]
	v_mfma_f32_16x16x32_bf16 v[120:123], v[172:175], v[196:199], v[120:123]
	v_mfma_f32_16x16x32_bf16 v[108:111], v[132:135], v[222:225], v[108:111]
	v_mfma_f32_16x16x32_bf16 v[104:107], v[172:175], v[222:225], v[104:107]
	v_mfma_f32_16x16x32_bf16 v[92:95], v[132:135], v[230:233], v[92:95]
	v_mfma_f32_16x16x32_bf16 v[88:91], v[172:175], v[230:233], v[88:91]
	v_mfma_f32_16x16x32_bf16 v[76:79], v[132:135], v[238:241], v[76:79]
	v_mfma_f32_16x16x32_bf16 v[72:75], v[172:175], v[238:241], v[72:75]
	v_mfma_f32_16x16x32_bf16 v[116:119], v[176:179], v[192:195], v[116:119]
	v_mfma_f32_16x16x32_bf16 v[112:115], v[184:187], v[192:195], v[112:115]
	v_mfma_f32_16x16x32_bf16 v[100:103], v[176:179], v[218:221], v[100:103]
	v_mfma_f32_16x16x32_bf16 v[96:99], v[184:187], v[218:221], v[96:99]
	v_mfma_f32_16x16x32_bf16 v[84:87], v[176:179], v[226:229], v[84:87]
	v_mfma_f32_16x16x32_bf16 v[80:83], v[184:187], v[226:229], v[80:83]
	v_mfma_f32_16x16x32_bf16 v[68:71], v[176:179], v[234:237], v[68:71]
	v_mfma_f32_16x16x32_bf16 v[64:67], v[184:187], v[234:237], v[64:67]
	v_mfma_f32_16x16x32_bf16 v[116:119], v[180:183], v[196:199], v[116:119]
	v_mfma_f32_16x16x32_bf16 v[112:115], v[188:191], v[196:199], v[112:115]
	v_mfma_f32_16x16x32_bf16 v[100:103], v[180:183], v[222:225], v[100:103]
	v_mfma_f32_16x16x32_bf16 v[96:99], v[188:191], v[222:225], v[96:99]
	v_mfma_f32_16x16x32_bf16 v[84:87], v[180:183], v[230:233], v[84:87]
	v_mfma_f32_16x16x32_bf16 v[80:83], v[188:191], v[230:233], v[80:83]
	v_mfma_f32_16x16x32_bf16 v[68:71], v[180:183], v[238:241], v[68:71]
	v_mfma_f32_16x16x32_bf16 v[64:67], v[188:191], v[238:241], v[64:67]
	s_setprio 0
	s_barrier
	s_add_i32 s18, s63, s49
	v_lshl_add_u64 v[242:243], s[40:41], 0, v[138:139]
	s_mov_b32 m0, s18
	ds_read_b128 v[192:195], v217 offset:16384
	ds_read_b128 v[196:199], v217 offset:17408
	ds_read_b128 v[218:221], v217 offset:18432
	ds_read_b128 v[222:225], v217 offset:19456
	ds_read_b128 v[226:229], v217 offset:20480
	ds_read_b128 v[230:233], v217 offset:21504
	ds_read_b128 v[234:237], v217 offset:22528
	ds_read_b128 v[238:241], v217 offset:23552
	global_load_lds_dwordx4 v[242:243], off
	s_add_i32 m0, s18, 0x2000
	s_add_u32 s18, s40, 0xb0000
	v_lshl_add_u64 v[244:245], s[40:41], 0, v[142:143]
	s_addc_u32 s19, s41, 0
	s_add_i32 s63, s66, s49
	global_load_lds_dwordx4 v[244:245], off
	v_lshl_add_u64 v[246:247], s[18:19], 0, v[138:139]
	s_mov_b32 m0, s63
	v_lshl_add_u64 v[248:249], s[42:43], 0, v[140:141]
	global_load_lds_dwordx4 v[246:247], off
	v_lshl_add_u64 v[246:247], s[18:19], 0, v[142:143]
	s_add_i32 m0, s63, 0x2000
	s_nop 0
	global_load_lds_dwordx4 v[246:247], off
	v_lshl_add_u64 v[246:247], s[42:43], 0, v[136:137]
	s_mov_b32 m0, s50
	s_nop 0
	global_load_lds_dwordx4 v[246:247], off
	s_mov_b32 m0, s51
	s_nop 0
	global_load_lds_dwordx4 v[248:249], off
	s_waitcnt vmcnt(8)
	s_waitcnt lgkmcnt(0)
	s_barrier
; #define PG8_STAGE(bufoff, gbase, voff) do { _Pragma("unroll") for (int _i = 0; _i < 2; ++_i) \
;         __builtin_amdgcn_global_load_lds((const unsigned*)((const char*)(gbase) + (voff)[_i]), (PG8_LAS unsigned*)(lds + (bufoff) + ldsw + _i * 8192), 16, 0, 0); } while (0)
; #define PG8_LDA(dst, b, h) do { _Pragma("unroll") for (int m = 0; m < 4; ++m) _Pragma("unroll") for (int k = 0; k < 2; ++k) dst[m][k] = *(const PG8_LAS bf16x8*)(lds + PG8_SA(b, h) + aoff + m * 2048 + k * 1024); } while (0)
; #define PG8_LDB(dst, b, h) do { _Pragma("unroll") for (int n = 0; n < 2; ++n) _Pragma("unroll") for (int k = 0; k < 2; ++k) dst[n][k] = *(const PG8_LAS bf16x8*)(lds + PG8_SB(b, h) + boff + n * 2048 + k * 1024); } while (0)
; #define PG8_MMA(ai, bj, At, Bt) do { __builtin_amdgcn_s_setprio(1); _Pragma("unroll") for (int m = 0; m < 4; ++m) _Pragma("unroll") for (int n = 0; n < 2; ++n) _Pragma("unroll") for (int k = 0; k < 2; ++k) \
;         acc[ai][bj][m][n] = __builtin_amdgcn_mfma_f32_16x16x32_bf16(Bt[n][k], At[m][k], acc[ai][bj][m][n], 0, 0, 0); __builtin_amdgcn_s_setprio(0); } while (0)
; #define PG8_WAIT_V(n) asm volatile("s_waitcnt vmcnt(" #n ")" ::: "memory")
; #define PG8_WAIT_L(n) asm volatile("s_waitcnt lgkmcnt(" #n ")" ::: "memory")
; #define PG8_BAR __builtin_amdgcn_s_barrier()
; #define PG8_SCHED __builtin_amdgcn_sched_barrier(0)
; template <class Epi, class Sched, bool ALIGN_EPI = false, bool SP2 = false>
; __device__ __forceinline__ void gemm_phase(PG8_LAS unsigned char* lds, const Gemm g, const Sched& S, const Epi& E) {
;     ...
;             PG8_WAIT_V(8); PG8_WAIT_L(0); PG8_BAR; PG8_MMA(1, 0, At, B0); PG8_MMA(1, 1, At, B1); PG8_BAR; PG8_SCHED;
;             PG8_LDB(B0, 1, 0); PG8_LDB(B1, 1, 1); PG8_SCHED; PG8_LDA(At, 1, 0); PG8_STAGE(PG8_SA(0, 1), a2 + hstep, voffA);
;             PG8_WAIT_V(8); PG8_WAIT_L(0); PG8_BAR; PG8_MMA(0, 0, At, B0); PG8_MMA(0, 1, At, B1); PG8_BAR; PG8_SCHED;
	s_setprio 1
	v_mfma_f32_16x16x32_bf16 v[60:63], v[128:131], v[192:195], v[60:63]
	v_mfma_f32_16x16x32_bf16 v[56:59], v[168:171], v[192:195], v[56:59]
	v_mfma_f32_16x16x32_bf16 v[44:47], v[128:131], v[218:221], v[44:47]
	v_mfma_f32_16x16x32_bf16 v[40:43], v[168:171], v[218:221], v[40:43]
	v_mfma_f32_16x16x32_bf16 v[28:31], v[128:131], v[226:229], v[28:31]
	v_mfma_f32_16x16x32_bf16 v[24:27], v[168:171], v[226:229], v[24:27]
	v_mfma_f32_16x16x32_bf16 v[12:15], v[128:131], v[234:237], v[12:15]
	v_mfma_f32_16x16x32_bf16 v[8:11], v[168:171], v[234:237], v[8:11]
	v_mfma_f32_16x16x32_bf16 v[60:63], v[132:135], v[196:199], v[60:63]
	v_mfma_f32_16x16x32_bf16 v[56:59], v[172:175], v[196:199], v[56:59]
	v_mfma_f32_16x16x32_bf16 v[44:47], v[132:135], v[222:225], v[44:47]
	v_mfma_f32_16x16x32_bf16 v[40:43], v[172:175], v[222:225], v[40:43]
	v_mfma_f32_16x16x32_bf16 v[28:31], v[132:135], v[230:233], v[28:31]
	v_mfma_f32_16x16x32_bf16 v[24:27], v[172:175], v[230:233], v[24:27]
	v_mfma_f32_16x16x32_bf16 v[12:15], v[132:135], v[238:241], v[12:15]
	v_mfma_f32_16x16x32_bf16 v[8:11], v[172:175], v[238:241], v[8:11]
	v_mfma_f32_16x16x32_bf16 v[52:55], v[176:179], v[192:195], v[52:55]
	v_mfma_f32_16x16x32_bf16 v[48:51], v[184:187], v[192:195], v[48:51]
	v_mfma_f32_16x16x32_bf16 v[36:39], v[176:179], v[218:221], v[36:39]
	v_mfma_f32_16x16x32_bf16 v[32:35], v[184:187], v[218:221], v[32:35]
	v_mfma_f32_16x16x32_bf16 v[20:23], v[176:179], v[226:229], v[20:23]
	v_mfma_f32_16x16x32_bf16 v[16:19], v[184:187], v[226:229], v[16:19]
	v_mfma_f32_16x16x32_bf16 v[4:7], v[176:179], v[234:237], v[4:7]
	v_mfma_f32_16x16x32_bf16 v[0:3], v[184:187], v[234:237], v[0:3]
	v_mfma_f32_16x16x32_bf16 v[52:55], v[180:183], v[196:199], v[52:55]
	v_mfma_f32_16x16x32_bf16 v[48:51], v[188:191], v[196:199], v[48:51]
	v_mfma_f32_16x16x32_bf16 v[36:39], v[180:183], v[222:225], v[36:39]
	v_mfma_f32_16x16x32_bf16 v[32:35], v[188:191], v[222:225], v[32:35]
	v_mfma_f32_16x16x32_bf16 v[20:23], v[180:183], v[230:233], v[20:23]
	v_mfma_f32_16x16x32_bf16 v[16:19], v[188:191], v[230:233], v[16:19]
	v_mfma_f32_16x16x32_bf16 v[4:7], v[180:183], v[238:241], v[4:7]
	v_mfma_f32_16x16x32_bf16 v[0:3], v[188:191], v[238:241], v[0:3]
	s_setprio 0
	s_barrier
	s_add_i32 s63, 0, 0x18000
	v_add_u32_e32 v144, s63, v216
	s_add_i32 s66, 0, 0x1c000
	ds_read_b128 v[128:131], v144
	ds_read_b128 v[132:135], v144 offset:1024
	ds_read_b128 v[168:171], v144 offset:2048
	ds_read_b128 v[172:175], v144 offset:3072
	v_add_u32_e32 v144, s66, v216
	ds_read_b128 v[176:179], v144
	ds_read_b128 v[180:183], v144 offset:1024
	ds_read_b128 v[184:187], v144 offset:2048
	ds_read_b128 v[188:191], v144 offset:3072
	s_add_u32 s18, s42, 0xb0000
	s_addc_u32 s19, s43, 0
	s_mov_b32 m0, s52
	v_lshl_add_u64 v[250:251], s[18:19], 0, v[136:137]
	ds_read_b128 v[192:195], v217 offset:32768
	ds_read_b128 v[196:199], v217 offset:33792
	ds_read_b128 v[218:221], v217 offset:34816
	ds_read_b128 v[222:225], v217 offset:35840
	ds_read_b128 v[226:229], v217 offset:36864
	ds_read_b128 v[230:233], v217 offset:37888
	ds_read_b128 v[234:237], v217 offset:38912
	ds_read_b128 v[238:241], v217 offset:39936
	global_load_lds_dwordx4 v[250:251], off
	v_lshl_add_u64 v[250:251], s[18:19], 0, v[140:141]
	s_mov_b32 m0, s53
	s_nop 0
	global_load_lds_dwordx4 v[250:251], off
	s_waitcnt vmcnt(8)
	s_waitcnt lgkmcnt(0)
	s_barrier
	s_setprio 1
	v_mfma_f32_16x16x32_bf16 v[124:127], v[128:131], v[192:195], v[124:127]
	v_mfma_f32_16x16x32_bf16 v[120:123], v[168:171], v[192:195], v[120:123]
	v_mfma_f32_16x16x32_bf16 v[108:111], v[128:131], v[218:221], v[108:111]
	v_mfma_f32_16x16x32_bf16 v[104:107], v[168:171], v[218:221], v[104:107]
	v_mfma_f32_16x16x32_bf16 v[92:95], v[128:131], v[226:229], v[92:95]
	v_mfma_f32_16x16x32_bf16 v[88:91], v[168:171], v[226:229], v[88:91]
	v_mfma_f32_16x16x32_bf16 v[76:79], v[128:131], v[234:237], v[76:79]
	v_mfma_f32_16x16x32_bf16 v[72:75], v[168:171], v[234:237], v[72:75]
	v_mfma_f32_16x16x32_bf16 v[124:127], v[132:135], v[196:199], v[124:127]
	v_mfma_f32_16x16x32_bf16 v[120:123], v[172:175], v[196:199], v[120:123]
	v_mfma_f32_16x16x32_bf16 v[108:111], v[132:135], v[222:225], v[108:111]
	v_mfma_f32_16x16x32_bf16 v[104:107], v[172:175], v[222:225], v[104:107]
	v_mfma_f32_16x16x32_bf16 v[92:95], v[132:135], v[230:233], v[92:95]
	v_mfma_f32_16x16x32_bf16 v[88:91], v[172:175], v[230:233], v[88:91]
	v_mfma_f32_16x16x32_bf16 v[76:79], v[132:135], v[238:241], v[76:79]
	v_mfma_f32_16x16x32_bf16 v[72:75], v[172:175], v[238:241], v[72:75]
	v_mfma_f32_16x16x32_bf16 v[116:119], v[176:179], v[192:195], v[116:119]
	v_mfma_f32_16x16x32_bf16 v[112:115], v[184:187], v[192:195], v[112:115]
	v_mfma_f32_16x16x32_bf16 v[100:103], v[176:179], v[218:221], v[100:103]
	v_mfma_f32_16x16x32_bf16 v[96:99], v[184:187], v[218:221], v[96:99]
	v_mfma_f32_16x16x32_bf16 v[84:87], v[176:179], v[226:229], v[84:87]
	v_mfma_f32_16x16x32_bf16 v[80:83], v[184:187], v[226:229], v[80:83]
	v_mfma_f32_16x16x32_bf16 v[68:71], v[176:179], v[234:237], v[68:71]
	v_mfma_f32_16x16x32_bf16 v[64:67], v[184:187], v[234:237], v[64:67]
	v_mfma_f32_16x16x32_bf16 v[116:119], v[180:183], v[196:199], v[116:119]
	v_mfma_f32_16x16x32_bf16 v[112:115], v[188:191], v[196:199], v[112:115]
	v_mfma_f32_16x16x32_bf16 v[100:103], v[180:183], v[222:225], v[100:103]
	v_mfma_f32_16x16x32_bf16 v[96:99], v[188:191], v[222:225], v[96:99]
	v_mfma_f32_16x16x32_bf16 v[84:87], v[180:183], v[230:233], v[84:87]
	v_mfma_f32_16x16x32_bf16 v[80:83], v[188:191], v[230:233], v[80:83]
	v_mfma_f32_16x16x32_bf16 v[68:71], v[180:183], v[238:241], v[68:71]
	v_mfma_f32_16x16x32_bf16 v[64:67], v[188:191], v[238:241], v[64:67]
	s_setprio 0
	s_barrier
; #define PG8_STAGE(bufoff, gbase, voff) do { _Pragma("unroll") for (int _i = 0; _i < 2; ++_i) \
;         __builtin_amdgcn_global_load_lds((const unsigned*)((const char*)(gbase) + (voff)[_i]), (PG8_LAS unsigned*)(lds + (bufoff) + ldsw + _i * 8192), 16, 0, 0); } while (0)
; #define PG8_LDA(dst, b, h) do { _Pragma("unroll") for (int m = 0; m < 4; ++m) _Pragma("unroll") for (int k = 0; k < 2; ++k) dst[m][k] = *(const PG8_LAS bf16x8*)(lds + PG8_SA(b, h) + aoff + m * 2048 + k * 1024); } while (0)
; #define PG8_MMA(ai, bj, At, Bt) do { __builtin_amdgcn_s_setprio(1); _Pragma("unroll") for (int m = 0; m < 4; ++m) _Pragma("unroll") for (int n = 0; n < 2; ++n) _Pragma("unroll") for (int k = 0; k < 2; ++k) \
;         acc[ai][bj][m][n] = __builtin_amdgcn_mfma_f32_16x16x32_bf16(Bt[n][k], At[m][k], acc[ai][bj][m][n], 0, 0, 0); __builtin_amdgcn_s_setprio(0); } while (0)
; #define PG8_WAIT_V(n) asm volatile("s_waitcnt vmcnt(" #n ")" ::: "memory")
; #define PG8_WAIT_L(n) asm volatile("s_waitcnt lgkmcnt(" #n ")" ::: "memory")
; #define PG8_BAR __builtin_amdgcn_s_barrier()
; #define PG8_SCHED __builtin_amdgcn_sched_barrier(0)
; template <class Epi, class Sched, bool ALIGN_EPI = false, bool SP2 = false>
; __device__ __forceinline__ void gemm_phase(PG8_LAS unsigned char* lds, const Gemm g, const Sched& S, const Epi& E) {
;     ...
;             PG8_LDA(At, 1, 1); PG8_STAGE(PG8_SB(1, 0), b3, voffB); PG8_STAGE(PG8_SB(1, 1), b3 + hstep, voffB); PG8_STAGE(PG8_SA(1, 0), a3, voffA);
;             PG8_WAIT_V(8); PG8_WAIT_L(0); PG8_BAR; PG8_MMA(1, 0, At, B0); PG8_MMA(1, 1, At, B1); PG8_BAR; PG8_SCHED;
	s_add_i32 s18, s63, s49
	v_lshl_add_u64 v[242:243], v[242:243], 0, s[2:3]
	s_mov_b32 m0, s18
	ds_read_b128 v[192:195], v217 offset:49152
	ds_read_b128 v[196:199], v217 offset:50176
	ds_read_b128 v[218:221], v217 offset:51200
	ds_read_b128 v[222:225], v217 offset:52224
	ds_read_b128 v[226:229], v217 offset:53248
	ds_read_b128 v[230:233], v217 offset:54272
	ds_read_b128 v[234:237], v217 offset:55296
	ds_read_b128 v[238:241], v217 offset:56320
	global_load_lds_dwordx4 v[242:243], off
	s_add_i32 m0, s18, 0x2000
	s_add_u32 s18, s40, 0xb0080
	v_lshl_add_u64 v[242:243], v[244:245], 0, s[2:3]
	s_addc_u32 s19, s41, 0
	s_add_i32 s40, s66, s49
	global_load_lds_dwordx4 v[242:243], off
	v_lshl_add_u64 v[242:243], s[18:19], 0, v[138:139]
	s_mov_b32 m0, s40
	s_nop 0
	global_load_lds_dwordx4 v[242:243], off
	v_lshl_add_u64 v[242:243], s[18:19], 0, v[142:143]
	s_add_i32 m0, s40, 0x2000
	s_nop 0
	global_load_lds_dwordx4 v[242:243], off
	v_lshl_add_u64 v[242:243], v[246:247], 0, s[2:3]
	s_mov_b32 m0, s56
	s_nop 0
	global_load_lds_dwordx4 v[242:243], off
	v_lshl_add_u64 v[242:243], v[248:249], 0, s[2:3]
	s_mov_b32 m0, s57
	s_nop 0
	global_load_lds_dwordx4 v[242:243], off
	s_waitcnt vmcnt(8)
	s_waitcnt lgkmcnt(0)
	s_barrier
	s_setprio 1
	v_mfma_f32_16x16x32_bf16 v[60:63], v[128:131], v[192:195], v[60:63]
	v_mfma_f32_16x16x32_bf16 v[56:59], v[168:171], v[192:195], v[56:59]
	v_mfma_f32_16x16x32_bf16 v[44:47], v[128:131], v[218:221], v[44:47]
	v_mfma_f32_16x16x32_bf16 v[40:43], v[168:171], v[218:221], v[40:43]
	v_mfma_f32_16x16x32_bf16 v[28:31], v[128:131], v[226:229], v[28:31]
	v_mfma_f32_16x16x32_bf16 v[24:27], v[168:171], v[226:229], v[24:27]
	v_mfma_f32_16x16x32_bf16 v[12:15], v[128:131], v[234:237], v[12:15]
	v_mfma_f32_16x16x32_bf16 v[8:11], v[168:171], v[234:237], v[8:11]
	v_mfma_f32_16x16x32_bf16 v[60:63], v[132:135], v[196:199], v[60:63]
	v_mfma_f32_16x16x32_bf16 v[56:59], v[172:175], v[196:199], v[56:59]
	v_mfma_f32_16x16x32_bf16 v[44:47], v[132:135], v[222:225], v[44:47]
	v_mfma_f32_16x16x32_bf16 v[40:43], v[172:175], v[222:225], v[40:43]
	v_mfma_f32_16x16x32_bf16 v[28:31], v[132:135], v[230:233], v[28:31]
	v_mfma_f32_16x16x32_bf16 v[24:27], v[172:175], v[230:233], v[24:27]
	v_mfma_f32_16x16x32_bf16 v[12:15], v[132:135], v[238:241], v[12:15]
	v_mfma_f32_16x16x32_bf16 v[8:11], v[172:175], v[238:241], v[8:11]
	v_mfma_f32_16x16x32_bf16 v[52:55], v[176:179], v[192:195], v[52:55]
	v_mfma_f32_16x16x32_bf16 v[48:51], v[184:187], v[192:195], v[48:51]
	v_mfma_f32_16x16x32_bf16 v[36:39], v[176:179], v[218:221], v[36:39]
	v_mfma_f32_16x16x32_bf16 v[32:35], v[184:187], v[218:221], v[32:35]
	v_mfma_f32_16x16x32_bf16 v[20:23], v[176:179], v[226:229], v[20:23]
	v_mfma_f32_16x16x32_bf16 v[16:19], v[184:187], v[226:229], v[16:19]
	v_mfma_f32_16x16x32_bf16 v[4:7], v[176:179], v[234:237], v[4:7]
	v_mfma_f32_16x16x32_bf16 v[0:3], v[184:187], v[234:237], v[0:3]
	v_mfma_f32_16x16x32_bf16 v[52:55], v[180:183], v[196:199], v[52:55]
	v_mfma_f32_16x16x32_bf16 v[48:51], v[188:191], v[196:199], v[48:51]
	v_mfma_f32_16x16x32_bf16 v[36:39], v[180:183], v[222:225], v[36:39]
	v_mfma_f32_16x16x32_bf16 v[32:35], v[188:191], v[222:225], v[32:35]
	v_mfma_f32_16x16x32_bf16 v[20:23], v[180:183], v[230:233], v[20:23]
	v_mfma_f32_16x16x32_bf16 v[16:19], v[188:191], v[230:233], v[16:19]
	v_mfma_f32_16x16x32_bf16 v[4:7], v[180:183], v[238:241], v[4:7]
	v_mfma_f32_16x16x32_bf16 v[0:3], v[188:191], v[238:241], v[0:3]
	s_setprio 0
	s_barrier
	s_add_i32 s62, s62, 2
	s_add_u32 s4, s4, 0x100
	s_addc_u32 s45, s45, 0
	s_cmp_gt_u32 s62, 41
	s_mov_b64 s[18:19], s[28:29]
	s_cbranch_scc0 .LBB0_797
	s_and_b64 vcc, exec, s[12:13]
	s_cbranch_vccz .LBB0_800
	s_barrier

; #define PG8_STAGE(bufoff, gbase, voff) do { _Pragma("unroll") for (int _i = 0; _i < 2; ++_i) \
;         __builtin_amdgcn_global_load_lds((const unsigned*)((const char*)(gbase) + (voff)[_i]), (PG8_LAS unsigned*)(lds + (bufoff) + ldsw + _i * 8192), 16, 0, 0); } while (0)
; #define PG8_LDA(dst, b, h) do { _Pragma("unroll") for (int m = 0; m < 4; ++m) _Pragma("unroll") for (int k = 0; k < 2; ++k) dst[m][k] = *(const PG8_LAS bf16x8*)(lds + PG8_SA(b, h) + aoff + m * 2048 + k * 1024); } while (0)
; #define PG8_LDB(dst, b, h) do { _Pragma("unroll") for (int n = 0; n < 2; ++n) _Pragma("unroll") for (int k = 0; k < 2; ++k) dst[n][k] = *(const PG8_LAS bf16x8*)(lds + PG8_SB(b, h) + boff + n * 2048 + k * 1024); } while (0)
; #define PG8_WAIT_V(n) asm volatile("s_waitcnt vmcnt(" #n ")" ::: "memory")
; #define PG8_WAIT_L(n) asm volatile("s_waitcnt lgkmcnt(" #n ")" ::: "memory")
; #define PG8_BAR __builtin_amdgcn_s_barrier()
; #define PG8_SCHED __builtin_amdgcn_sched_barrier(0)
; template <class Epi, class Sched, bool ALIGN_EPI = false, bool SP2 = false>
; __device__ __forceinline__ void gemm_phase(PG8_LAS unsigned char* lds, const Gemm g, const Sched& S, const Epi& E) {
;     ...
;         const bool has_next = S.next(ui + 1, nxt);
;         const char* nA = has_next ? (const char*)g.A + (size_t)nxt.pm * tstep : cA; const char* nB = has_next ? (const char*)g.Bt + (size_t)nxt.pn * tstep : cB;
;         for (int t = 0; t < nt; t += 2) {
;             const bool last = (t == nt - 2);
;             const char* a1 = cA + (size_t)(t + 1) * kstep;
;             const char* a2 = last ? nA : cA + (size_t)(t + 2) * kstep; const char* b2 = last ? nB : cB + (size_t)(t + 2) * kstep;
;             const char* a3 = a2 + kstep; const char* b3 = b2 + kstep;
;             if (last && has_next) S.a_ready(nxt);
;             if constexpr (SP2) {
;             PG8_LDB(B0, 0, 0); PG8_LDB(B1, 0, 1); PG8_SCHED; PG8_LDA(At, 0, 0); PG8_STAGE(PG8_SA(1, 1), a1 + hstep, voffA);
;             PG8_WAIT_V(8); PG8_WAIT_L(0); PG8_BAR; PG8_MMA(0, 0, At, B0); PG8_MMA(0, 1, At, B1); PG8_BAR; PG8_SCHED;
;             PG8_LDA(At, 0, 1); PG8_STAGE(PG8_SB(0, 0), b2, voffB); PG8_STAGE(PG8_SB(0, 1), b2 + hstep, voffB); PG8_STAGE(PG8_SA(0, 0), a2, voffA);
;             PG8_WAIT_V(8); PG8_WAIT_L(0); PG8_BAR; PG8_MMA(1, 0, At, B0); PG8_MMA(1, 1, At, B1); PG8_BAR; PG8_SCHED;
.LBB0_857:
	s_add_u32 s18, s16, 0x100
	s_addc_u32 s19, s17, 0
	s_add_i32 s62, 0, 0x10000
	s_cmp_eq_u32 s61, 40
	s_cselect_b32 s41, s1, s19
	s_cselect_b32 s40, s0, s18
	v_add_u32_e32 v144, s62, v168
	s_cselect_b32 s29, s15, s60
	s_cselect_b32 s28, s14, s59
	s_add_i32 s63, 0, 0x14000
	ds_read_b128 v[128:131], v144
	ds_read_b128 v[132:135], v144 offset:1024
	ds_read_b128 v[162:165], v144 offset:2048
	ds_read_b128 v[170:173], v144 offset:3072
	v_add_u32_e32 v144, s63, v168
	ds_read_b128 v[174:177], v144
	ds_read_b128 v[178:181], v144 offset:1024
	ds_read_b128 v[182:185], v144 offset:2048
	ds_read_b128 v[186:189], v144 offset:3072
	v_lshl_add_u64 v[166:167], s[16:17], 0, v[158:159]
	s_add_i32 m0, s44, 0xc000
	ds_read_b128 v[190:193], v169
	ds_read_b128 v[194:197], v169 offset:1024
	ds_read_b128 v[216:219], v169 offset:2048
	ds_read_b128 v[220:223], v169 offset:3072
	ds_read_b128 v[224:227], v169 offset:4096
	ds_read_b128 v[228:231], v169 offset:5120
	ds_read_b128 v[232:235], v169 offset:6144
	ds_read_b128 v[236:239], v169 offset:7168
	global_load_lds_dwordx4 v[166:167], off
	v_lshl_add_u64 v[166:167], s[16:17], 0, v[160:161]
	s_add_i32 m0, s44, 0xe000
	s_nop 0
	global_load_lds_dwordx4 v[166:167], off
	s_waitcnt vmcnt(8)
	s_waitcnt lgkmcnt(0)
	s_barrier
	s_setprio 1
	v_mfma_f32_16x16x32_bf16 v[124:127], v[128:131], v[190:193], v[124:127]
	v_mfma_f32_16x16x32_bf16 v[120:123], v[162:165], v[190:193], v[120:123]
	v_mfma_f32_16x16x32_bf16 v[108:111], v[128:131], v[216:219], v[108:111]
	v_mfma_f32_16x16x32_bf16 v[104:107], v[162:165], v[216:219], v[104:107]
	v_mfma_f32_16x16x32_bf16 v[92:95], v[128:131], v[224:227], v[92:95]
	v_mfma_f32_16x16x32_bf16 v[88:91], v[162:165], v[224:227], v[88:91]
	v_mfma_f32_16x16x32_bf16 v[76:79], v[128:131], v[232:235], v[76:79]
	v_mfma_f32_16x16x32_bf16 v[72:75], v[162:165], v[232:235], v[72:75]
	v_mfma_f32_16x16x32_bf16 v[124:127], v[132:135], v[194:197], v[124:127]
	v_mfma_f32_16x16x32_bf16 v[120:123], v[170:173], v[194:197], v[120:123]
	v_mfma_f32_16x16x32_bf16 v[108:111], v[132:135], v[220:223], v[108:111]
	v_mfma_f32_16x16x32_bf16 v[104:107], v[170:173], v[220:223], v[104:107]
	v_mfma_f32_16x16x32_bf16 v[92:95], v[132:135], v[228:231], v[92:95]
	v_mfma_f32_16x16x32_bf16 v[88:91], v[170:173], v[228:231], v[88:91]
	v_mfma_f32_16x16x32_bf16 v[76:79], v[132:135], v[236:239], v[76:79]
	v_mfma_f32_16x16x32_bf16 v[72:75], v[170:173], v[236:239], v[72:75]
	v_mfma_f32_16x16x32_bf16 v[116:119], v[174:177], v[190:193], v[116:119]
	v_mfma_f32_16x16x32_bf16 v[112:115], v[182:185], v[190:193], v[112:115]
	v_mfma_f32_16x16x32_bf16 v[100:103], v[174:177], v[216:219], v[100:103]
	v_mfma_f32_16x16x32_bf16 v[96:99], v[182:185], v[216:219], v[96:99]
	v_mfma_f32_16x16x32_bf16 v[84:87], v[174:177], v[224:227], v[84:87]
	v_mfma_f32_16x16x32_bf16 v[80:83], v[182:185], v[224:227], v[80:83]
	v_mfma_f32_16x16x32_bf16 v[68:71], v[174:177], v[232:235], v[68:71]
	v_mfma_f32_16x16x32_bf16 v[64:67], v[182:185], v[232:235], v[64:67]
	v_mfma_f32_16x16x32_bf16 v[116:119], v[178:181], v[194:197], v[116:119]
	v_mfma_f32_16x16x32_bf16 v[112:115], v[186:189], v[194:197], v[112:115]
	v_mfma_f32_16x16x32_bf16 v[100:103], v[178:181], v[220:223], v[100:103]
	v_mfma_f32_16x16x32_bf16 v[96:99], v[186:189], v[220:223], v[96:99]
	v_mfma_f32_16x16x32_bf16 v[84:87], v[178:181], v[228:231], v[84:87]
	v_mfma_f32_16x16x32_bf16 v[80:83], v[186:189], v[228:231], v[80:83]
	v_mfma_f32_16x16x32_bf16 v[68:71], v[178:181], v[236:239], v[68:71]
	v_mfma_f32_16x16x32_bf16 v[64:67], v[186:189], v[236:239], v[64:67]
	s_setprio 0
	s_barrier
	s_add_i32 s16, s62, s43
	v_lshl_add_u64 v[166:167], s[28:29], 0, v[138:139]
	s_mov_b32 m0, s16
	ds_read_b128 v[190:193], v169 offset:16384
	ds_read_b128 v[194:197], v169 offset:17408
	ds_read_b128 v[216:219], v169 offset:18432
	ds_read_b128 v[220:223], v169 offset:19456
	ds_read_b128 v[224:227], v169 offset:20480
	ds_read_b128 v[228:231], v169 offset:21504
	ds_read_b128 v[232:235], v169 offset:22528
	ds_read_b128 v[236:239], v169 offset:23552
	global_load_lds_dwordx4 v[166:167], off
	s_add_i32 m0, s16, 0x2000
	s_add_u32 s16, s28, 0xb0000
	v_lshl_add_u64 v[198:199], s[28:29], 0, v[142:143]
	s_addc_u32 s17, s29, 0
	s_add_i32 s62, s63, s43
	global_load_lds_dwordx4 v[198:199], off
	v_lshl_add_u64 v[240:241], s[16:17], 0, v[138:139]
	s_mov_b32 m0, s62
	v_lshl_add_u64 v[242:243], s[40:41], 0, v[140:141]
	global_load_lds_dwordx4 v[240:241], off
	v_lshl_add_u64 v[240:241], s[16:17], 0, v[142:143]
	s_add_i32 m0, s62, 0x2000
	s_nop 0
	global_load_lds_dwordx4 v[240:241], off
	v_lshl_add_u64 v[240:241], s[40:41], 0, v[136:137]
	s_mov_b32 m0, s44
	s_nop 0
	global_load_lds_dwordx4 v[240:241], off
	s_mov_b32 m0, s45
	s_nop 0
	global_load_lds_dwordx4 v[242:243], off
	s_waitcnt vmcnt(8)
	s_waitcnt lgkmcnt(0)
	s_barrier
; #define PG8_STAGE(bufoff, gbase, voff) do { _Pragma("unroll") for (int _i = 0; _i < 2; ++_i) \
;         __builtin_amdgcn_global_load_lds((const unsigned*)((const char*)(gbase) + (voff)[_i]), (PG8_LAS unsigned*)(lds + (bufoff) + ldsw + _i * 8192), 16, 0, 0); } while (0)
; #define PG8_LDA(dst, b, h) do { _Pragma("unroll") for (int m = 0; m < 4; ++m) _Pragma("unroll") for (int k = 0; k < 2; ++k) dst[m][k] = *(const PG8_LAS bf16x8*)(lds + PG8_SA(b, h) + aoff + m * 2048 + k * 1024); } while (0)
; #define PG8_LDB(dst, b, h) do { _Pragma("unroll") for (int n = 0; n < 2; ++n) _Pragma("unroll") for (int k = 0; k < 2; ++k) dst[n][k] = *(const PG8_LAS bf16x8*)(lds + PG8_SB(b, h) + boff + n * 2048 + k * 1024); } while (0)
; #define PG8_MMA(ai, bj, At, Bt) do { __builtin_amdgcn_s_setprio(1); _Pragma("unroll") for (int m = 0; m < 4; ++m) _Pragma("unroll") for (int n = 0; n < 2; ++n) _Pragma("unroll") for (int k = 0; k < 2; ++k) \
;         acc[ai][bj][m][n] = __builtin_amdgcn_mfma_f32_16x16x32_bf16(Bt[n][k], At[m][k], acc[ai][bj][m][n], 0, 0, 0); __builtin_amdgcn_s_setprio(0); } while (0)
; #define PG8_WAIT_V(n) asm volatile("s_waitcnt vmcnt(" #n ")" ::: "memory")
; #define PG8_WAIT_L(n) asm volatile("s_waitcnt lgkmcnt(" #n ")" ::: "memory")
; #define PG8_BAR __builtin_amdgcn_s_barrier()
; #define PG8_SCHED __builtin_amdgcn_sched_barrier(0)
; template <class Epi, class Sched, bool ALIGN_EPI = false, bool SP2 = false>
; __device__ __forceinline__ void gemm_phase(PG8_LAS unsigned char* lds, const Gemm g, const Sched& S, const Epi& E) {
;     ...
;             PG8_WAIT_V(8); PG8_WAIT_L(0); PG8_BAR; PG8_MMA(1, 0, At, B0); PG8_MMA(1, 1, At, B1); PG8_BAR; PG8_SCHED;
;             PG8_LDB(B0, 1, 0); PG8_LDB(B1, 1, 1); PG8_SCHED; PG8_LDA(At, 1, 0); PG8_STAGE(PG8_SA(0, 1), a2 + hstep, voffA);
;             PG8_WAIT_V(8); PG8_WAIT_L(0); PG8_BAR; PG8_MMA(0, 0, At, B0); PG8_MMA(0, 1, At, B1); PG8_BAR; PG8_SCHED;
	s_setprio 1
	v_mfma_f32_16x16x32_bf16 v[60:63], v[128:131], v[190:193], v[60:63]
	v_mfma_f32_16x16x32_bf16 v[56:59], v[162:165], v[190:193], v[56:59]
	v_mfma_f32_16x16x32_bf16 v[44:47], v[128:131], v[216:219], v[44:47]
	v_mfma_f32_16x16x32_bf16 v[40:43], v[162:165], v[216:219], v[40:43]
	v_mfma_f32_16x16x32_bf16 v[28:31], v[128:131], v[224:227], v[28:31]
	v_mfma_f32_16x16x32_bf16 v[24:27], v[162:165], v[224:227], v[24:27]
	v_mfma_f32_16x16x32_bf16 v[12:15], v[128:131], v[232:235], v[12:15]
	v_mfma_f32_16x16x32_bf16 v[8:11], v[162:165], v[232:235], v[8:11]
	v_mfma_f32_16x16x32_bf16 v[60:63], v[132:135], v[194:197], v[60:63]
	v_mfma_f32_16x16x32_bf16 v[56:59], v[170:173], v[194:197], v[56:59]
	v_mfma_f32_16x16x32_bf16 v[44:47], v[132:135], v[220:223], v[44:47]
	v_mfma_f32_16x16x32_bf16 v[40:43], v[170:173], v[220:223], v[40:43]
	v_mfma_f32_16x16x32_bf16 v[28:31], v[132:135], v[228:231], v[28:31]
	v_mfma_f32_16x16x32_bf16 v[24:27], v[170:173], v[228:231], v[24:27]
	v_mfma_f32_16x16x32_bf16 v[12:15], v[132:135], v[236:239], v[12:15]
	v_mfma_f32_16x16x32_bf16 v[8:11], v[170:173], v[236:239], v[8:11]
	v_mfma_f32_16x16x32_bf16 v[52:55], v[174:177], v[190:193], v[52:55]
	v_mfma_f32_16x16x32_bf16 v[48:51], v[182:185], v[190:193], v[48:51]
	v_mfma_f32_16x16x32_bf16 v[36:39], v[174:177], v[216:219], v[36:39]
	v_mfma_f32_16x16x32_bf16 v[32:35], v[182:185], v[216:219], v[32:35]
	v_mfma_f32_16x16x32_bf16 v[20:23], v[174:177], v[224:227], v[20:23]
	v_mfma_f32_16x16x32_bf16 v[16:19], v[182:185], v[224:227], v[16:19]
	v_mfma_f32_16x16x32_bf16 v[4:7], v[174:177], v[232:235], v[4:7]
	v_mfma_f32_16x16x32_bf16 v[0:3], v[182:185], v[232:235], v[0:3]
	v_mfma_f32_16x16x32_bf16 v[52:55], v[178:181], v[194:197], v[52:55]
	v_mfma_f32_16x16x32_bf16 v[48:51], v[186:189], v[194:197], v[48:51]
	v_mfma_f32_16x16x32_bf16 v[36:39], v[178:181], v[220:223], v[36:39]
	v_mfma_f32_16x16x32_bf16 v[32:35], v[186:189], v[220:223], v[32:35]
	v_mfma_f32_16x16x32_bf16 v[20:23], v[178:181], v[228:231], v[20:23]
	v_mfma_f32_16x16x32_bf16 v[16:19], v[186:189], v[228:231], v[16:19]
	v_mfma_f32_16x16x32_bf16 v[4:7], v[178:181], v[236:239], v[4:7]
	v_mfma_f32_16x16x32_bf16 v[0:3], v[186:189], v[236:239], v[0:3]
	s_setprio 0
	s_barrier
	s_add_i32 s62, 0, 0x18000
	v_add_u32_e32 v144, s62, v168
	s_add_i32 s63, 0, 0x1c000
	ds_read_b128 v[128:131], v144
	ds_read_b128 v[132:135], v144 offset:1024
	ds_read_b128 v[162:165], v144 offset:2048
	ds_read_b128 v[170:173], v144 offset:3072
	v_add_u32_e32 v144, s63, v168
	ds_read_b128 v[174:177], v144
	ds_read_b128 v[178:181], v144 offset:1024
	ds_read_b128 v[182:185], v144 offset:2048
	ds_read_b128 v[186:189], v144 offset:3072
	s_add_u32 s16, s40, 0xb0000
	s_addc_u32 s17, s41, 0
	s_mov_b32 m0, s48
	v_lshl_add_u64 v[244:245], s[16:17], 0, v[136:137]
	ds_read_b128 v[190:193], v169 offset:32768
	ds_read_b128 v[194:197], v169 offset:33792
	ds_read_b128 v[216:219], v169 offset:34816
	ds_read_b128 v[220:223], v169 offset:35840
	ds_read_b128 v[224:227], v169 offset:36864
	ds_read_b128 v[228:231], v169 offset:37888
	ds_read_b128 v[232:235], v169 offset:38912
	ds_read_b128 v[236:239], v169 offset:39936
	global_load_lds_dwordx4 v[244:245], off
	v_lshl_add_u64 v[244:245], s[16:17], 0, v[140:141]
	s_mov_b32 m0, s49
	s_nop 0
	global_load_lds_dwordx4 v[244:245], off
	s_waitcnt vmcnt(8)
	s_waitcnt lgkmcnt(0)
	s_barrier
	s_setprio 1
	v_mfma_f32_16x16x32_bf16 v[124:127], v[128:131], v[190:193], v[124:127]
	v_mfma_f32_16x16x32_bf16 v[120:123], v[162:165], v[190:193], v[120:123]
	v_mfma_f32_16x16x32_bf16 v[108:111], v[128:131], v[216:219], v[108:111]
	v_mfma_f32_16x16x32_bf16 v[104:107], v[162:165], v[216:219], v[104:107]
	v_mfma_f32_16x16x32_bf16 v[92:95], v[128:131], v[224:227], v[92:95]
	v_mfma_f32_16x16x32_bf16 v[88:91], v[162:165], v[224:227], v[88:91]
	v_mfma_f32_16x16x32_bf16 v[76:79], v[128:131], v[232:235], v[76:79]
	v_mfma_f32_16x16x32_bf16 v[72:75], v[162:165], v[232:235], v[72:75]
	v_mfma_f32_16x16x32_bf16 v[124:127], v[132:135], v[194:197], v[124:127]
	v_mfma_f32_16x16x32_bf16 v[120:123], v[170:173], v[194:197], v[120:123]
	v_mfma_f32_16x16x32_bf16 v[108:111], v[132:135], v[220:223], v[108:111]
	v_mfma_f32_16x16x32_bf16 v[104:107], v[170:173], v[220:223], v[104:107]
	v_mfma_f32_16x16x32_bf16 v[92:95], v[132:135], v[228:231], v[92:95]
	v_mfma_f32_16x16x32_bf16 v[88:91], v[170:173], v[228:231], v[88:91]
	v_mfma_f32_16x16x32_bf16 v[76:79], v[132:135], v[236:239], v[76:79]
	v_mfma_f32_16x16x32_bf16 v[72:75], v[170:173], v[236:239], v[72:75]
	v_mfma_f32_16x16x32_bf16 v[116:119], v[174:177], v[190:193], v[116:119]
	v_mfma_f32_16x16x32_bf16 v[112:115], v[182:185], v[190:193], v[112:115]
	v_mfma_f32_16x16x32_bf16 v[100:103], v[174:177], v[216:219], v[100:103]
	v_mfma_f32_16x16x32_bf16 v[96:99], v[182:185], v[216:219], v[96:99]
	v_mfma_f32_16x16x32_bf16 v[84:87], v[174:177], v[224:227], v[84:87]
	v_mfma_f32_16x16x32_bf16 v[80:83], v[182:185], v[224:227], v[80:83]
	v_mfma_f32_16x16x32_bf16 v[68:71], v[174:177], v[232:235], v[68:71]
	v_mfma_f32_16x16x32_bf16 v[64:67], v[182:185], v[232:235], v[64:67]
	v_mfma_f32_16x16x32_bf16 v[116:119], v[178:181], v[194:197], v[116:119]
	v_mfma_f32_16x16x32_bf16 v[112:115], v[186:189], v[194:197], v[112:115]
	v_mfma_f32_16x16x32_bf16 v[100:103], v[178:181], v[220:223], v[100:103]
	v_mfma_f32_16x16x32_bf16 v[96:99], v[186:189], v[220:223], v[96:99]
	v_mfma_f32_16x16x32_bf16 v[84:87], v[178:181], v[228:231], v[84:87]
	v_mfma_f32_16x16x32_bf16 v[80:83], v[186:189], v[228:231], v[80:83]
	v_mfma_f32_16x16x32_bf16 v[68:71], v[178:181], v[236:239], v[68:71]
	v_mfma_f32_16x16x32_bf16 v[64:67], v[186:189], v[236:239], v[64:67]
	s_setprio 0
	s_barrier
; #define PG8_STAGE(bufoff, gbase, voff) do { _Pragma("unroll") for (int _i = 0; _i < 2; ++_i) \
;         __builtin_amdgcn_global_load_lds((const unsigned*)((const char*)(gbase) + (voff)[_i]), (PG8_LAS unsigned*)(lds + (bufoff) + ldsw + _i * 8192), 16, 0, 0); } while (0)
; #define PG8_LDA(dst, b, h) do { _Pragma("unroll") for (int m = 0; m < 4; ++m) _Pragma("unroll") for (int k = 0; k < 2; ++k) dst[m][k] = *(const PG8_LAS bf16x8*)(lds + PG8_SA(b, h) + aoff + m * 2048 + k * 1024); } while (0)
; #define PG8_MMA(ai, bj, At, Bt) do { __builtin_amdgcn_s_setprio(1); _Pragma("unroll") for (int m = 0; m < 4; ++m) _Pragma("unroll") for (int n = 0; n < 2; ++n) _Pragma("unroll") for (int k = 0; k < 2; ++k) \
;         acc[ai][bj][m][n] = __builtin_amdgcn_mfma_f32_16x16x32_bf16(Bt[n][k], At[m][k], acc[ai][bj][m][n], 0, 0, 0); __builtin_amdgcn_s_setprio(0); } while (0)
; #define PG8_WAIT_V(n) asm volatile("s_waitcnt vmcnt(" #n ")" ::: "memory")
; #define PG8_WAIT_L(n) asm volatile("s_waitcnt lgkmcnt(" #n ")" ::: "memory")
; #define PG8_BAR __builtin_amdgcn_s_barrier()
; #define PG8_SCHED __builtin_amdgcn_sched_barrier(0)
; template <class Epi, class Sched, bool ALIGN_EPI = false, bool SP2 = false>
; __device__ __forceinline__ void gemm_phase(PG8_LAS unsigned char* lds, const Gemm g, const Sched& S, const Epi& E) {
;     ...
;             PG8_LDA(At, 1, 1); PG8_STAGE(PG8_SB(1, 0), b3, voffB); PG8_STAGE(PG8_SB(1, 1), b3 + hstep, voffB); PG8_STAGE(PG8_SA(1, 0), a3, voffA);
;             PG8_WAIT_V(8); PG8_WAIT_L(0); PG8_BAR; PG8_MMA(1, 0, At, B0); PG8_MMA(1, 1, At, B1); PG8_BAR; PG8_SCHED;
	s_add_i32 s16, s62, s43
	v_lshl_add_u64 v[166:167], v[166:167], 0, s[2:3]
	s_mov_b32 m0, s16
	ds_read_b128 v[190:193], v169 offset:49152
	ds_read_b128 v[194:197], v169 offset:50176
	ds_read_b128 v[216:219], v169 offset:51200
	ds_read_b128 v[220:223], v169 offset:52224
	ds_read_b128 v[224:227], v169 offset:53248
	ds_read_b128 v[228:231], v169 offset:54272
	ds_read_b128 v[232:235], v169 offset:55296
	ds_read_b128 v[236:239], v169 offset:56320
	global_load_lds_dwordx4 v[166:167], off
	s_add_i32 m0, s16, 0x2000
	s_add_u32 s16, s28, 0xb0080
	v_lshl_add_u64 v[166:167], v[198:199], 0, s[2:3]
	s_addc_u32 s17, s29, 0
	s_add_i32 s28, s63, s43
	global_load_lds_dwordx4 v[166:167], off
	v_lshl_add_u64 v[166:167], s[16:17], 0, v[138:139]
	s_mov_b32 m0, s28
	s_nop 0
	global_load_lds_dwordx4 v[166:167], off
	v_lshl_add_u64 v[166:167], s[16:17], 0, v[142:143]
	s_add_i32 m0, s28, 0x2000
	s_nop 0
	global_load_lds_dwordx4 v[166:167], off
	v_lshl_add_u64 v[166:167], v[240:241], 0, s[2:3]
	s_mov_b32 m0, s52
	s_nop 0
	global_load_lds_dwordx4 v[166:167], off
	v_lshl_add_u64 v[166:167], v[242:243], 0, s[2:3]
	s_mov_b32 m0, s53
	s_nop 0
	global_load_lds_dwordx4 v[166:167], off
	s_waitcnt vmcnt(8)
	s_waitcnt lgkmcnt(0)
	s_barrier
	s_setprio 1
	v_mfma_f32_16x16x32_bf16 v[60:63], v[128:131], v[190:193], v[60:63]
	v_mfma_f32_16x16x32_bf16 v[56:59], v[162:165], v[190:193], v[56:59]
	v_mfma_f32_16x16x32_bf16 v[44:47], v[128:131], v[216:219], v[44:47]
	v_mfma_f32_16x16x32_bf16 v[40:43], v[162:165], v[216:219], v[40:43]
	v_mfma_f32_16x16x32_bf16 v[28:31], v[128:131], v[224:227], v[28:31]
	v_mfma_f32_16x16x32_bf16 v[24:27], v[162:165], v[224:227], v[24:27]
	v_mfma_f32_16x16x32_bf16 v[12:15], v[128:131], v[232:235], v[12:15]
	v_mfma_f32_16x16x32_bf16 v[8:11], v[162:165], v[232:235], v[8:11]
	v_mfma_f32_16x16x32_bf16 v[60:63], v[132:135], v[194:197], v[60:63]
	v_mfma_f32_16x16x32_bf16 v[56:59], v[170:173], v[194:197], v[56:59]
	v_mfma_f32_16x16x32_bf16 v[44:47], v[132:135], v[220:223], v[44:47]
	v_mfma_f32_16x16x32_bf16 v[40:43], v[170:173], v[220:223], v[40:43]
	v_mfma_f32_16x16x32_bf16 v[28:31], v[132:135], v[228:231], v[28:31]
	v_mfma_f32_16x16x32_bf16 v[24:27], v[170:173], v[228:231], v[24:27]
	v_mfma_f32_16x16x32_bf16 v[12:15], v[132:135], v[236:239], v[12:15]
	v_mfma_f32_16x16x32_bf16 v[8:11], v[170:173], v[236:239], v[8:11]
	v_mfma_f32_16x16x32_bf16 v[52:55], v[174:177], v[190:193], v[52:55]
	v_mfma_f32_16x16x32_bf16 v[48:51], v[182:185], v[190:193], v[48:51]
	v_mfma_f32_16x16x32_bf16 v[36:39], v[174:177], v[216:219], v[36:39]
	v_mfma_f32_16x16x32_bf16 v[32:35], v[182:185], v[216:219], v[32:35]
	v_mfma_f32_16x16x32_bf16 v[20:23], v[174:177], v[224:227], v[20:23]
	v_mfma_f32_16x16x32_bf16 v[16:19], v[182:185], v[224:227], v[16:19]
	v_mfma_f32_16x16x32_bf16 v[4:7], v[174:177], v[232:235], v[4:7]
	v_mfma_f32_16x16x32_bf16 v[0:3], v[182:185], v[232:235], v[0:3]
	v_mfma_f32_16x16x32_bf16 v[52:55], v[178:181], v[194:197], v[52:55]
	v_mfma_f32_16x16x32_bf16 v[48:51], v[186:189], v[194:197], v[48:51]
	v_mfma_f32_16x16x32_bf16 v[36:39], v[178:181], v[220:223], v[36:39]
	v_mfma_f32_16x16x32_bf16 v[32:35], v[186:189], v[220:223], v[32:35]
	v_mfma_f32_16x16x32_bf16 v[20:23], v[178:181], v[228:231], v[20:23]
	v_mfma_f32_16x16x32_bf16 v[16:19], v[186:189], v[228:231], v[16:19]
	v_mfma_f32_16x16x32_bf16 v[4:7], v[178:181], v[236:239], v[4:7]
	v_mfma_f32_16x16x32_bf16 v[0:3], v[186:189], v[236:239], v[0:3]
	s_setprio 0
	s_barrier
	s_add_i32 s61, s61, 2
	s_add_u32 s59, s59, 0x100
	s_addc_u32 s60, s60, 0
	s_cmp_gt_u32 s61, 41
	s_mov_b64 s[16:17], s[18:19]
	s_cbranch_scc0 .LBB0_857
	s_and_b64 vcc, exec, s[12:13]
	s_cbranch_vccz .LBB0_860
	s_barrier
